# loop-edge edit: GEMM K-loop pointer/counter SALU updates and loop test moved before the closing s_barrier (only the branch follows it), 6 loops + peeled copies
# baseline (speedup 1.0000x reference)
; #define PG8_STAGE(bufoff, gbase, voff) do { _Pragma("unroll") for (int _i = 0; _i < 2; ++_i) \
;         __builtin_amdgcn_global_load_lds((const unsigned*)((const char*)(gbase) + (voff)[_i]), (LAS unsigned*)(lds + (bufoff) + ldsw + _i * 8192), 16, 0, 0); } while (0)
; #define PG8_LDA(dst, b, h) do { _Pragma("unroll") for (int m = 0; m < 4; ++m) _Pragma("unroll") for (int k = 0; k < 2; ++k) dst[m][k] = *(const LAS bf16x8*)(lds + PG8_SA(b, h) + aoff + m * 2048 + k * 1024); } while (0)
; #define PG8_LDB(dst, b, h) do { _Pragma("unroll") for (int n = 0; n < 2; ++n) _Pragma("unroll") for (int k = 0; k < 2; ++k) dst[n][k] = *(const LAS bf16x8*)(lds + PG8_SB(b, h) + boff + n * 2048 + k * 1024); } while (0)
; #define PG8_WAIT_V(n) asm volatile("s_waitcnt vmcnt(" #n ")" ::: "memory")
; #define PG8_WAIT_L(n) asm volatile("s_waitcnt lgkmcnt(" #n ")" ::: "memory")
; template <class Epi>
; __device__ __forceinline__ void gemm_phase(LAS unsigned char* lds, const Gemm g, const Sched& S, const Epi& E, const int tid) {
;     ...
;         for (int t = 0; t < nt; t += 2) {
;             const bool last = (t == nt - 2);
;             const char* a1 = cA + (size_t)(t + 1) * kstep;
;             const char* a2 = last ? nA : cA + (size_t)(t + 2) * kstep; const char* b2 = last ? nB : cB + (size_t)(t + 2) * kstep;
;             const char* a3 = a2 + kstep; const char* b3 = b2 + kstep;
;             PG8_LDB(B0, 0, 0); PG8_LDB(B1, 0, 1); PG8_SCHED; PG8_LDA(At, 0, 0); PG8_STAGE(PG8_SA(1, 1), a1 + hA, voffA);
;             PG8_WAIT_V(8); PG8_WAIT_L(0); PG8_BAR; PG8_MMA(0, 0, At, B0); PG8_MMA(0, 1, At, B1); PG8_BAR; PG8_SCHED;
;             PG8_LDA(At, 0, 1); PG8_STAGE(PG8_SB(0, 0), b2, voffB); PG8_STAGE(PG8_SB(0, 1), b2 + hB, voffB); PG8_STAGE(PG8_SA(0, 0), a2, voffA);
;             PG8_WAIT_V(8); PG8_WAIT_L(0); PG8_BAR; PG8_MMA(1, 0, At, B0); PG8_MMA(1, 1, At, B1); PG8_BAR; PG8_SCHED;
;             PG8_LDB(B0, 1, 0); PG8_LDB(B1, 1, 1); PG8_SCHED; PG8_LDA(At, 1, 0); PG8_STAGE(PG8_SA(0, 1), a2 + hA, voffA);
;             PG8_WAIT_V(8); PG8_WAIT_L(0); PG8_BAR; PG8_MMA(0, 0, At, B0); PG8_MMA(0, 1, At, B1); PG8_BAR; PG8_SCHED;
;             PG8_LDA(At, 1, 1); PG8_STAGE(PG8_SB(1, 0), b3, voffB); PG8_STAGE(PG8_SB(1, 1), b3 + hB, voffB); PG8_STAGE(PG8_SA(1, 0), a3, voffA);
;             PG8_WAIT_V(8); PG8_WAIT_L(0); PG8_BAR; PG8_MMA(1, 0, At, B0); PG8_MMA(1, 1, At, B1); PG8_BAR; PG8_SCHED;
.LBB0_332:
	s_add_u32 s10, s10, 0x40080
	s_addc_u32 s11, s11, 0
	s_add_u32 s9, s74, 0x100
	s_addc_u32 s19, s75, 0
	s_mov_b32 s21, -2
	s_add_u32 s35, s10, 0xfffc0080
	s_addc_u32 s37, s11, -1
	s_add_i32 vcc_lo, 0, 0x10000
	s_cmp_eq_u32 s21, 12
	s_cselect_b32 s77, s23, s37
	s_cselect_b32 s76, s22, s35
	s_cselect_b32 s75, s73, s19
	s_cselect_b32 s74, s72, s9
	s_add_i32 s35, 0, 0x14000
	v_add_u32_e32 v156, vcc_lo, v145
	v_add_u32_e32 v172, s35, v145
	ds_read_b128 v[140:143], v156
	ds_read_b128 v[148:151], v156 offset:1024
	ds_read_b128 v[152:155], v156 offset:2048
	ds_read_b128 v[156:159], v156 offset:3072
	ds_read_b128 v[160:163], v172
	ds_read_b128 v[164:167], v172 offset:1024
	ds_read_b128 v[168:171], v172 offset:2048
	ds_read_b128 v[172:175], v172 offset:3072
	v_lshl_add_u64 v[190:191], s[10:11], 0, v[136:137]
	s_add_i32 m0, s13, 0xc000
	ds_read_b128 v[178:181], v147
	ds_read_b128 v[182:185], v147 offset:1024
	ds_read_b128 v[186:189], v147 offset:2048
	ds_read_b128 v[194:197], v147 offset:3072
	ds_read_b128 v[198:201], v147 offset:4096
	ds_read_b128 v[202:205], v147 offset:5120
	ds_read_b128 v[206:209], v147 offset:6144
	ds_read_b128 v[210:213], v147 offset:7168
	global_load_lds_dwordx4 v[190:191], off
	v_lshl_add_u64 v[190:191], s[10:11], 0, v[138:139]
	s_add_i32 m0, s13, 0xe000
	s_nop 0
	global_load_lds_dwordx4 v[190:191], off
	s_waitcnt vmcnt(8)
	s_waitcnt lgkmcnt(0)
	s_barrier
	s_setprio 1
	s_waitcnt lgkmcnt(0)
	v_mfma_f32_16x16x32_bf16 v[124:127], v[140:143], v[178:181], 0
	v_mfma_f32_16x16x32_bf16 v[120:123], v[152:155], v[178:181], 0
	v_mfma_f32_16x16x32_bf16 v[116:119], v[140:143], v[186:189], 0
	v_mfma_f32_16x16x32_bf16 v[108:111], v[152:155], v[186:189], 0
	v_mfma_f32_16x16x32_bf16 v[92:95], v[140:143], v[198:201], 0
	v_mfma_f32_16x16x32_bf16 v[88:91], v[152:155], v[198:201], 0
	v_mfma_f32_16x16x32_bf16 v[84:87], v[140:143], v[206:209], 0
	v_mfma_f32_16x16x32_bf16 v[76:79], v[152:155], v[206:209], 0
	v_mfma_f32_16x16x32_bf16 v[124:127], v[148:151], v[182:185], v[124:127]
	v_mfma_f32_16x16x32_bf16 v[120:123], v[156:159], v[182:185], v[120:123]
	v_mfma_f32_16x16x32_bf16 v[116:119], v[148:151], v[194:197], v[116:119]
	v_mfma_f32_16x16x32_bf16 v[108:111], v[156:159], v[194:197], v[108:111]
	v_mfma_f32_16x16x32_bf16 v[92:95], v[148:151], v[202:205], v[92:95]
	v_mfma_f32_16x16x32_bf16 v[88:91], v[156:159], v[202:205], v[88:91]
	v_mfma_f32_16x16x32_bf16 v[84:87], v[148:151], v[210:213], v[84:87]
	v_mfma_f32_16x16x32_bf16 v[76:79], v[156:159], v[210:213], v[76:79]
	s_setprio 0
	s_setprio 1
	v_mfma_f32_16x16x32_bf16 v[112:115], v[160:163], v[178:181], 0
	v_mfma_f32_16x16x32_bf16 v[104:107], v[168:171], v[178:181], 0
	v_mfma_f32_16x16x32_bf16 v[100:103], v[160:163], v[186:189], 0
	v_mfma_f32_16x16x32_bf16 v[96:99], v[168:171], v[186:189], 0
	v_mfma_f32_16x16x32_bf16 v[80:83], v[160:163], v[198:201], 0
	v_mfma_f32_16x16x32_bf16 v[72:75], v[168:171], v[198:201], 0
	v_mfma_f32_16x16x32_bf16 v[68:71], v[160:163], v[206:209], 0
	v_mfma_f32_16x16x32_bf16 v[64:67], v[168:171], v[206:209], 0
	v_mfma_f32_16x16x32_bf16 v[112:115], v[164:167], v[182:185], v[112:115]
	v_mfma_f32_16x16x32_bf16 v[104:107], v[172:175], v[182:185], v[104:107]
	v_mfma_f32_16x16x32_bf16 v[100:103], v[164:167], v[194:197], v[100:103]
	v_mfma_f32_16x16x32_bf16 v[96:99], v[172:175], v[194:197], v[96:99]
	v_mfma_f32_16x16x32_bf16 v[80:83], v[164:167], v[202:205], v[80:83]
	v_mfma_f32_16x16x32_bf16 v[72:75], v[172:175], v[202:205], v[72:75]
	v_mfma_f32_16x16x32_bf16 v[68:71], v[164:167], v[210:213], v[68:71]
	v_mfma_f32_16x16x32_bf16 v[64:67], v[172:175], v[210:213], v[64:67]
	s_setprio 0
	s_barrier
	s_add_i32 s37, vcc_lo, s39
	v_lshl_add_u64 v[190:191], s[74:75], 0, v[192:193]
	s_mov_b32 m0, s37
	ds_read_b128 v[178:181], v147 offset:16384
	ds_read_b128 v[182:185], v147 offset:17408
	ds_read_b128 v[186:189], v147 offset:18432
	ds_read_b128 v[194:197], v147 offset:19456
	ds_read_b128 v[198:201], v147 offset:20480
	ds_read_b128 v[202:205], v147 offset:21504
	ds_read_b128 v[206:209], v147 offset:22528
	ds_read_b128 v[210:213], v147 offset:23552
	global_load_lds_dwordx4 v[190:191], off
	s_add_i32 m0, s37, 0x2000
	s_add_u32 vcc_lo, s74, 0x40000
	v_lshl_add_u64 v[214:215], s[74:75], 0, v[132:133]
	s_addc_u32 vcc_hi, s75, 0
	s_add_i32 s35, s35, s39
	global_load_lds_dwordx4 v[214:215], off
	v_lshl_add_u64 v[216:217], vcc, 0, v[192:193]
	s_mov_b32 m0, s35
	v_lshl_add_u64 v[218:219], s[76:77], 0, v[130:131]
	global_load_lds_dwordx4 v[216:217], off
	v_lshl_add_u64 v[216:217], vcc, 0, v[132:133]
	s_add_i32 m0, s35, 0x2000
	s_nop 0
	global_load_lds_dwordx4 v[216:217], off
	v_lshl_add_u64 v[216:217], s[76:77], 0, v[128:129]
	s_mov_b32 m0, s13
	s_nop 0
	global_load_lds_dwordx4 v[216:217], off
	s_mov_b32 m0, s40
	s_nop 0
	global_load_lds_dwordx4 v[218:219], off
	s_waitcnt vmcnt(8)
	s_waitcnt lgkmcnt(0)
	s_barrier
; #define PG8_STAGE(bufoff, gbase, voff) do { _Pragma("unroll") for (int _i = 0; _i < 2; ++_i) \
;         __builtin_amdgcn_global_load_lds((const unsigned*)((const char*)(gbase) + (voff)[_i]), (LAS unsigned*)(lds + (bufoff) + ldsw + _i * 8192), 16, 0, 0); } while (0)
; #define PG8_LDA(dst, b, h) do { _Pragma("unroll") for (int m = 0; m < 4; ++m) _Pragma("unroll") for (int k = 0; k < 2; ++k) dst[m][k] = *(const LAS bf16x8*)(lds + PG8_SA(b, h) + aoff + m * 2048 + k * 1024); } while (0)
; #define PG8_LDB(dst, b, h) do { _Pragma("unroll") for (int n = 0; n < 2; ++n) _Pragma("unroll") for (int k = 0; k < 2; ++k) dst[n][k] = *(const LAS bf16x8*)(lds + PG8_SB(b, h) + boff + n * 2048 + k * 1024); } while (0)
; #define PG8_MMA(ai, bj, At, Bt) do { __builtin_amdgcn_s_setprio(1); _Pragma("unroll") for (int m = 0; m < 4; ++m) _Pragma("unroll") for (int n = 0; n < 2; ++n) _Pragma("unroll") for (int k = 0; k < 2; ++k) \
;         acc[ai][bj][m][n] = __builtin_amdgcn_mfma_f32_16x16x32_bf16(Bt[n][k], At[m][k], acc[ai][bj][m][n], 0, 0, 0); __builtin_amdgcn_s_setprio(0); } while (0)
; #define PG8_WAIT_V(n) asm volatile("s_waitcnt vmcnt(" #n ")" ::: "memory")
; #define PG8_WAIT_L(n) asm volatile("s_waitcnt lgkmcnt(" #n ")" ::: "memory")
; #define PG8_BAR __builtin_amdgcn_s_barrier()
; #define PG8_SCHED __builtin_amdgcn_sched_barrier(0)
; template <class Epi>
; __device__ __forceinline__ void gemm_phase(LAS unsigned char* lds, const Gemm g, const Sched& S, const Epi& E, const int tid) {
;     ...
;             PG8_WAIT_V(8); PG8_WAIT_L(0); PG8_BAR; PG8_MMA(0, 0, At, B0); PG8_MMA(0, 1, At, B1); PG8_BAR; PG8_SCHED;
;             PG8_LDA(At, 0, 1); PG8_STAGE(PG8_SB(0, 0), b2, voffB); PG8_STAGE(PG8_SB(0, 1), b2 + hB, voffB); PG8_STAGE(PG8_SA(0, 0), a2, voffA);
;             PG8_WAIT_V(8); PG8_WAIT_L(0); PG8_BAR; PG8_MMA(1, 0, At, B0); PG8_MMA(1, 1, At, B1); PG8_BAR; PG8_SCHED;
;             PG8_LDB(B0, 1, 0); PG8_LDB(B1, 1, 1); PG8_SCHED; PG8_LDA(At, 1, 0); PG8_STAGE(PG8_SA(0, 1), a2 + hA, voffA);
;             PG8_WAIT_V(8); PG8_WAIT_L(0); PG8_BAR; PG8_MMA(0, 0, At, B0); PG8_MMA(0, 1, At, B1); PG8_BAR; PG8_SCHED;
;             PG8_LDA(At, 1, 1); PG8_STAGE(PG8_SB(1, 0), b3, voffB); PG8_STAGE(PG8_SB(1, 1), b3 + hB, voffB); PG8_STAGE(PG8_SA(1, 0), a3, voffA);
	s_setprio 1
	s_waitcnt lgkmcnt(0)
	v_mfma_f32_16x16x32_bf16 v[60:63], v[140:143], v[178:181], 0
	v_mfma_f32_16x16x32_bf16 v[56:59], v[152:155], v[178:181], 0
	v_mfma_f32_16x16x32_bf16 v[52:55], v[140:143], v[186:189], 0
	v_mfma_f32_16x16x32_bf16 v[44:47], v[152:155], v[186:189], 0
	v_mfma_f32_16x16x32_bf16 v[28:31], v[140:143], v[198:201], 0
	v_mfma_f32_16x16x32_bf16 v[24:27], v[152:155], v[198:201], 0
	v_mfma_f32_16x16x32_bf16 v[20:23], v[140:143], v[206:209], 0
	v_mfma_f32_16x16x32_bf16 v[12:15], v[152:155], v[206:209], 0
	v_mfma_f32_16x16x32_bf16 v[60:63], v[148:151], v[182:185], v[60:63]
	v_mfma_f32_16x16x32_bf16 v[56:59], v[156:159], v[182:185], v[56:59]
	v_mfma_f32_16x16x32_bf16 v[52:55], v[148:151], v[194:197], v[52:55]
	v_mfma_f32_16x16x32_bf16 v[44:47], v[156:159], v[194:197], v[44:47]
	v_mfma_f32_16x16x32_bf16 v[28:31], v[148:151], v[202:205], v[28:31]
	v_mfma_f32_16x16x32_bf16 v[24:27], v[156:159], v[202:205], v[24:27]
	v_mfma_f32_16x16x32_bf16 v[20:23], v[148:151], v[210:213], v[20:23]
	v_mfma_f32_16x16x32_bf16 v[12:15], v[156:159], v[210:213], v[12:15]
	s_setprio 0
	s_setprio 1
	v_mfma_f32_16x16x32_bf16 v[48:51], v[160:163], v[178:181], 0
	v_mfma_f32_16x16x32_bf16 v[40:43], v[168:171], v[178:181], 0
	v_mfma_f32_16x16x32_bf16 v[36:39], v[160:163], v[186:189], 0
	v_mfma_f32_16x16x32_bf16 v[32:35], v[168:171], v[186:189], 0
	v_mfma_f32_16x16x32_bf16 v[16:19], v[160:163], v[198:201], 0
	v_mfma_f32_16x16x32_bf16 v[8:11], v[168:171], v[198:201], 0
	v_mfma_f32_16x16x32_bf16 v[4:7], v[160:163], v[206:209], 0
	v_mfma_f32_16x16x32_bf16 v[0:3], v[168:171], v[206:209], 0
	v_mfma_f32_16x16x32_bf16 v[48:51], v[164:167], v[182:185], v[48:51]
	v_mfma_f32_16x16x32_bf16 v[40:43], v[172:175], v[182:185], v[40:43]
	v_mfma_f32_16x16x32_bf16 v[36:39], v[164:167], v[194:197], v[36:39]
	v_mfma_f32_16x16x32_bf16 v[32:35], v[172:175], v[194:197], v[32:35]
	v_mfma_f32_16x16x32_bf16 v[16:19], v[164:167], v[202:205], v[16:19]
	v_mfma_f32_16x16x32_bf16 v[8:11], v[172:175], v[202:205], v[8:11]
	v_mfma_f32_16x16x32_bf16 v[4:7], v[164:167], v[210:213], v[4:7]
	v_mfma_f32_16x16x32_bf16 v[0:3], v[172:175], v[210:213], v[0:3]
	s_setprio 0
	s_barrier
	s_add_i32 s35, 0, 0x18000
	s_add_i32 s37, 0, 0x1c000
	v_add_u32_e32 v156, s35, v145
	v_add_u32_e32 v172, s37, v145
	ds_read_b128 v[140:143], v156
	ds_read_b128 v[148:151], v156 offset:1024
	ds_read_b128 v[152:155], v156 offset:2048
	ds_read_b128 v[156:159], v156 offset:3072
	ds_read_b128 v[160:163], v172
	ds_read_b128 v[164:167], v172 offset:1024
	ds_read_b128 v[168:171], v172 offset:2048
	ds_read_b128 v[172:175], v172 offset:3072
	s_add_u32 s76, s76, 0x40000
	s_addc_u32 s77, s77, 0
	s_mov_b32 m0, s45
	v_lshl_add_u64 v[224:225], s[76:77], 0, v[128:129]
	ds_read_b128 v[178:181], v147 offset:32768
	ds_read_b128 v[182:185], v147 offset:33792
	ds_read_b128 v[186:189], v147 offset:34816
	ds_read_b128 v[194:197], v147 offset:35840
	ds_read_b128 v[198:201], v147 offset:36864
	ds_read_b128 v[202:205], v147 offset:37888
	ds_read_b128 v[206:209], v147 offset:38912
	ds_read_b128 v[210:213], v147 offset:39936
	global_load_lds_dwordx4 v[224:225], off
	v_lshl_add_u64 v[224:225], s[76:77], 0, v[130:131]
	s_mov_b32 m0, s47
	s_nop 0
	global_load_lds_dwordx4 v[224:225], off
	s_waitcnt vmcnt(8)
	s_waitcnt lgkmcnt(0)
	s_barrier
	s_setprio 1
	s_waitcnt lgkmcnt(0)
	v_mfma_f32_16x16x32_bf16 v[124:127], v[140:143], v[178:181], v[124:127]
	v_mfma_f32_16x16x32_bf16 v[120:123], v[152:155], v[178:181], v[120:123]
	v_mfma_f32_16x16x32_bf16 v[116:119], v[140:143], v[186:189], v[116:119]
	v_mfma_f32_16x16x32_bf16 v[108:111], v[152:155], v[186:189], v[108:111]
	v_mfma_f32_16x16x32_bf16 v[92:95], v[140:143], v[198:201], v[92:95]
	v_mfma_f32_16x16x32_bf16 v[88:91], v[152:155], v[198:201], v[88:91]
	v_mfma_f32_16x16x32_bf16 v[84:87], v[140:143], v[206:209], v[84:87]
	v_mfma_f32_16x16x32_bf16 v[76:79], v[152:155], v[206:209], v[76:79]
	v_mfma_f32_16x16x32_bf16 v[124:127], v[148:151], v[182:185], v[124:127]
	v_mfma_f32_16x16x32_bf16 v[120:123], v[156:159], v[182:185], v[120:123]
	v_mfma_f32_16x16x32_bf16 v[116:119], v[148:151], v[194:197], v[116:119]
	v_mfma_f32_16x16x32_bf16 v[108:111], v[156:159], v[194:197], v[108:111]
	v_mfma_f32_16x16x32_bf16 v[92:95], v[148:151], v[202:205], v[92:95]
	v_mfma_f32_16x16x32_bf16 v[88:91], v[156:159], v[202:205], v[88:91]
	v_mfma_f32_16x16x32_bf16 v[84:87], v[148:151], v[210:213], v[84:87]
	v_mfma_f32_16x16x32_bf16 v[76:79], v[156:159], v[210:213], v[76:79]
	s_setprio 0
	s_setprio 1
	v_mfma_f32_16x16x32_bf16 v[112:115], v[160:163], v[178:181], v[112:115]
	v_mfma_f32_16x16x32_bf16 v[104:107], v[168:171], v[178:181], v[104:107]
	v_mfma_f32_16x16x32_bf16 v[100:103], v[160:163], v[186:189], v[100:103]
	v_mfma_f32_16x16x32_bf16 v[96:99], v[168:171], v[186:189], v[96:99]
	v_mfma_f32_16x16x32_bf16 v[80:83], v[160:163], v[198:201], v[80:83]
	v_mfma_f32_16x16x32_bf16 v[72:75], v[168:171], v[198:201], v[72:75]
	v_mfma_f32_16x16x32_bf16 v[68:71], v[160:163], v[206:209], v[68:71]
	v_mfma_f32_16x16x32_bf16 v[64:67], v[168:171], v[206:209], v[64:67]
	v_mfma_f32_16x16x32_bf16 v[112:115], v[164:167], v[182:185], v[112:115]
	v_mfma_f32_16x16x32_bf16 v[104:107], v[172:175], v[182:185], v[104:107]
	v_mfma_f32_16x16x32_bf16 v[100:103], v[164:167], v[194:197], v[100:103]
	v_mfma_f32_16x16x32_bf16 v[96:99], v[172:175], v[194:197], v[96:99]
	v_mfma_f32_16x16x32_bf16 v[80:83], v[164:167], v[202:205], v[80:83]
	v_mfma_f32_16x16x32_bf16 v[72:75], v[172:175], v[202:205], v[72:75]
	v_mfma_f32_16x16x32_bf16 v[68:71], v[164:167], v[210:213], v[68:71]
	v_mfma_f32_16x16x32_bf16 v[64:67], v[172:175], v[210:213], v[64:67]
	s_setprio 0
	s_barrier
; #define PG8_STAGE(bufoff, gbase, voff) do { _Pragma("unroll") for (int _i = 0; _i < 2; ++_i) \
;         __builtin_amdgcn_global_load_lds((const unsigned*)((const char*)(gbase) + (voff)[_i]), (LAS unsigned*)(lds + (bufoff) + ldsw + _i * 8192), 16, 0, 0); } while (0)
; #define PG8_LDA(dst, b, h) do { _Pragma("unroll") for (int m = 0; m < 4; ++m) _Pragma("unroll") for (int k = 0; k < 2; ++k) dst[m][k] = *(const LAS bf16x8*)(lds + PG8_SA(b, h) + aoff + m * 2048 + k * 1024); } while (0)
; #define PG8_LDB(dst, b, h) do { _Pragma("unroll") for (int n = 0; n < 2; ++n) _Pragma("unroll") for (int k = 0; k < 2; ++k) dst[n][k] = *(const LAS bf16x8*)(lds + PG8_SB(b, h) + boff + n * 2048 + k * 1024); } while (0)
; #define PG8_MMA(ai, bj, At, Bt) do { __builtin_amdgcn_s_setprio(1); _Pragma("unroll") for (int m = 0; m < 4; ++m) _Pragma("unroll") for (int n = 0; n < 2; ++n) _Pragma("unroll") for (int k = 0; k < 2; ++k) \
;         acc[ai][bj][m][n] = __builtin_amdgcn_mfma_f32_16x16x32_bf16(Bt[n][k], At[m][k], acc[ai][bj][m][n], 0, 0, 0); __builtin_amdgcn_s_setprio(0); } while (0)
; #define PG8_WAIT_V(n) asm volatile("s_waitcnt vmcnt(" #n ")" ::: "memory")
; #define PG8_WAIT_L(n) asm volatile("s_waitcnt lgkmcnt(" #n ")" ::: "memory")
; #define PG8_BAR __builtin_amdgcn_s_barrier()
; #define PG8_SCHED __builtin_amdgcn_sched_barrier(0)
; template <class Epi>
; __device__ __forceinline__ void gemm_phase(LAS unsigned char* lds, const Gemm g, const Sched& S, const Epi& E, const int tid) {
;     ...
;             PG8_LDB(B0, 0, 0); PG8_LDB(B1, 0, 1); PG8_SCHED; PG8_LDA(At, 0, 0); PG8_STAGE(PG8_SA(1, 1), a1 + hA, voffA);
;             PG8_WAIT_V(8); PG8_WAIT_L(0); PG8_BAR; PG8_MMA(0, 0, At, B0); PG8_MMA(0, 1, At, B1); PG8_BAR; PG8_SCHED;
;     ...
;             PG8_LDA(At, 1, 1); PG8_STAGE(PG8_SB(1, 0), b3, voffB); PG8_STAGE(PG8_SB(1, 1), b3 + hB, voffB); PG8_STAGE(PG8_SA(1, 0), a3, voffA);
;             PG8_WAIT_V(8); PG8_WAIT_L(0); PG8_BAR; PG8_MMA(1, 0, At, B0); PG8_MMA(1, 1, At, B1); PG8_BAR; PG8_SCHED;
	s_add_i32 s35, s35, s39
	v_lshl_add_u64 v[190:191], v[190:191], 0, s[94:95]
	s_mov_b32 m0, s35
	ds_read_b128 v[178:181], v147 offset:49152
	ds_read_b128 v[182:185], v147 offset:50176
	ds_read_b128 v[186:189], v147 offset:51200
	ds_read_b128 v[194:197], v147 offset:52224
	ds_read_b128 v[198:201], v147 offset:53248
	ds_read_b128 v[202:205], v147 offset:54272
	ds_read_b128 v[206:209], v147 offset:55296
	ds_read_b128 v[210:213], v147 offset:56320
	global_load_lds_dwordx4 v[190:191], off
	s_add_i32 m0, s35, 0x2000
	s_add_u32 s74, s74, 0x40080
	v_lshl_add_u64 v[190:191], v[214:215], 0, s[94:95]
	s_addc_u32 s75, s75, 0
	s_add_i32 s35, s37, s39
	global_load_lds_dwordx4 v[190:191], off
	v_lshl_add_u64 v[190:191], s[74:75], 0, v[192:193]
	s_mov_b32 m0, s35
	s_nop 0
	global_load_lds_dwordx4 v[190:191], off
	v_lshl_add_u64 v[190:191], s[74:75], 0, v[132:133]
	s_add_i32 m0, s35, 0x2000
	s_nop 0
	global_load_lds_dwordx4 v[190:191], off
	v_lshl_add_u64 v[190:191], v[216:217], 0, s[94:95]
	s_mov_b32 m0, s78
	s_nop 0
	global_load_lds_dwordx4 v[190:191], off
	v_lshl_add_u64 v[190:191], v[218:219], 0, s[94:95]
	s_mov_b32 m0, s80
	s_nop 0
	global_load_lds_dwordx4 v[190:191], off
	s_waitcnt vmcnt(8)
	s_waitcnt lgkmcnt(0)
	s_barrier
	s_setprio 1
	s_waitcnt lgkmcnt(0)
	v_mfma_f32_16x16x32_bf16 v[60:63], v[140:143], v[178:181], v[60:63]
	v_mfma_f32_16x16x32_bf16 v[56:59], v[152:155], v[178:181], v[56:59]
	v_mfma_f32_16x16x32_bf16 v[52:55], v[140:143], v[186:189], v[52:55]
	v_mfma_f32_16x16x32_bf16 v[44:47], v[152:155], v[186:189], v[44:47]
	v_mfma_f32_16x16x32_bf16 v[28:31], v[140:143], v[198:201], v[28:31]
	v_mfma_f32_16x16x32_bf16 v[24:27], v[152:155], v[198:201], v[24:27]
	v_mfma_f32_16x16x32_bf16 v[20:23], v[140:143], v[206:209], v[20:23]
	v_mfma_f32_16x16x32_bf16 v[12:15], v[152:155], v[206:209], v[12:15]
	v_mfma_f32_16x16x32_bf16 v[60:63], v[148:151], v[182:185], v[60:63]
	v_mfma_f32_16x16x32_bf16 v[56:59], v[156:159], v[182:185], v[56:59]
	v_mfma_f32_16x16x32_bf16 v[52:55], v[148:151], v[194:197], v[52:55]
	v_mfma_f32_16x16x32_bf16 v[44:47], v[156:159], v[194:197], v[44:47]
	v_mfma_f32_16x16x32_bf16 v[28:31], v[148:151], v[202:205], v[28:31]
	v_mfma_f32_16x16x32_bf16 v[24:27], v[156:159], v[202:205], v[24:27]
	v_mfma_f32_16x16x32_bf16 v[20:23], v[148:151], v[210:213], v[20:23]
	v_mfma_f32_16x16x32_bf16 v[12:15], v[156:159], v[210:213], v[12:15]
	s_setprio 0
	s_setprio 1
	v_mfma_f32_16x16x32_bf16 v[48:51], v[160:163], v[178:181], v[48:51]
	v_mfma_f32_16x16x32_bf16 v[40:43], v[168:171], v[178:181], v[40:43]
	v_mfma_f32_16x16x32_bf16 v[36:39], v[160:163], v[186:189], v[36:39]
	v_mfma_f32_16x16x32_bf16 v[32:35], v[168:171], v[186:189], v[32:35]
	v_mfma_f32_16x16x32_bf16 v[16:19], v[160:163], v[198:201], v[16:19]
	v_mfma_f32_16x16x32_bf16 v[8:11], v[168:171], v[198:201], v[8:11]
	v_mfma_f32_16x16x32_bf16 v[4:7], v[160:163], v[206:209], v[4:7]
	v_mfma_f32_16x16x32_bf16 v[0:3], v[168:171], v[206:209], v[0:3]
	v_mfma_f32_16x16x32_bf16 v[48:51], v[164:167], v[182:185], v[48:51]
	v_mfma_f32_16x16x32_bf16 v[40:43], v[172:175], v[182:185], v[40:43]
	v_mfma_f32_16x16x32_bf16 v[36:39], v[164:167], v[194:197], v[36:39]
	v_mfma_f32_16x16x32_bf16 v[32:35], v[172:175], v[194:197], v[32:35]
	v_mfma_f32_16x16x32_bf16 v[16:19], v[164:167], v[202:205], v[16:19]
	v_mfma_f32_16x16x32_bf16 v[8:11], v[172:175], v[202:205], v[8:11]
	v_mfma_f32_16x16x32_bf16 v[4:7], v[164:167], v[210:213], v[4:7]
	v_mfma_f32_16x16x32_bf16 v[0:3], v[172:175], v[210:213], v[0:3]
	s_add_i32 s21, s21, 2
	s_add_u32 s10, s10, 0x100
	s_addc_u32 s11, s11, 0
	s_add_u32 s9, s9, 0x100
	s_addc_u32 s19, s19, 0
	s_cmp_gt_u32 s21, 13
	s_setprio 0
	s_barrier
	s_cbranch_scc1 .Lgk_exit_0
.LBB0_333:
	s_add_u32 s35, s10, 0xfffc0080
	s_addc_u32 s37, s11, -1
	s_add_i32 vcc_lo, 0, 0x10000
	s_cmp_eq_u32 s21, 12
	s_cselect_b32 s77, s23, s37
	s_cselect_b32 s76, s22, s35
	s_cselect_b32 s75, s73, s19
	s_cselect_b32 s74, s72, s9
	s_add_i32 s35, 0, 0x14000
	v_add_u32_e32 v156, vcc_lo, v145
	v_add_u32_e32 v172, s35, v145
	ds_read_b128 v[140:143], v156
	ds_read_b128 v[148:151], v156 offset:1024
	ds_read_b128 v[152:155], v156 offset:2048
	ds_read_b128 v[156:159], v156 offset:3072
	ds_read_b128 v[160:163], v172
	ds_read_b128 v[164:167], v172 offset:1024
	ds_read_b128 v[168:171], v172 offset:2048
	ds_read_b128 v[172:175], v172 offset:3072
	v_lshl_add_u64 v[190:191], s[10:11], 0, v[136:137]
	s_add_i32 m0, s13, 0xc000
	ds_read_b128 v[178:181], v147
	ds_read_b128 v[182:185], v147 offset:1024
	ds_read_b128 v[186:189], v147 offset:2048
	ds_read_b128 v[194:197], v147 offset:3072
	ds_read_b128 v[198:201], v147 offset:4096
	ds_read_b128 v[202:205], v147 offset:5120
	ds_read_b128 v[206:209], v147 offset:6144
	ds_read_b128 v[210:213], v147 offset:7168
	global_load_lds_dwordx4 v[190:191], off
	v_lshl_add_u64 v[190:191], s[10:11], 0, v[138:139]
	s_add_i32 m0, s13, 0xe000
	s_nop 0
	global_load_lds_dwordx4 v[190:191], off
	s_waitcnt vmcnt(8)
	s_waitcnt lgkmcnt(0)
	s_barrier
; #define PG8_STAGE(bufoff, gbase, voff) do { _Pragma("unroll") for (int _i = 0; _i < 2; ++_i) \
;         __builtin_amdgcn_global_load_lds((const unsigned*)((const char*)(gbase) + (voff)[_i]), (LAS unsigned*)(lds + (bufoff) + ldsw + _i * 8192), 16, 0, 0); } while (0)
; #define PG8_LDA(dst, b, h) do { _Pragma("unroll") for (int m = 0; m < 4; ++m) _Pragma("unroll") for (int k = 0; k < 2; ++k) dst[m][k] = *(const LAS bf16x8*)(lds + PG8_SA(b, h) + aoff + m * 2048 + k * 1024); } while (0)
; #define PG8_LDB(dst, b, h) do { _Pragma("unroll") for (int n = 0; n < 2; ++n) _Pragma("unroll") for (int k = 0; k < 2; ++k) dst[n][k] = *(const LAS bf16x8*)(lds + PG8_SB(b, h) + boff + n * 2048 + k * 1024); } while (0)
; #define PG8_MMA(ai, bj, At, Bt) do { __builtin_amdgcn_s_setprio(1); _Pragma("unroll") for (int m = 0; m < 4; ++m) _Pragma("unroll") for (int n = 0; n < 2; ++n) _Pragma("unroll") for (int k = 0; k < 2; ++k) \
;         acc[ai][bj][m][n] = __builtin_amdgcn_mfma_f32_16x16x32_bf16(Bt[n][k], At[m][k], acc[ai][bj][m][n], 0, 0, 0); __builtin_amdgcn_s_setprio(0); } while (0)
; #define PG8_WAIT_V(n) asm volatile("s_waitcnt vmcnt(" #n ")" ::: "memory")
; #define PG8_WAIT_L(n) asm volatile("s_waitcnt lgkmcnt(" #n ")" ::: "memory")
; #define PG8_BAR __builtin_amdgcn_s_barrier()
; #define PG8_SCHED __builtin_amdgcn_sched_barrier(0)
; template <class Epi>
; __device__ __forceinline__ void gemm_phase(LAS unsigned char* lds, const Gemm g, const Sched& S, const Epi& E, const int tid) {
;     ...
;             PG8_LDB(B0, 0, 0); PG8_LDB(B1, 0, 1); PG8_SCHED; PG8_LDA(At, 0, 0); PG8_STAGE(PG8_SA(1, 1), a1 + hA, voffA);
;             PG8_WAIT_V(8); PG8_WAIT_L(0); PG8_BAR; PG8_MMA(0, 0, At, B0); PG8_MMA(0, 1, At, B1); PG8_BAR; PG8_SCHED;
;             PG8_LDA(At, 0, 1); PG8_STAGE(PG8_SB(0, 0), b2, voffB); PG8_STAGE(PG8_SB(0, 1), b2 + hB, voffB); PG8_STAGE(PG8_SA(0, 0), a2, voffA);
;             PG8_WAIT_V(8); PG8_WAIT_L(0); PG8_BAR; PG8_MMA(1, 0, At, B0); PG8_MMA(1, 1, At, B1); PG8_BAR; PG8_SCHED;
;             PG8_LDB(B0, 1, 0); PG8_LDB(B1, 1, 1); PG8_SCHED; PG8_LDA(At, 1, 0); PG8_STAGE(PG8_SA(0, 1), a2 + hA, voffA);
;             PG8_WAIT_V(8); PG8_WAIT_L(0); PG8_BAR; PG8_MMA(0, 0, At, B0); PG8_MMA(0, 1, At, B1); PG8_BAR; PG8_SCHED;
	s_setprio 1
	s_waitcnt lgkmcnt(0)
	v_mfma_f32_16x16x32_bf16 v[124:127], v[140:143], v[178:181], v[124:127]
	v_mfma_f32_16x16x32_bf16 v[120:123], v[152:155], v[178:181], v[120:123]
	v_mfma_f32_16x16x32_bf16 v[116:119], v[140:143], v[186:189], v[116:119]
	v_mfma_f32_16x16x32_bf16 v[108:111], v[152:155], v[186:189], v[108:111]
	v_mfma_f32_16x16x32_bf16 v[92:95], v[140:143], v[198:201], v[92:95]
	v_mfma_f32_16x16x32_bf16 v[88:91], v[152:155], v[198:201], v[88:91]
	v_mfma_f32_16x16x32_bf16 v[84:87], v[140:143], v[206:209], v[84:87]
	v_mfma_f32_16x16x32_bf16 v[76:79], v[152:155], v[206:209], v[76:79]
	v_mfma_f32_16x16x32_bf16 v[124:127], v[148:151], v[182:185], v[124:127]
	v_mfma_f32_16x16x32_bf16 v[120:123], v[156:159], v[182:185], v[120:123]
	v_mfma_f32_16x16x32_bf16 v[116:119], v[148:151], v[194:197], v[116:119]
	v_mfma_f32_16x16x32_bf16 v[108:111], v[156:159], v[194:197], v[108:111]
	v_mfma_f32_16x16x32_bf16 v[92:95], v[148:151], v[202:205], v[92:95]
	v_mfma_f32_16x16x32_bf16 v[88:91], v[156:159], v[202:205], v[88:91]
	v_mfma_f32_16x16x32_bf16 v[84:87], v[148:151], v[210:213], v[84:87]
	v_mfma_f32_16x16x32_bf16 v[76:79], v[156:159], v[210:213], v[76:79]
	s_setprio 0
	s_setprio 1
	v_mfma_f32_16x16x32_bf16 v[112:115], v[160:163], v[178:181], v[112:115]
	v_mfma_f32_16x16x32_bf16 v[104:107], v[168:171], v[178:181], v[104:107]
	v_mfma_f32_16x16x32_bf16 v[100:103], v[160:163], v[186:189], v[100:103]
	v_mfma_f32_16x16x32_bf16 v[96:99], v[168:171], v[186:189], v[96:99]
	v_mfma_f32_16x16x32_bf16 v[80:83], v[160:163], v[198:201], v[80:83]
	v_mfma_f32_16x16x32_bf16 v[72:75], v[168:171], v[198:201], v[72:75]
	v_mfma_f32_16x16x32_bf16 v[68:71], v[160:163], v[206:209], v[68:71]
	v_mfma_f32_16x16x32_bf16 v[64:67], v[168:171], v[206:209], v[64:67]
	v_mfma_f32_16x16x32_bf16 v[112:115], v[164:167], v[182:185], v[112:115]
	v_mfma_f32_16x16x32_bf16 v[104:107], v[172:175], v[182:185], v[104:107]
	v_mfma_f32_16x16x32_bf16 v[100:103], v[164:167], v[194:197], v[100:103]
	v_mfma_f32_16x16x32_bf16 v[96:99], v[172:175], v[194:197], v[96:99]
	v_mfma_f32_16x16x32_bf16 v[80:83], v[164:167], v[202:205], v[80:83]
	v_mfma_f32_16x16x32_bf16 v[72:75], v[172:175], v[202:205], v[72:75]
	v_mfma_f32_16x16x32_bf16 v[68:71], v[164:167], v[210:213], v[68:71]
	v_mfma_f32_16x16x32_bf16 v[64:67], v[172:175], v[210:213], v[64:67]
	s_setprio 0
	s_barrier
	s_add_i32 s37, vcc_lo, s39
	v_lshl_add_u64 v[190:191], s[74:75], 0, v[192:193]
	s_mov_b32 m0, s37
	ds_read_b128 v[178:181], v147 offset:16384
	ds_read_b128 v[182:185], v147 offset:17408
	ds_read_b128 v[186:189], v147 offset:18432
	ds_read_b128 v[194:197], v147 offset:19456
	ds_read_b128 v[198:201], v147 offset:20480
	ds_read_b128 v[202:205], v147 offset:21504
	ds_read_b128 v[206:209], v147 offset:22528
	ds_read_b128 v[210:213], v147 offset:23552
	global_load_lds_dwordx4 v[190:191], off
	s_add_i32 m0, s37, 0x2000
	s_add_u32 vcc_lo, s74, 0x40000
	v_lshl_add_u64 v[214:215], s[74:75], 0, v[132:133]
	s_addc_u32 vcc_hi, s75, 0
	s_add_i32 s35, s35, s39
	global_load_lds_dwordx4 v[214:215], off
	v_lshl_add_u64 v[216:217], vcc, 0, v[192:193]
	s_mov_b32 m0, s35
	v_lshl_add_u64 v[218:219], s[76:77], 0, v[130:131]
	global_load_lds_dwordx4 v[216:217], off
	v_lshl_add_u64 v[216:217], vcc, 0, v[132:133]
	s_add_i32 m0, s35, 0x2000
	s_nop 0
	global_load_lds_dwordx4 v[216:217], off
	v_lshl_add_u64 v[216:217], s[76:77], 0, v[128:129]
	s_mov_b32 m0, s13
	s_nop 0
	global_load_lds_dwordx4 v[216:217], off
	s_mov_b32 m0, s40
	s_nop 0
	global_load_lds_dwordx4 v[218:219], off
	s_waitcnt vmcnt(8)
	s_waitcnt lgkmcnt(0)
	s_barrier
	s_setprio 1
	s_waitcnt lgkmcnt(0)
	v_mfma_f32_16x16x32_bf16 v[60:63], v[140:143], v[178:181], v[60:63]
	v_mfma_f32_16x16x32_bf16 v[56:59], v[152:155], v[178:181], v[56:59]
	v_mfma_f32_16x16x32_bf16 v[52:55], v[140:143], v[186:189], v[52:55]
	v_mfma_f32_16x16x32_bf16 v[44:47], v[152:155], v[186:189], v[44:47]
	v_mfma_f32_16x16x32_bf16 v[28:31], v[140:143], v[198:201], v[28:31]
	v_mfma_f32_16x16x32_bf16 v[24:27], v[152:155], v[198:201], v[24:27]
	v_mfma_f32_16x16x32_bf16 v[20:23], v[140:143], v[206:209], v[20:23]
	v_mfma_f32_16x16x32_bf16 v[12:15], v[152:155], v[206:209], v[12:15]
	v_mfma_f32_16x16x32_bf16 v[60:63], v[148:151], v[182:185], v[60:63]
	v_mfma_f32_16x16x32_bf16 v[56:59], v[156:159], v[182:185], v[56:59]
	v_mfma_f32_16x16x32_bf16 v[52:55], v[148:151], v[194:197], v[52:55]
	v_mfma_f32_16x16x32_bf16 v[44:47], v[156:159], v[194:197], v[44:47]
	v_mfma_f32_16x16x32_bf16 v[28:31], v[148:151], v[202:205], v[28:31]
	v_mfma_f32_16x16x32_bf16 v[24:27], v[156:159], v[202:205], v[24:27]
	v_mfma_f32_16x16x32_bf16 v[20:23], v[148:151], v[210:213], v[20:23]
	v_mfma_f32_16x16x32_bf16 v[12:15], v[156:159], v[210:213], v[12:15]
	s_setprio 0
	s_setprio 1
	v_mfma_f32_16x16x32_bf16 v[48:51], v[160:163], v[178:181], v[48:51]
	v_mfma_f32_16x16x32_bf16 v[40:43], v[168:171], v[178:181], v[40:43]
	v_mfma_f32_16x16x32_bf16 v[36:39], v[160:163], v[186:189], v[36:39]
	v_mfma_f32_16x16x32_bf16 v[32:35], v[168:171], v[186:189], v[32:35]
	v_mfma_f32_16x16x32_bf16 v[16:19], v[160:163], v[198:201], v[16:19]
	v_mfma_f32_16x16x32_bf16 v[8:11], v[168:171], v[198:201], v[8:11]
	v_mfma_f32_16x16x32_bf16 v[4:7], v[160:163], v[206:209], v[4:7]
	v_mfma_f32_16x16x32_bf16 v[0:3], v[168:171], v[206:209], v[0:3]
	v_mfma_f32_16x16x32_bf16 v[48:51], v[164:167], v[182:185], v[48:51]
	v_mfma_f32_16x16x32_bf16 v[40:43], v[172:175], v[182:185], v[40:43]
	v_mfma_f32_16x16x32_bf16 v[36:39], v[164:167], v[194:197], v[36:39]
	v_mfma_f32_16x16x32_bf16 v[32:35], v[172:175], v[194:197], v[32:35]
	v_mfma_f32_16x16x32_bf16 v[16:19], v[164:167], v[202:205], v[16:19]
	v_mfma_f32_16x16x32_bf16 v[8:11], v[172:175], v[202:205], v[8:11]
	v_mfma_f32_16x16x32_bf16 v[4:7], v[164:167], v[210:213], v[4:7]
	v_mfma_f32_16x16x32_bf16 v[0:3], v[172:175], v[210:213], v[0:3]
	s_setprio 0
	s_barrier
; #define PG8_STAGE(bufoff, gbase, voff) do { _Pragma("unroll") for (int _i = 0; _i < 2; ++_i) \
;         __builtin_amdgcn_global_load_lds((const unsigned*)((const char*)(gbase) + (voff)[_i]), (LAS unsigned*)(lds + (bufoff) + ldsw + _i * 8192), 16, 0, 0); } while (0)
; #define PG8_LDA(dst, b, h) do { _Pragma("unroll") for (int m = 0; m < 4; ++m) _Pragma("unroll") for (int k = 0; k < 2; ++k) dst[m][k] = *(const LAS bf16x8*)(lds + PG8_SA(b, h) + aoff + m * 2048 + k * 1024); } while (0)
; #define PG8_LDB(dst, b, h) do { _Pragma("unroll") for (int n = 0; n < 2; ++n) _Pragma("unroll") for (int k = 0; k < 2; ++k) dst[n][k] = *(const LAS bf16x8*)(lds + PG8_SB(b, h) + boff + n * 2048 + k * 1024); } while (0)
; #define PG8_MMA(ai, bj, At, Bt) do { __builtin_amdgcn_s_setprio(1); _Pragma("unroll") for (int m = 0; m < 4; ++m) _Pragma("unroll") for (int n = 0; n < 2; ++n) _Pragma("unroll") for (int k = 0; k < 2; ++k) \
;         acc[ai][bj][m][n] = __builtin_amdgcn_mfma_f32_16x16x32_bf16(Bt[n][k], At[m][k], acc[ai][bj][m][n], 0, 0, 0); __builtin_amdgcn_s_setprio(0); } while (0)
; #define PG8_WAIT_V(n) asm volatile("s_waitcnt vmcnt(" #n ")" ::: "memory")
; #define PG8_WAIT_L(n) asm volatile("s_waitcnt lgkmcnt(" #n ")" ::: "memory")
; #define PG8_BAR __builtin_amdgcn_s_barrier()
; #define PG8_SCHED __builtin_amdgcn_sched_barrier(0)
; template <class Epi>
; __device__ __forceinline__ void gemm_phase(LAS unsigned char* lds, const Gemm g, const Sched& S, const Epi& E, const int tid) {
;     ...
;             PG8_LDB(B0, 1, 0); PG8_LDB(B1, 1, 1); PG8_SCHED; PG8_LDA(At, 1, 0); PG8_STAGE(PG8_SA(0, 1), a2 + hA, voffA);
;             PG8_WAIT_V(8); PG8_WAIT_L(0); PG8_BAR; PG8_MMA(0, 0, At, B0); PG8_MMA(0, 1, At, B1); PG8_BAR; PG8_SCHED;
	s_add_i32 s35, 0, 0x18000
	s_add_i32 s37, 0, 0x1c000
	v_add_u32_e32 v156, s35, v145
	v_add_u32_e32 v172, s37, v145
	ds_read_b128 v[140:143], v156
	ds_read_b128 v[148:151], v156 offset:1024
	ds_read_b128 v[152:155], v156 offset:2048
	ds_read_b128 v[156:159], v156 offset:3072
	ds_read_b128 v[160:163], v172
	ds_read_b128 v[164:167], v172 offset:1024
	ds_read_b128 v[168:171], v172 offset:2048
	ds_read_b128 v[172:175], v172 offset:3072
	s_add_u32 s76, s76, 0x40000
	s_addc_u32 s77, s77, 0
	s_mov_b32 m0, s45
	v_lshl_add_u64 v[224:225], s[76:77], 0, v[128:129]
	ds_read_b128 v[178:181], v147 offset:32768
	ds_read_b128 v[182:185], v147 offset:33792
	ds_read_b128 v[186:189], v147 offset:34816
	ds_read_b128 v[194:197], v147 offset:35840
	ds_read_b128 v[198:201], v147 offset:36864
	ds_read_b128 v[202:205], v147 offset:37888
	ds_read_b128 v[206:209], v147 offset:38912
	ds_read_b128 v[210:213], v147 offset:39936
	global_load_lds_dwordx4 v[224:225], off
	v_lshl_add_u64 v[224:225], s[76:77], 0, v[130:131]
	s_mov_b32 m0, s47
	s_nop 0
	global_load_lds_dwordx4 v[224:225], off
	s_waitcnt vmcnt(8)
	s_waitcnt lgkmcnt(0)
	s_barrier
	s_setprio 1
	s_waitcnt lgkmcnt(0)
	v_mfma_f32_16x16x32_bf16 v[124:127], v[140:143], v[178:181], v[124:127]
	v_mfma_f32_16x16x32_bf16 v[120:123], v[152:155], v[178:181], v[120:123]
	v_mfma_f32_16x16x32_bf16 v[116:119], v[140:143], v[186:189], v[116:119]
	v_mfma_f32_16x16x32_bf16 v[108:111], v[152:155], v[186:189], v[108:111]
	v_mfma_f32_16x16x32_bf16 v[92:95], v[140:143], v[198:201], v[92:95]
	v_mfma_f32_16x16x32_bf16 v[88:91], v[152:155], v[198:201], v[88:91]
	v_mfma_f32_16x16x32_bf16 v[84:87], v[140:143], v[206:209], v[84:87]
	v_mfma_f32_16x16x32_bf16 v[76:79], v[152:155], v[206:209], v[76:79]
	v_mfma_f32_16x16x32_bf16 v[124:127], v[148:151], v[182:185], v[124:127]
	v_mfma_f32_16x16x32_bf16 v[120:123], v[156:159], v[182:185], v[120:123]
	v_mfma_f32_16x16x32_bf16 v[116:119], v[148:151], v[194:197], v[116:119]
	v_mfma_f32_16x16x32_bf16 v[108:111], v[156:159], v[194:197], v[108:111]
	v_mfma_f32_16x16x32_bf16 v[92:95], v[148:151], v[202:205], v[92:95]
	v_mfma_f32_16x16x32_bf16 v[88:91], v[156:159], v[202:205], v[88:91]
	v_mfma_f32_16x16x32_bf16 v[84:87], v[148:151], v[210:213], v[84:87]
	v_mfma_f32_16x16x32_bf16 v[76:79], v[156:159], v[210:213], v[76:79]
	s_setprio 0
	s_setprio 1
	v_mfma_f32_16x16x32_bf16 v[112:115], v[160:163], v[178:181], v[112:115]
	v_mfma_f32_16x16x32_bf16 v[104:107], v[168:171], v[178:181], v[104:107]
	v_mfma_f32_16x16x32_bf16 v[100:103], v[160:163], v[186:189], v[100:103]
	v_mfma_f32_16x16x32_bf16 v[96:99], v[168:171], v[186:189], v[96:99]
	v_mfma_f32_16x16x32_bf16 v[80:83], v[160:163], v[198:201], v[80:83]
	v_mfma_f32_16x16x32_bf16 v[72:75], v[168:171], v[198:201], v[72:75]
	v_mfma_f32_16x16x32_bf16 v[68:71], v[160:163], v[206:209], v[68:71]
	v_mfma_f32_16x16x32_bf16 v[64:67], v[168:171], v[206:209], v[64:67]
	v_mfma_f32_16x16x32_bf16 v[112:115], v[164:167], v[182:185], v[112:115]
	v_mfma_f32_16x16x32_bf16 v[104:107], v[172:175], v[182:185], v[104:107]
	v_mfma_f32_16x16x32_bf16 v[100:103], v[164:167], v[194:197], v[100:103]
	v_mfma_f32_16x16x32_bf16 v[96:99], v[172:175], v[194:197], v[96:99]
	v_mfma_f32_16x16x32_bf16 v[80:83], v[164:167], v[202:205], v[80:83]
	v_mfma_f32_16x16x32_bf16 v[72:75], v[172:175], v[202:205], v[72:75]
	v_mfma_f32_16x16x32_bf16 v[68:71], v[164:167], v[210:213], v[68:71]
	v_mfma_f32_16x16x32_bf16 v[64:67], v[172:175], v[210:213], v[64:67]
	s_setprio 0
	s_barrier
; #define PG8_STAGE(bufoff, gbase, voff) do { _Pragma("unroll") for (int _i = 0; _i < 2; ++_i) \
;         __builtin_amdgcn_global_load_lds((const unsigned*)((const char*)(gbase) + (voff)[_i]), (LAS unsigned*)(lds + (bufoff) + ldsw + _i * 8192), 16, 0, 0); } while (0)
; #define PG8_LDA(dst, b, h) do { _Pragma("unroll") for (int m = 0; m < 4; ++m) _Pragma("unroll") for (int k = 0; k < 2; ++k) dst[m][k] = *(const LAS bf16x8*)(lds + PG8_SA(b, h) + aoff + m * 2048 + k * 1024); } while (0)
; #define PG8_MMA(ai, bj, At, Bt) do { __builtin_amdgcn_s_setprio(1); _Pragma("unroll") for (int m = 0; m < 4; ++m) _Pragma("unroll") for (int n = 0; n < 2; ++n) _Pragma("unroll") for (int k = 0; k < 2; ++k) \
;         acc[ai][bj][m][n] = __builtin_amdgcn_mfma_f32_16x16x32_bf16(Bt[n][k], At[m][k], acc[ai][bj][m][n], 0, 0, 0); __builtin_amdgcn_s_setprio(0); } while (0)
; #define PG8_WAIT_V(n) asm volatile("s_waitcnt vmcnt(" #n ")" ::: "memory")
; #define PG8_WAIT_L(n) asm volatile("s_waitcnt lgkmcnt(" #n ")" ::: "memory")
; #define PG8_BAR __builtin_amdgcn_s_barrier()
; #define PG8_SCHED __builtin_amdgcn_sched_barrier(0)
; template <class Epi>
; __device__ __forceinline__ void gemm_phase(LAS unsigned char* lds, const Gemm g, const Sched& S, const Epi& E, const int tid) {
;     ...
;             PG8_LDA(At, 1, 1); PG8_STAGE(PG8_SB(1, 0), b3, voffB); PG8_STAGE(PG8_SB(1, 1), b3 + hB, voffB); PG8_STAGE(PG8_SA(1, 0), a3, voffA);
;             PG8_WAIT_V(8); PG8_WAIT_L(0); PG8_BAR; PG8_MMA(1, 0, At, B0); PG8_MMA(1, 1, At, B1); PG8_BAR; PG8_SCHED;
	s_add_i32 s35, s35, s39
	v_lshl_add_u64 v[190:191], v[190:191], 0, s[94:95]
	s_mov_b32 m0, s35
	ds_read_b128 v[178:181], v147 offset:49152
	ds_read_b128 v[182:185], v147 offset:50176
	ds_read_b128 v[186:189], v147 offset:51200
	ds_read_b128 v[194:197], v147 offset:52224
	ds_read_b128 v[198:201], v147 offset:53248
	ds_read_b128 v[202:205], v147 offset:54272
	ds_read_b128 v[206:209], v147 offset:55296
	ds_read_b128 v[210:213], v147 offset:56320
	global_load_lds_dwordx4 v[190:191], off
	s_add_i32 m0, s35, 0x2000
	s_add_u32 s74, s74, 0x40080
	v_lshl_add_u64 v[190:191], v[214:215], 0, s[94:95]
	s_addc_u32 s75, s75, 0
	s_add_i32 s35, s37, s39
	global_load_lds_dwordx4 v[190:191], off
	v_lshl_add_u64 v[190:191], s[74:75], 0, v[192:193]
	s_mov_b32 m0, s35
	s_nop 0
	global_load_lds_dwordx4 v[190:191], off
	v_lshl_add_u64 v[190:191], s[74:75], 0, v[132:133]
	s_add_i32 m0, s35, 0x2000
	s_nop 0
	global_load_lds_dwordx4 v[190:191], off
	v_lshl_add_u64 v[190:191], v[216:217], 0, s[94:95]
	s_mov_b32 m0, s78
	s_nop 0
	global_load_lds_dwordx4 v[190:191], off
	v_lshl_add_u64 v[190:191], v[218:219], 0, s[94:95]
	s_mov_b32 m0, s80
	s_nop 0
	global_load_lds_dwordx4 v[190:191], off
	s_waitcnt vmcnt(8)
	s_waitcnt lgkmcnt(0)
	s_barrier
	s_setprio 1
	s_waitcnt lgkmcnt(0)
	v_mfma_f32_16x16x32_bf16 v[60:63], v[140:143], v[178:181], v[60:63]
	v_mfma_f32_16x16x32_bf16 v[56:59], v[152:155], v[178:181], v[56:59]
	v_mfma_f32_16x16x32_bf16 v[52:55], v[140:143], v[186:189], v[52:55]
	v_mfma_f32_16x16x32_bf16 v[44:47], v[152:155], v[186:189], v[44:47]
	v_mfma_f32_16x16x32_bf16 v[28:31], v[140:143], v[198:201], v[28:31]
	v_mfma_f32_16x16x32_bf16 v[24:27], v[152:155], v[198:201], v[24:27]
	v_mfma_f32_16x16x32_bf16 v[20:23], v[140:143], v[206:209], v[20:23]
	v_mfma_f32_16x16x32_bf16 v[12:15], v[152:155], v[206:209], v[12:15]
	v_mfma_f32_16x16x32_bf16 v[60:63], v[148:151], v[182:185], v[60:63]
	v_mfma_f32_16x16x32_bf16 v[56:59], v[156:159], v[182:185], v[56:59]
	v_mfma_f32_16x16x32_bf16 v[52:55], v[148:151], v[194:197], v[52:55]
	v_mfma_f32_16x16x32_bf16 v[44:47], v[156:159], v[194:197], v[44:47]
	v_mfma_f32_16x16x32_bf16 v[28:31], v[148:151], v[202:205], v[28:31]
	v_mfma_f32_16x16x32_bf16 v[24:27], v[156:159], v[202:205], v[24:27]
	v_mfma_f32_16x16x32_bf16 v[20:23], v[148:151], v[210:213], v[20:23]
	v_mfma_f32_16x16x32_bf16 v[12:15], v[156:159], v[210:213], v[12:15]
	s_setprio 0
	s_setprio 1
	v_mfma_f32_16x16x32_bf16 v[48:51], v[160:163], v[178:181], v[48:51]
	v_mfma_f32_16x16x32_bf16 v[40:43], v[168:171], v[178:181], v[40:43]
	v_mfma_f32_16x16x32_bf16 v[36:39], v[160:163], v[186:189], v[36:39]
	v_mfma_f32_16x16x32_bf16 v[32:35], v[168:171], v[186:189], v[32:35]
	v_mfma_f32_16x16x32_bf16 v[16:19], v[160:163], v[198:201], v[16:19]
	v_mfma_f32_16x16x32_bf16 v[8:11], v[168:171], v[198:201], v[8:11]
	v_mfma_f32_16x16x32_bf16 v[4:7], v[160:163], v[206:209], v[4:7]
	v_mfma_f32_16x16x32_bf16 v[0:3], v[168:171], v[206:209], v[0:3]
	v_mfma_f32_16x16x32_bf16 v[48:51], v[164:167], v[182:185], v[48:51]
	v_mfma_f32_16x16x32_bf16 v[40:43], v[172:175], v[182:185], v[40:43]
	v_mfma_f32_16x16x32_bf16 v[36:39], v[164:167], v[194:197], v[36:39]
	v_mfma_f32_16x16x32_bf16 v[32:35], v[172:175], v[194:197], v[32:35]
	v_mfma_f32_16x16x32_bf16 v[16:19], v[164:167], v[202:205], v[16:19]
	v_mfma_f32_16x16x32_bf16 v[8:11], v[172:175], v[202:205], v[8:11]
	v_mfma_f32_16x16x32_bf16 v[4:7], v[164:167], v[210:213], v[4:7]
	v_mfma_f32_16x16x32_bf16 v[0:3], v[172:175], v[210:213], v[0:3]
	s_add_i32 s21, s21, 2
	s_add_u32 s10, s10, 0x100
	s_addc_u32 s11, s11, 0
	s_add_u32 s9, s9, 0x100
	s_addc_u32 s19, s19, 0
	s_cmp_gt_u32 s21, 13
	s_setprio 0
	s_barrier
	s_cbranch_scc0 .LBB0_333

; #define PG8_STAGE(bufoff, gbase, voff) do { _Pragma("unroll") for (int _i = 0; _i < 2; ++_i) \
;         __builtin_amdgcn_global_load_lds((const unsigned*)((const char*)(gbase) + (voff)[_i]), (LAS unsigned*)(lds + (bufoff) + ldsw + _i * 8192), 16, 0, 0); } while (0)
; #define PG8_LDA(dst, b, h) do { _Pragma("unroll") for (int m = 0; m < 4; ++m) _Pragma("unroll") for (int k = 0; k < 2; ++k) dst[m][k] = *(const LAS bf16x8*)(lds + PG8_SA(b, h) + aoff + m * 2048 + k * 1024); } while (0)
; #define PG8_LDB(dst, b, h) do { _Pragma("unroll") for (int n = 0; n < 2; ++n) _Pragma("unroll") for (int k = 0; k < 2; ++k) dst[n][k] = *(const LAS bf16x8*)(lds + PG8_SB(b, h) + boff + n * 2048 + k * 1024); } while (0)
; #define PG8_MMA(ai, bj, At, Bt) do { __builtin_amdgcn_s_setprio(1); _Pragma("unroll") for (int m = 0; m < 4; ++m) _Pragma("unroll") for (int n = 0; n < 2; ++n) _Pragma("unroll") for (int k = 0; k < 2; ++k) \
;         acc[ai][bj][m][n] = __builtin_amdgcn_mfma_f32_16x16x32_bf16(Bt[n][k], At[m][k], acc[ai][bj][m][n], 0, 0, 0); __builtin_amdgcn_s_setprio(0); } while (0)
; #define PG8_BAR __builtin_amdgcn_s_barrier()
; template <class Epi>
; __device__ __forceinline__ void gemm_phase(LAS unsigned char* lds, const Gemm g, const Sched& S, const Epi& E, const int tid) {
;     ...
;         for (int t = 0; t < nt; t += 2) {
;             const bool last = (t == nt - 2);
;             const char* a1 = cA + (size_t)(t + 1) * kstep;
;             const char* a2 = last ? nA : cA + (size_t)(t + 2) * kstep; const char* b2 = last ? nB : cB + (size_t)(t + 2) * kstep;
;             const char* a3 = a2 + kstep; const char* b3 = b2 + kstep;
;             PG8_LDB(B0, 0, 0); PG8_LDB(B1, 0, 1); PG8_SCHED; PG8_LDA(At, 0, 0); PG8_STAGE(PG8_SA(1, 1), a1 + hA, voffA);
;             PG8_WAIT_V(8); PG8_WAIT_L(0); PG8_BAR; PG8_MMA(0, 0, At, B0); PG8_MMA(0, 1, At, B1); PG8_BAR; PG8_SCHED;
;             PG8_LDA(At, 0, 1); PG8_STAGE(PG8_SB(0, 0), b2, voffB); PG8_STAGE(PG8_SB(0, 1), b2 + hB, voffB); PG8_STAGE(PG8_SA(0, 0), a2, voffA);
;             PG8_WAIT_V(8); PG8_WAIT_L(0); PG8_BAR; PG8_MMA(1, 0, At, B0); PG8_MMA(1, 1, At, B1); PG8_BAR; PG8_SCHED;
;             PG8_LDB(B0, 1, 0); PG8_LDB(B1, 1, 1); PG8_SCHED; PG8_LDA(At, 1, 0); PG8_STAGE(PG8_SA(0, 1), a2 + hA, voffA);
;             PG8_WAIT_V(8); PG8_WAIT_L(0); PG8_BAR; PG8_MMA(0, 0, At, B0); PG8_MMA(0, 1, At, B1); PG8_BAR; PG8_SCHED;
.LBB0_993:
	s_add_u32 s13, s18, 0x100
	s_addc_u32 s40, s19, 0
	s_mov_b32 s42, -2
	s_add_u32 s18, s16, 0x100
	s_addc_u32 s19, s17, 0
	s_add_i32 s45, 0, 0x10000
	s_cmp_eq_u32 s42, 4
	s_cselect_b32 s23, s7, s19
	s_cselect_b32 s22, s6, s18
	s_cselect_b32 s21, s15, s40
	s_cselect_b32 s20, s14, s13
	s_add_i32 s51, 0, 0x14000
	v_add_u32_e32 v128, s45, v183
	v_add_u32_e32 v156, s51, v183
	ds_read_b128 v[104:107], v128
	ds_read_b128 v[112:115], v128 offset:1024
	ds_read_b128 v[124:127], v128 offset:2048
	ds_read_b128 v[128:131], v128 offset:3072
	ds_read_b128 v[136:139], v156
	ds_read_b128 v[144:147], v156 offset:1024
	ds_read_b128 v[152:155], v156 offset:2048
	ds_read_b128 v[156:159], v156 offset:3072
	v_lshl_add_u64 v[190:191], s[16:17], 0, v[166:167]
	s_add_i32 m0, s73, 0xc000
	ds_read_b128 v[170:173], v185
	ds_read_b128 v[174:177], v185 offset:1024
	ds_read_b128 v[178:181], v185 offset:2048
	ds_read_b128 v[186:189], v185 offset:3072
	ds_read_b128 v[194:197], v185 offset:4096
	ds_read_b128 v[198:201], v185 offset:5120
	ds_read_b128 v[204:207], v185 offset:6144
	ds_read_b128 v[208:211], v185 offset:7168
	global_load_lds_dwordx4 v[190:191], off
	v_lshl_add_u64 v[190:191], s[16:17], 0, v[168:169]
	s_add_i32 m0, s73, 0xe000
	s_nop 0
	global_load_lds_dwordx4 v[190:191], off
	s_waitcnt vmcnt(8)
	s_waitcnt lgkmcnt(0)
	s_barrier
	s_setprio 1
	s_waitcnt lgkmcnt(0)
	v_mfma_f32_16x16x32_bf16 v[148:151], v[104:107], v[170:173], 0
	v_mfma_f32_16x16x32_bf16 v[140:143], v[124:127], v[170:173], 0
	v_mfma_f32_16x16x32_bf16 v[116:119], v[104:107], v[178:181], 0
	v_mfma_f32_16x16x32_bf16 v[108:111], v[124:127], v[178:181], 0
	v_mfma_f32_16x16x32_bf16 v[92:95], v[104:107], v[194:197], 0
	v_mfma_f32_16x16x32_bf16 v[88:91], v[124:127], v[194:197], 0
	v_mfma_f32_16x16x32_bf16 v[76:79], v[104:107], v[204:207], 0
	v_mfma_f32_16x16x32_bf16 v[72:75], v[124:127], v[204:207], 0
	v_mfma_f32_16x16x32_bf16 v[148:151], v[112:115], v[174:177], v[148:151]
	v_mfma_f32_16x16x32_bf16 v[140:143], v[128:131], v[174:177], v[140:143]
	v_mfma_f32_16x16x32_bf16 v[116:119], v[112:115], v[186:189], v[116:119]
	v_mfma_f32_16x16x32_bf16 v[108:111], v[128:131], v[186:189], v[108:111]
	v_mfma_f32_16x16x32_bf16 v[92:95], v[112:115], v[198:201], v[92:95]
	v_mfma_f32_16x16x32_bf16 v[88:91], v[128:131], v[198:201], v[88:91]
	v_mfma_f32_16x16x32_bf16 v[76:79], v[112:115], v[208:211], v[76:79]
	v_mfma_f32_16x16x32_bf16 v[72:75], v[128:131], v[208:211], v[72:75]
	s_setprio 0
	s_setprio 1
	v_mfma_f32_16x16x32_bf16 v[132:135], v[136:139], v[170:173], 0
	v_mfma_f32_16x16x32_bf16 v[120:123], v[152:155], v[170:173], 0
	v_mfma_f32_16x16x32_bf16 v[100:103], v[136:139], v[178:181], 0
	v_mfma_f32_16x16x32_bf16 v[96:99], v[152:155], v[178:181], 0
	v_mfma_f32_16x16x32_bf16 v[84:87], v[136:139], v[194:197], 0
	v_mfma_f32_16x16x32_bf16 v[80:83], v[152:155], v[194:197], 0
	v_mfma_f32_16x16x32_bf16 v[68:71], v[136:139], v[204:207], 0
	v_mfma_f32_16x16x32_bf16 v[64:67], v[152:155], v[204:207], 0
	v_mfma_f32_16x16x32_bf16 v[132:135], v[144:147], v[174:177], v[132:135]
	v_mfma_f32_16x16x32_bf16 v[120:123], v[156:159], v[174:177], v[120:123]
	v_mfma_f32_16x16x32_bf16 v[100:103], v[144:147], v[186:189], v[100:103]
	v_mfma_f32_16x16x32_bf16 v[96:99], v[156:159], v[186:189], v[96:99]
	v_mfma_f32_16x16x32_bf16 v[84:87], v[144:147], v[198:201], v[84:87]
	v_mfma_f32_16x16x32_bf16 v[80:83], v[156:159], v[198:201], v[80:83]
	v_mfma_f32_16x16x32_bf16 v[68:71], v[144:147], v[208:211], v[68:71]
	v_mfma_f32_16x16x32_bf16 v[64:67], v[156:159], v[208:211], v[64:67]
	s_setprio 0
	s_barrier
	s_add_i32 s16, s45, s47
	v_lshl_add_u64 v[190:191], s[20:21], 0, v[192:193]
	s_mov_b32 m0, s16
	ds_read_b128 v[170:173], v185 offset:16384
	ds_read_b128 v[174:177], v185 offset:17408
	ds_read_b128 v[178:181], v185 offset:18432
	ds_read_b128 v[186:189], v185 offset:19456
	ds_read_b128 v[194:197], v185 offset:20480
	ds_read_b128 v[198:201], v185 offset:21504
	ds_read_b128 v[204:207], v185 offset:22528
	ds_read_b128 v[208:211], v185 offset:23552
	global_load_lds_dwordx4 v[190:191], off
	s_add_i32 m0, s16, 0x2000
	s_add_u32 s16, s20, 0x20000
	v_lshl_add_u64 v[212:213], s[20:21], 0, v[164:165]
	s_addc_u32 s17, s21, 0
	s_add_i32 s45, s51, s47
	global_load_lds_dwordx4 v[212:213], off
	v_lshl_add_u64 v[214:215], s[16:17], 0, v[192:193]
	s_mov_b32 m0, s45
	v_lshl_add_u64 v[216:217], s[22:23], 0, v[162:163]
	global_load_lds_dwordx4 v[214:215], off
	v_lshl_add_u64 v[214:215], s[16:17], 0, v[164:165]
	s_add_i32 m0, s45, 0x2000
	s_nop 0
	global_load_lds_dwordx4 v[214:215], off
	v_lshl_add_u64 v[214:215], s[22:23], 0, v[160:161]
	s_mov_b32 m0, s73
	s_nop 0
	global_load_lds_dwordx4 v[214:215], off
	s_mov_b32 m0, s74
	s_nop 0
	global_load_lds_dwordx4 v[216:217], off
	s_waitcnt vmcnt(8)
	s_waitcnt lgkmcnt(0)
	s_barrier
; #define PG8_STAGE(bufoff, gbase, voff) do { _Pragma("unroll") for (int _i = 0; _i < 2; ++_i) \
;         __builtin_amdgcn_global_load_lds((const unsigned*)((const char*)(gbase) + (voff)[_i]), (LAS unsigned*)(lds + (bufoff) + ldsw + _i * 8192), 16, 0, 0); } while (0)
; #define PG8_LDA(dst, b, h) do { _Pragma("unroll") for (int m = 0; m < 4; ++m) _Pragma("unroll") for (int k = 0; k < 2; ++k) dst[m][k] = *(const LAS bf16x8*)(lds + PG8_SA(b, h) + aoff + m * 2048 + k * 1024); } while (0)
; #define PG8_LDB(dst, b, h) do { _Pragma("unroll") for (int n = 0; n < 2; ++n) _Pragma("unroll") for (int k = 0; k < 2; ++k) dst[n][k] = *(const LAS bf16x8*)(lds + PG8_SB(b, h) + boff + n * 2048 + k * 1024); } while (0)
; #define PG8_MMA(ai, bj, At, Bt) do { __builtin_amdgcn_s_setprio(1); _Pragma("unroll") for (int m = 0; m < 4; ++m) _Pragma("unroll") for (int n = 0; n < 2; ++n) _Pragma("unroll") for (int k = 0; k < 2; ++k) \
;         acc[ai][bj][m][n] = __builtin_amdgcn_mfma_f32_16x16x32_bf16(Bt[n][k], At[m][k], acc[ai][bj][m][n], 0, 0, 0); __builtin_amdgcn_s_setprio(0); } while (0)
; #define PG8_WAIT_V(n) asm volatile("s_waitcnt vmcnt(" #n ")" ::: "memory")
; #define PG8_WAIT_L(n) asm volatile("s_waitcnt lgkmcnt(" #n ")" ::: "memory")
; #define PG8_BAR __builtin_amdgcn_s_barrier()
; #define PG8_SCHED __builtin_amdgcn_sched_barrier(0)
; template <class Epi>
; __device__ __forceinline__ void gemm_phase(LAS unsigned char* lds, const Gemm g, const Sched& S, const Epi& E, const int tid) {
;     ...
;             PG8_WAIT_V(8); PG8_WAIT_L(0); PG8_BAR; PG8_MMA(0, 0, At, B0); PG8_MMA(0, 1, At, B1); PG8_BAR; PG8_SCHED;
;             PG8_LDA(At, 0, 1); PG8_STAGE(PG8_SB(0, 0), b2, voffB); PG8_STAGE(PG8_SB(0, 1), b2 + hB, voffB); PG8_STAGE(PG8_SA(0, 0), a2, voffA);
;             PG8_WAIT_V(8); PG8_WAIT_L(0); PG8_BAR; PG8_MMA(1, 0, At, B0); PG8_MMA(1, 1, At, B1); PG8_BAR; PG8_SCHED;
;             PG8_LDB(B0, 1, 0); PG8_LDB(B1, 1, 1); PG8_SCHED; PG8_LDA(At, 1, 0); PG8_STAGE(PG8_SA(0, 1), a2 + hA, voffA);
;             PG8_WAIT_V(8); PG8_WAIT_L(0); PG8_BAR; PG8_MMA(0, 0, At, B0); PG8_MMA(0, 1, At, B1); PG8_BAR; PG8_SCHED;
	s_setprio 1
	s_waitcnt lgkmcnt(0)
	v_mfma_f32_16x16x32_bf16 v[60:63], v[104:107], v[170:173], 0
	v_mfma_f32_16x16x32_bf16 v[56:59], v[124:127], v[170:173], 0
	v_mfma_f32_16x16x32_bf16 v[44:47], v[104:107], v[178:181], 0
	v_mfma_f32_16x16x32_bf16 v[40:43], v[124:127], v[178:181], 0
	v_mfma_f32_16x16x32_bf16 v[28:31], v[104:107], v[194:197], 0
	v_mfma_f32_16x16x32_bf16 v[24:27], v[124:127], v[194:197], 0
	v_mfma_f32_16x16x32_bf16 v[12:15], v[104:107], v[204:207], 0
	v_mfma_f32_16x16x32_bf16 v[8:11], v[124:127], v[204:207], 0
	v_mfma_f32_16x16x32_bf16 v[60:63], v[112:115], v[174:177], v[60:63]
	v_mfma_f32_16x16x32_bf16 v[56:59], v[128:131], v[174:177], v[56:59]
	v_mfma_f32_16x16x32_bf16 v[44:47], v[112:115], v[186:189], v[44:47]
	v_mfma_f32_16x16x32_bf16 v[40:43], v[128:131], v[186:189], v[40:43]
	v_mfma_f32_16x16x32_bf16 v[28:31], v[112:115], v[198:201], v[28:31]
	v_mfma_f32_16x16x32_bf16 v[24:27], v[128:131], v[198:201], v[24:27]
	v_mfma_f32_16x16x32_bf16 v[12:15], v[112:115], v[208:211], v[12:15]
	v_mfma_f32_16x16x32_bf16 v[8:11], v[128:131], v[208:211], v[8:11]
	s_setprio 0
	s_setprio 1
	v_mfma_f32_16x16x32_bf16 v[52:55], v[136:139], v[170:173], 0
	v_mfma_f32_16x16x32_bf16 v[48:51], v[152:155], v[170:173], 0
	v_mfma_f32_16x16x32_bf16 v[36:39], v[136:139], v[178:181], 0
	v_mfma_f32_16x16x32_bf16 v[32:35], v[152:155], v[178:181], 0
	v_mfma_f32_16x16x32_bf16 v[20:23], v[136:139], v[194:197], 0
	v_mfma_f32_16x16x32_bf16 v[16:19], v[152:155], v[194:197], 0
	v_mfma_f32_16x16x32_bf16 v[4:7], v[136:139], v[204:207], 0
	v_mfma_f32_16x16x32_bf16 v[0:3], v[152:155], v[204:207], 0
	v_mfma_f32_16x16x32_bf16 v[52:55], v[144:147], v[174:177], v[52:55]
	v_mfma_f32_16x16x32_bf16 v[48:51], v[156:159], v[174:177], v[48:51]
	v_mfma_f32_16x16x32_bf16 v[36:39], v[144:147], v[186:189], v[36:39]
	v_mfma_f32_16x16x32_bf16 v[32:35], v[156:159], v[186:189], v[32:35]
	v_mfma_f32_16x16x32_bf16 v[20:23], v[144:147], v[198:201], v[20:23]
	v_mfma_f32_16x16x32_bf16 v[16:19], v[156:159], v[198:201], v[16:19]
	v_mfma_f32_16x16x32_bf16 v[4:7], v[144:147], v[208:211], v[4:7]
	v_mfma_f32_16x16x32_bf16 v[0:3], v[156:159], v[208:211], v[0:3]
	s_setprio 0
	s_barrier
	s_add_i32 s45, 0, 0x18000
	s_add_i32 s51, 0, 0x1c000
	v_add_u32_e32 v128, s45, v183
	v_add_u32_e32 v156, s51, v183
	ds_read_b128 v[104:107], v128
	ds_read_b128 v[112:115], v128 offset:1024
	ds_read_b128 v[124:127], v128 offset:2048
	ds_read_b128 v[128:131], v128 offset:3072
	ds_read_b128 v[136:139], v156
	ds_read_b128 v[144:147], v156 offset:1024
	ds_read_b128 v[152:155], v156 offset:2048
	ds_read_b128 v[156:159], v156 offset:3072
	s_add_u32 s16, s22, 0x120000
	s_addc_u32 s17, s23, 0
	s_mov_b32 m0, s75
	v_lshl_add_u64 v[218:219], s[16:17], 0, v[160:161]
	ds_read_b128 v[170:173], v185 offset:32768
	ds_read_b128 v[174:177], v185 offset:33792
	ds_read_b128 v[178:181], v185 offset:34816
	ds_read_b128 v[186:189], v185 offset:35840
	ds_read_b128 v[194:197], v185 offset:36864
	ds_read_b128 v[198:201], v185 offset:37888
	ds_read_b128 v[204:207], v185 offset:38912
	ds_read_b128 v[208:211], v185 offset:39936
	global_load_lds_dwordx4 v[218:219], off
	v_lshl_add_u64 v[218:219], s[16:17], 0, v[162:163]
	s_mov_b32 m0, s76
	s_nop 0
	global_load_lds_dwordx4 v[218:219], off
	s_waitcnt vmcnt(8)
	s_waitcnt lgkmcnt(0)
	s_barrier
	s_setprio 1
	s_waitcnt lgkmcnt(0)
	v_mfma_f32_16x16x32_bf16 v[148:151], v[104:107], v[170:173], v[148:151]
	v_mfma_f32_16x16x32_bf16 v[140:143], v[124:127], v[170:173], v[140:143]
	v_mfma_f32_16x16x32_bf16 v[116:119], v[104:107], v[178:181], v[116:119]
	v_mfma_f32_16x16x32_bf16 v[108:111], v[124:127], v[178:181], v[108:111]
	v_mfma_f32_16x16x32_bf16 v[92:95], v[104:107], v[194:197], v[92:95]
	v_mfma_f32_16x16x32_bf16 v[88:91], v[124:127], v[194:197], v[88:91]
	v_mfma_f32_16x16x32_bf16 v[76:79], v[104:107], v[204:207], v[76:79]
	v_mfma_f32_16x16x32_bf16 v[72:75], v[124:127], v[204:207], v[72:75]
	v_mfma_f32_16x16x32_bf16 v[148:151], v[112:115], v[174:177], v[148:151]
	v_mfma_f32_16x16x32_bf16 v[140:143], v[128:131], v[174:177], v[140:143]
	v_mfma_f32_16x16x32_bf16 v[116:119], v[112:115], v[186:189], v[116:119]
	v_mfma_f32_16x16x32_bf16 v[108:111], v[128:131], v[186:189], v[108:111]
	v_mfma_f32_16x16x32_bf16 v[92:95], v[112:115], v[198:201], v[92:95]
	v_mfma_f32_16x16x32_bf16 v[88:91], v[128:131], v[198:201], v[88:91]
	v_mfma_f32_16x16x32_bf16 v[76:79], v[112:115], v[208:211], v[76:79]
	v_mfma_f32_16x16x32_bf16 v[72:75], v[128:131], v[208:211], v[72:75]
	s_setprio 0
	s_setprio 1
	v_mfma_f32_16x16x32_bf16 v[132:135], v[136:139], v[170:173], v[132:135]
	v_mfma_f32_16x16x32_bf16 v[120:123], v[152:155], v[170:173], v[120:123]
	v_mfma_f32_16x16x32_bf16 v[100:103], v[136:139], v[178:181], v[100:103]
	v_mfma_f32_16x16x32_bf16 v[96:99], v[152:155], v[178:181], v[96:99]
	v_mfma_f32_16x16x32_bf16 v[84:87], v[136:139], v[194:197], v[84:87]
	v_mfma_f32_16x16x32_bf16 v[80:83], v[152:155], v[194:197], v[80:83]
	v_mfma_f32_16x16x32_bf16 v[68:71], v[136:139], v[204:207], v[68:71]
	v_mfma_f32_16x16x32_bf16 v[64:67], v[152:155], v[204:207], v[64:67]
	v_mfma_f32_16x16x32_bf16 v[132:135], v[144:147], v[174:177], v[132:135]
	v_mfma_f32_16x16x32_bf16 v[120:123], v[156:159], v[174:177], v[120:123]
	v_mfma_f32_16x16x32_bf16 v[100:103], v[144:147], v[186:189], v[100:103]
	v_mfma_f32_16x16x32_bf16 v[96:99], v[156:159], v[186:189], v[96:99]
	v_mfma_f32_16x16x32_bf16 v[84:87], v[144:147], v[198:201], v[84:87]
	v_mfma_f32_16x16x32_bf16 v[80:83], v[156:159], v[198:201], v[80:83]
	v_mfma_f32_16x16x32_bf16 v[68:71], v[144:147], v[208:211], v[68:71]
	v_mfma_f32_16x16x32_bf16 v[64:67], v[156:159], v[208:211], v[64:67]
	s_setprio 0
	s_barrier
; #define PG8_STAGE(bufoff, gbase, voff) do { _Pragma("unroll") for (int _i = 0; _i < 2; ++_i) \
;         __builtin_amdgcn_global_load_lds((const unsigned*)((const char*)(gbase) + (voff)[_i]), (LAS unsigned*)(lds + (bufoff) + ldsw + _i * 8192), 16, 0, 0); } while (0)
; #define PG8_LDA(dst, b, h) do { _Pragma("unroll") for (int m = 0; m < 4; ++m) _Pragma("unroll") for (int k = 0; k < 2; ++k) dst[m][k] = *(const LAS bf16x8*)(lds + PG8_SA(b, h) + aoff + m * 2048 + k * 1024); } while (0)
; #define PG8_LDB(dst, b, h) do { _Pragma("unroll") for (int n = 0; n < 2; ++n) _Pragma("unroll") for (int k = 0; k < 2; ++k) dst[n][k] = *(const LAS bf16x8*)(lds + PG8_SB(b, h) + boff + n * 2048 + k * 1024); } while (0)
; #define PG8_MMA(ai, bj, At, Bt) do { __builtin_amdgcn_s_setprio(1); _Pragma("unroll") for (int m = 0; m < 4; ++m) _Pragma("unroll") for (int n = 0; n < 2; ++n) _Pragma("unroll") for (int k = 0; k < 2; ++k) \
;         acc[ai][bj][m][n] = __builtin_amdgcn_mfma_f32_16x16x32_bf16(Bt[n][k], At[m][k], acc[ai][bj][m][n], 0, 0, 0); __builtin_amdgcn_s_setprio(0); } while (0)
; #define PG8_WAIT_V(n) asm volatile("s_waitcnt vmcnt(" #n ")" ::: "memory")
; #define PG8_WAIT_L(n) asm volatile("s_waitcnt lgkmcnt(" #n ")" ::: "memory")
; #define PG8_BAR __builtin_amdgcn_s_barrier()
; #define PG8_SCHED __builtin_amdgcn_sched_barrier(0)
; template <class Epi>
; __device__ __forceinline__ void gemm_phase(LAS unsigned char* lds, const Gemm g, const Sched& S, const Epi& E, const int tid) {
;     ...
;             PG8_LDB(B0, 0, 0); PG8_LDB(B1, 0, 1); PG8_SCHED; PG8_LDA(At, 0, 0); PG8_STAGE(PG8_SA(1, 1), a1 + hA, voffA);
;             PG8_WAIT_V(8); PG8_WAIT_L(0); PG8_BAR; PG8_MMA(0, 0, At, B0); PG8_MMA(0, 1, At, B1); PG8_BAR; PG8_SCHED;
;     ...
;             PG8_LDA(At, 1, 1); PG8_STAGE(PG8_SB(1, 0), b3, voffB); PG8_STAGE(PG8_SB(1, 1), b3 + hB, voffB); PG8_STAGE(PG8_SA(1, 0), a3, voffA);
;             PG8_WAIT_V(8); PG8_WAIT_L(0); PG8_BAR; PG8_MMA(1, 0, At, B0); PG8_MMA(1, 1, At, B1); PG8_BAR; PG8_SCHED;
	s_add_i32 s16, s45, s47
	v_lshl_add_u64 v[190:191], v[190:191], 0, s[94:95]
	s_mov_b32 m0, s16
	ds_read_b128 v[170:173], v185 offset:49152
	ds_read_b128 v[174:177], v185 offset:50176
	ds_read_b128 v[178:181], v185 offset:51200
	ds_read_b128 v[186:189], v185 offset:52224
	ds_read_b128 v[194:197], v185 offset:53248
	ds_read_b128 v[198:201], v185 offset:54272
	ds_read_b128 v[204:207], v185 offset:55296
	ds_read_b128 v[208:211], v185 offset:56320
	global_load_lds_dwordx4 v[190:191], off
	s_add_i32 m0, s16, 0x2000
	s_add_u32 s16, s20, 0x20080
	v_lshl_add_u64 v[190:191], v[212:213], 0, s[94:95]
	s_addc_u32 s17, s21, 0
	s_add_i32 s20, s51, s47
	global_load_lds_dwordx4 v[190:191], off
	v_lshl_add_u64 v[190:191], s[16:17], 0, v[192:193]
	s_mov_b32 m0, s20
	s_nop 0
	global_load_lds_dwordx4 v[190:191], off
	v_lshl_add_u64 v[190:191], s[16:17], 0, v[164:165]
	s_add_i32 m0, s20, 0x2000
	s_nop 0
	global_load_lds_dwordx4 v[190:191], off
	v_lshl_add_u64 v[190:191], v[214:215], 0, s[94:95]
	s_mov_b32 m0, s77
	s_nop 0
	global_load_lds_dwordx4 v[190:191], off
	v_lshl_add_u64 v[190:191], v[216:217], 0, s[94:95]
	s_mov_b32 m0, s78
	s_nop 0
	global_load_lds_dwordx4 v[190:191], off
	s_waitcnt vmcnt(8)
	s_waitcnt lgkmcnt(0)
	s_barrier
	s_setprio 1
	s_waitcnt lgkmcnt(0)
	v_mfma_f32_16x16x32_bf16 v[60:63], v[104:107], v[170:173], v[60:63]
	v_mfma_f32_16x16x32_bf16 v[56:59], v[124:127], v[170:173], v[56:59]
	v_mfma_f32_16x16x32_bf16 v[44:47], v[104:107], v[178:181], v[44:47]
	v_mfma_f32_16x16x32_bf16 v[40:43], v[124:127], v[178:181], v[40:43]
	v_mfma_f32_16x16x32_bf16 v[28:31], v[104:107], v[194:197], v[28:31]
	v_mfma_f32_16x16x32_bf16 v[24:27], v[124:127], v[194:197], v[24:27]
	v_mfma_f32_16x16x32_bf16 v[12:15], v[104:107], v[204:207], v[12:15]
	v_mfma_f32_16x16x32_bf16 v[8:11], v[124:127], v[204:207], v[8:11]
	v_mfma_f32_16x16x32_bf16 v[60:63], v[112:115], v[174:177], v[60:63]
	v_mfma_f32_16x16x32_bf16 v[56:59], v[128:131], v[174:177], v[56:59]
	v_mfma_f32_16x16x32_bf16 v[44:47], v[112:115], v[186:189], v[44:47]
	v_mfma_f32_16x16x32_bf16 v[40:43], v[128:131], v[186:189], v[40:43]
	v_mfma_f32_16x16x32_bf16 v[28:31], v[112:115], v[198:201], v[28:31]
	v_mfma_f32_16x16x32_bf16 v[24:27], v[128:131], v[198:201], v[24:27]
	v_mfma_f32_16x16x32_bf16 v[12:15], v[112:115], v[208:211], v[12:15]
	v_mfma_f32_16x16x32_bf16 v[8:11], v[128:131], v[208:211], v[8:11]
	s_setprio 0
	s_setprio 1
	v_mfma_f32_16x16x32_bf16 v[52:55], v[136:139], v[170:173], v[52:55]
	v_mfma_f32_16x16x32_bf16 v[48:51], v[152:155], v[170:173], v[48:51]
	v_mfma_f32_16x16x32_bf16 v[36:39], v[136:139], v[178:181], v[36:39]
	v_mfma_f32_16x16x32_bf16 v[32:35], v[152:155], v[178:181], v[32:35]
	v_mfma_f32_16x16x32_bf16 v[20:23], v[136:139], v[194:197], v[20:23]
	v_mfma_f32_16x16x32_bf16 v[16:19], v[152:155], v[194:197], v[16:19]
	v_mfma_f32_16x16x32_bf16 v[4:7], v[136:139], v[204:207], v[4:7]
	v_mfma_f32_16x16x32_bf16 v[0:3], v[152:155], v[204:207], v[0:3]
	v_mfma_f32_16x16x32_bf16 v[52:55], v[144:147], v[174:177], v[52:55]
	v_mfma_f32_16x16x32_bf16 v[48:51], v[156:159], v[174:177], v[48:51]
	v_mfma_f32_16x16x32_bf16 v[36:39], v[144:147], v[186:189], v[36:39]
	v_mfma_f32_16x16x32_bf16 v[32:35], v[156:159], v[186:189], v[32:35]
	v_mfma_f32_16x16x32_bf16 v[20:23], v[144:147], v[198:201], v[20:23]
	v_mfma_f32_16x16x32_bf16 v[16:19], v[156:159], v[198:201], v[16:19]
	v_mfma_f32_16x16x32_bf16 v[4:7], v[144:147], v[208:211], v[4:7]
	v_mfma_f32_16x16x32_bf16 v[0:3], v[156:159], v[208:211], v[0:3]
	s_add_i32 s42, s42, 2
	s_add_u32 s13, s13, 0x100
	s_addc_u32 s40, s40, 0
	s_cmp_gt_u32 s42, 5
	s_mov_b64 s[16:17], s[18:19]
	s_setprio 0
	s_barrier
	s_cbranch_scc1 .Lgk_exit_1
.LBB0_994:
	s_add_u32 s18, s16, 0x100
	s_addc_u32 s19, s17, 0
	s_add_i32 s45, 0, 0x10000
	s_cmp_eq_u32 s42, 4
	s_cselect_b32 s23, s7, s19
	s_cselect_b32 s22, s6, s18
	s_cselect_b32 s21, s15, s40
	s_cselect_b32 s20, s14, s13
	s_add_i32 s51, 0, 0x14000
	v_add_u32_e32 v128, s45, v183
	v_add_u32_e32 v156, s51, v183
	ds_read_b128 v[104:107], v128
	ds_read_b128 v[112:115], v128 offset:1024
	ds_read_b128 v[124:127], v128 offset:2048
	ds_read_b128 v[128:131], v128 offset:3072
	ds_read_b128 v[136:139], v156
	ds_read_b128 v[144:147], v156 offset:1024
	ds_read_b128 v[152:155], v156 offset:2048
	ds_read_b128 v[156:159], v156 offset:3072
	v_lshl_add_u64 v[190:191], s[16:17], 0, v[166:167]
	s_add_i32 m0, s73, 0xc000
	ds_read_b128 v[170:173], v185
	ds_read_b128 v[174:177], v185 offset:1024
	ds_read_b128 v[178:181], v185 offset:2048
	ds_read_b128 v[186:189], v185 offset:3072
	ds_read_b128 v[194:197], v185 offset:4096
	ds_read_b128 v[198:201], v185 offset:5120
	ds_read_b128 v[204:207], v185 offset:6144
	ds_read_b128 v[208:211], v185 offset:7168
	global_load_lds_dwordx4 v[190:191], off
	v_lshl_add_u64 v[190:191], s[16:17], 0, v[168:169]
	s_add_i32 m0, s73, 0xe000
	s_nop 0
	global_load_lds_dwordx4 v[190:191], off
	s_waitcnt vmcnt(8)
	s_waitcnt lgkmcnt(0)
	s_barrier
; #define PG8_STAGE(bufoff, gbase, voff) do { _Pragma("unroll") for (int _i = 0; _i < 2; ++_i) \
;         __builtin_amdgcn_global_load_lds((const unsigned*)((const char*)(gbase) + (voff)[_i]), (LAS unsigned*)(lds + (bufoff) + ldsw + _i * 8192), 16, 0, 0); } while (0)
; #define PG8_LDA(dst, b, h) do { _Pragma("unroll") for (int m = 0; m < 4; ++m) _Pragma("unroll") for (int k = 0; k < 2; ++k) dst[m][k] = *(const LAS bf16x8*)(lds + PG8_SA(b, h) + aoff + m * 2048 + k * 1024); } while (0)
; #define PG8_LDB(dst, b, h) do { _Pragma("unroll") for (int n = 0; n < 2; ++n) _Pragma("unroll") for (int k = 0; k < 2; ++k) dst[n][k] = *(const LAS bf16x8*)(lds + PG8_SB(b, h) + boff + n * 2048 + k * 1024); } while (0)
; #define PG8_MMA(ai, bj, At, Bt) do { __builtin_amdgcn_s_setprio(1); _Pragma("unroll") for (int m = 0; m < 4; ++m) _Pragma("unroll") for (int n = 0; n < 2; ++n) _Pragma("unroll") for (int k = 0; k < 2; ++k) \
;         acc[ai][bj][m][n] = __builtin_amdgcn_mfma_f32_16x16x32_bf16(Bt[n][k], At[m][k], acc[ai][bj][m][n], 0, 0, 0); __builtin_amdgcn_s_setprio(0); } while (0)
; #define PG8_WAIT_V(n) asm volatile("s_waitcnt vmcnt(" #n ")" ::: "memory")
; #define PG8_WAIT_L(n) asm volatile("s_waitcnt lgkmcnt(" #n ")" ::: "memory")
; #define PG8_BAR __builtin_amdgcn_s_barrier()
; #define PG8_SCHED __builtin_amdgcn_sched_barrier(0)
; template <class Epi>
; __device__ __forceinline__ void gemm_phase(LAS unsigned char* lds, const Gemm g, const Sched& S, const Epi& E, const int tid) {
;     ...
;             PG8_LDB(B0, 0, 0); PG8_LDB(B1, 0, 1); PG8_SCHED; PG8_LDA(At, 0, 0); PG8_STAGE(PG8_SA(1, 1), a1 + hA, voffA);
;             PG8_WAIT_V(8); PG8_WAIT_L(0); PG8_BAR; PG8_MMA(0, 0, At, B0); PG8_MMA(0, 1, At, B1); PG8_BAR; PG8_SCHED;
;             PG8_LDA(At, 0, 1); PG8_STAGE(PG8_SB(0, 0), b2, voffB); PG8_STAGE(PG8_SB(0, 1), b2 + hB, voffB); PG8_STAGE(PG8_SA(0, 0), a2, voffA);
;             PG8_WAIT_V(8); PG8_WAIT_L(0); PG8_BAR; PG8_MMA(1, 0, At, B0); PG8_MMA(1, 1, At, B1); PG8_BAR; PG8_SCHED;
;             PG8_LDB(B0, 1, 0); PG8_LDB(B1, 1, 1); PG8_SCHED; PG8_LDA(At, 1, 0); PG8_STAGE(PG8_SA(0, 1), a2 + hA, voffA);
;             PG8_WAIT_V(8); PG8_WAIT_L(0); PG8_BAR; PG8_MMA(0, 0, At, B0); PG8_MMA(0, 1, At, B1); PG8_BAR; PG8_SCHED;
	s_setprio 1
	s_waitcnt lgkmcnt(0)
	v_mfma_f32_16x16x32_bf16 v[148:151], v[104:107], v[170:173], v[148:151]
	v_mfma_f32_16x16x32_bf16 v[140:143], v[124:127], v[170:173], v[140:143]
	v_mfma_f32_16x16x32_bf16 v[116:119], v[104:107], v[178:181], v[116:119]
	v_mfma_f32_16x16x32_bf16 v[108:111], v[124:127], v[178:181], v[108:111]
	v_mfma_f32_16x16x32_bf16 v[92:95], v[104:107], v[194:197], v[92:95]
	v_mfma_f32_16x16x32_bf16 v[88:91], v[124:127], v[194:197], v[88:91]
	v_mfma_f32_16x16x32_bf16 v[76:79], v[104:107], v[204:207], v[76:79]
	v_mfma_f32_16x16x32_bf16 v[72:75], v[124:127], v[204:207], v[72:75]
	v_mfma_f32_16x16x32_bf16 v[148:151], v[112:115], v[174:177], v[148:151]
	v_mfma_f32_16x16x32_bf16 v[140:143], v[128:131], v[174:177], v[140:143]
	v_mfma_f32_16x16x32_bf16 v[116:119], v[112:115], v[186:189], v[116:119]
	v_mfma_f32_16x16x32_bf16 v[108:111], v[128:131], v[186:189], v[108:111]
	v_mfma_f32_16x16x32_bf16 v[92:95], v[112:115], v[198:201], v[92:95]
	v_mfma_f32_16x16x32_bf16 v[88:91], v[128:131], v[198:201], v[88:91]
	v_mfma_f32_16x16x32_bf16 v[76:79], v[112:115], v[208:211], v[76:79]
	v_mfma_f32_16x16x32_bf16 v[72:75], v[128:131], v[208:211], v[72:75]
	s_setprio 0
	s_setprio 1
	v_mfma_f32_16x16x32_bf16 v[132:135], v[136:139], v[170:173], v[132:135]
	v_mfma_f32_16x16x32_bf16 v[120:123], v[152:155], v[170:173], v[120:123]
	v_mfma_f32_16x16x32_bf16 v[100:103], v[136:139], v[178:181], v[100:103]
	v_mfma_f32_16x16x32_bf16 v[96:99], v[152:155], v[178:181], v[96:99]
	v_mfma_f32_16x16x32_bf16 v[84:87], v[136:139], v[194:197], v[84:87]
	v_mfma_f32_16x16x32_bf16 v[80:83], v[152:155], v[194:197], v[80:83]
	v_mfma_f32_16x16x32_bf16 v[68:71], v[136:139], v[204:207], v[68:71]
	v_mfma_f32_16x16x32_bf16 v[64:67], v[152:155], v[204:207], v[64:67]
	v_mfma_f32_16x16x32_bf16 v[132:135], v[144:147], v[174:177], v[132:135]
	v_mfma_f32_16x16x32_bf16 v[120:123], v[156:159], v[174:177], v[120:123]
	v_mfma_f32_16x16x32_bf16 v[100:103], v[144:147], v[186:189], v[100:103]
	v_mfma_f32_16x16x32_bf16 v[96:99], v[156:159], v[186:189], v[96:99]
	v_mfma_f32_16x16x32_bf16 v[84:87], v[144:147], v[198:201], v[84:87]
	v_mfma_f32_16x16x32_bf16 v[80:83], v[156:159], v[198:201], v[80:83]
	v_mfma_f32_16x16x32_bf16 v[68:71], v[144:147], v[208:211], v[68:71]
	v_mfma_f32_16x16x32_bf16 v[64:67], v[156:159], v[208:211], v[64:67]
	s_setprio 0
	s_barrier
	s_add_i32 s16, s45, s47
	v_lshl_add_u64 v[190:191], s[20:21], 0, v[192:193]
	s_mov_b32 m0, s16
	ds_read_b128 v[170:173], v185 offset:16384
	ds_read_b128 v[174:177], v185 offset:17408
	ds_read_b128 v[178:181], v185 offset:18432
	ds_read_b128 v[186:189], v185 offset:19456
	ds_read_b128 v[194:197], v185 offset:20480
	ds_read_b128 v[198:201], v185 offset:21504
	ds_read_b128 v[204:207], v185 offset:22528
	ds_read_b128 v[208:211], v185 offset:23552
	global_load_lds_dwordx4 v[190:191], off
	s_add_i32 m0, s16, 0x2000
	s_add_u32 s16, s20, 0x20000
	v_lshl_add_u64 v[212:213], s[20:21], 0, v[164:165]
	s_addc_u32 s17, s21, 0
	s_add_i32 s45, s51, s47
	global_load_lds_dwordx4 v[212:213], off
	v_lshl_add_u64 v[214:215], s[16:17], 0, v[192:193]
	s_mov_b32 m0, s45
	v_lshl_add_u64 v[216:217], s[22:23], 0, v[162:163]
	global_load_lds_dwordx4 v[214:215], off
	v_lshl_add_u64 v[214:215], s[16:17], 0, v[164:165]
	s_add_i32 m0, s45, 0x2000
	s_nop 0
	global_load_lds_dwordx4 v[214:215], off
	v_lshl_add_u64 v[214:215], s[22:23], 0, v[160:161]
	s_mov_b32 m0, s73
	s_nop 0
	global_load_lds_dwordx4 v[214:215], off
	s_mov_b32 m0, s74
	s_nop 0
	global_load_lds_dwordx4 v[216:217], off
	s_waitcnt vmcnt(8)
	s_waitcnt lgkmcnt(0)
	s_barrier
	s_setprio 1
	s_waitcnt lgkmcnt(0)
	v_mfma_f32_16x16x32_bf16 v[60:63], v[104:107], v[170:173], v[60:63]
	v_mfma_f32_16x16x32_bf16 v[56:59], v[124:127], v[170:173], v[56:59]
	v_mfma_f32_16x16x32_bf16 v[44:47], v[104:107], v[178:181], v[44:47]
	v_mfma_f32_16x16x32_bf16 v[40:43], v[124:127], v[178:181], v[40:43]
	v_mfma_f32_16x16x32_bf16 v[28:31], v[104:107], v[194:197], v[28:31]
	v_mfma_f32_16x16x32_bf16 v[24:27], v[124:127], v[194:197], v[24:27]
	v_mfma_f32_16x16x32_bf16 v[12:15], v[104:107], v[204:207], v[12:15]
	v_mfma_f32_16x16x32_bf16 v[8:11], v[124:127], v[204:207], v[8:11]
	v_mfma_f32_16x16x32_bf16 v[60:63], v[112:115], v[174:177], v[60:63]
	v_mfma_f32_16x16x32_bf16 v[56:59], v[128:131], v[174:177], v[56:59]
	v_mfma_f32_16x16x32_bf16 v[44:47], v[112:115], v[186:189], v[44:47]
	v_mfma_f32_16x16x32_bf16 v[40:43], v[128:131], v[186:189], v[40:43]
	v_mfma_f32_16x16x32_bf16 v[28:31], v[112:115], v[198:201], v[28:31]
	v_mfma_f32_16x16x32_bf16 v[24:27], v[128:131], v[198:201], v[24:27]
	v_mfma_f32_16x16x32_bf16 v[12:15], v[112:115], v[208:211], v[12:15]
	v_mfma_f32_16x16x32_bf16 v[8:11], v[128:131], v[208:211], v[8:11]
	s_setprio 0
	s_setprio 1
	v_mfma_f32_16x16x32_bf16 v[52:55], v[136:139], v[170:173], v[52:55]
	v_mfma_f32_16x16x32_bf16 v[48:51], v[152:155], v[170:173], v[48:51]
	v_mfma_f32_16x16x32_bf16 v[36:39], v[136:139], v[178:181], v[36:39]
	v_mfma_f32_16x16x32_bf16 v[32:35], v[152:155], v[178:181], v[32:35]
	v_mfma_f32_16x16x32_bf16 v[20:23], v[136:139], v[194:197], v[20:23]
	v_mfma_f32_16x16x32_bf16 v[16:19], v[152:155], v[194:197], v[16:19]
	v_mfma_f32_16x16x32_bf16 v[4:7], v[136:139], v[204:207], v[4:7]
	v_mfma_f32_16x16x32_bf16 v[0:3], v[152:155], v[204:207], v[0:3]
	v_mfma_f32_16x16x32_bf16 v[52:55], v[144:147], v[174:177], v[52:55]
	v_mfma_f32_16x16x32_bf16 v[48:51], v[156:159], v[174:177], v[48:51]
	v_mfma_f32_16x16x32_bf16 v[36:39], v[144:147], v[186:189], v[36:39]
	v_mfma_f32_16x16x32_bf16 v[32:35], v[156:159], v[186:189], v[32:35]
	v_mfma_f32_16x16x32_bf16 v[20:23], v[144:147], v[198:201], v[20:23]
	v_mfma_f32_16x16x32_bf16 v[16:19], v[156:159], v[198:201], v[16:19]
	v_mfma_f32_16x16x32_bf16 v[4:7], v[144:147], v[208:211], v[4:7]
	v_mfma_f32_16x16x32_bf16 v[0:3], v[156:159], v[208:211], v[0:3]
	s_setprio 0
	s_barrier
; #define PG8_STAGE(bufoff, gbase, voff) do { _Pragma("unroll") for (int _i = 0; _i < 2; ++_i) \
;         __builtin_amdgcn_global_load_lds((const unsigned*)((const char*)(gbase) + (voff)[_i]), (LAS unsigned*)(lds + (bufoff) + ldsw + _i * 8192), 16, 0, 0); } while (0)
; #define PG8_LDA(dst, b, h) do { _Pragma("unroll") for (int m = 0; m < 4; ++m) _Pragma("unroll") for (int k = 0; k < 2; ++k) dst[m][k] = *(const LAS bf16x8*)(lds + PG8_SA(b, h) + aoff + m * 2048 + k * 1024); } while (0)
; #define PG8_LDB(dst, b, h) do { _Pragma("unroll") for (int n = 0; n < 2; ++n) _Pragma("unroll") for (int k = 0; k < 2; ++k) dst[n][k] = *(const LAS bf16x8*)(lds + PG8_SB(b, h) + boff + n * 2048 + k * 1024); } while (0)
; #define PG8_MMA(ai, bj, At, Bt) do { __builtin_amdgcn_s_setprio(1); _Pragma("unroll") for (int m = 0; m < 4; ++m) _Pragma("unroll") for (int n = 0; n < 2; ++n) _Pragma("unroll") for (int k = 0; k < 2; ++k) \
;         acc[ai][bj][m][n] = __builtin_amdgcn_mfma_f32_16x16x32_bf16(Bt[n][k], At[m][k], acc[ai][bj][m][n], 0, 0, 0); __builtin_amdgcn_s_setprio(0); } while (0)
; #define PG8_WAIT_V(n) asm volatile("s_waitcnt vmcnt(" #n ")" ::: "memory")
; #define PG8_WAIT_L(n) asm volatile("s_waitcnt lgkmcnt(" #n ")" ::: "memory")
; #define PG8_BAR __builtin_amdgcn_s_barrier()
; #define PG8_SCHED __builtin_amdgcn_sched_barrier(0)
; template <class Epi>
; __device__ __forceinline__ void gemm_phase(LAS unsigned char* lds, const Gemm g, const Sched& S, const Epi& E, const int tid) {
;     ...
;             PG8_LDB(B0, 1, 0); PG8_LDB(B1, 1, 1); PG8_SCHED; PG8_LDA(At, 1, 0); PG8_STAGE(PG8_SA(0, 1), a2 + hA, voffA);
;             PG8_WAIT_V(8); PG8_WAIT_L(0); PG8_BAR; PG8_MMA(0, 0, At, B0); PG8_MMA(0, 1, At, B1); PG8_BAR; PG8_SCHED;
	s_add_i32 s45, 0, 0x18000
	s_add_i32 s51, 0, 0x1c000
	v_add_u32_e32 v128, s45, v183
	v_add_u32_e32 v156, s51, v183
	ds_read_b128 v[104:107], v128
	ds_read_b128 v[112:115], v128 offset:1024
	ds_read_b128 v[124:127], v128 offset:2048
	ds_read_b128 v[128:131], v128 offset:3072
	ds_read_b128 v[136:139], v156
	ds_read_b128 v[144:147], v156 offset:1024
	ds_read_b128 v[152:155], v156 offset:2048
	ds_read_b128 v[156:159], v156 offset:3072
	s_add_u32 s16, s22, 0x120000
	s_addc_u32 s17, s23, 0
	s_mov_b32 m0, s75
	v_lshl_add_u64 v[218:219], s[16:17], 0, v[160:161]
	ds_read_b128 v[170:173], v185 offset:32768
	ds_read_b128 v[174:177], v185 offset:33792
	ds_read_b128 v[178:181], v185 offset:34816
	ds_read_b128 v[186:189], v185 offset:35840
	ds_read_b128 v[194:197], v185 offset:36864
	ds_read_b128 v[198:201], v185 offset:37888
	ds_read_b128 v[204:207], v185 offset:38912
	ds_read_b128 v[208:211], v185 offset:39936
	global_load_lds_dwordx4 v[218:219], off
	v_lshl_add_u64 v[218:219], s[16:17], 0, v[162:163]
	s_mov_b32 m0, s76
	s_nop 0
	global_load_lds_dwordx4 v[218:219], off
	s_waitcnt vmcnt(8)
	s_waitcnt lgkmcnt(0)
	s_barrier
	s_setprio 1
	s_waitcnt lgkmcnt(0)
	v_mfma_f32_16x16x32_bf16 v[148:151], v[104:107], v[170:173], v[148:151]
	v_mfma_f32_16x16x32_bf16 v[140:143], v[124:127], v[170:173], v[140:143]
	v_mfma_f32_16x16x32_bf16 v[116:119], v[104:107], v[178:181], v[116:119]
	v_mfma_f32_16x16x32_bf16 v[108:111], v[124:127], v[178:181], v[108:111]
	v_mfma_f32_16x16x32_bf16 v[92:95], v[104:107], v[194:197], v[92:95]
	v_mfma_f32_16x16x32_bf16 v[88:91], v[124:127], v[194:197], v[88:91]
	v_mfma_f32_16x16x32_bf16 v[76:79], v[104:107], v[204:207], v[76:79]
	v_mfma_f32_16x16x32_bf16 v[72:75], v[124:127], v[204:207], v[72:75]
	v_mfma_f32_16x16x32_bf16 v[148:151], v[112:115], v[174:177], v[148:151]
	v_mfma_f32_16x16x32_bf16 v[140:143], v[128:131], v[174:177], v[140:143]
	v_mfma_f32_16x16x32_bf16 v[116:119], v[112:115], v[186:189], v[116:119]
	v_mfma_f32_16x16x32_bf16 v[108:111], v[128:131], v[186:189], v[108:111]
	v_mfma_f32_16x16x32_bf16 v[92:95], v[112:115], v[198:201], v[92:95]
	v_mfma_f32_16x16x32_bf16 v[88:91], v[128:131], v[198:201], v[88:91]
	v_mfma_f32_16x16x32_bf16 v[76:79], v[112:115], v[208:211], v[76:79]
	v_mfma_f32_16x16x32_bf16 v[72:75], v[128:131], v[208:211], v[72:75]
	s_setprio 0
	s_setprio 1
	v_mfma_f32_16x16x32_bf16 v[132:135], v[136:139], v[170:173], v[132:135]
	v_mfma_f32_16x16x32_bf16 v[120:123], v[152:155], v[170:173], v[120:123]
	v_mfma_f32_16x16x32_bf16 v[100:103], v[136:139], v[178:181], v[100:103]
	v_mfma_f32_16x16x32_bf16 v[96:99], v[152:155], v[178:181], v[96:99]
	v_mfma_f32_16x16x32_bf16 v[84:87], v[136:139], v[194:197], v[84:87]
	v_mfma_f32_16x16x32_bf16 v[80:83], v[152:155], v[194:197], v[80:83]
	v_mfma_f32_16x16x32_bf16 v[68:71], v[136:139], v[204:207], v[68:71]
	v_mfma_f32_16x16x32_bf16 v[64:67], v[152:155], v[204:207], v[64:67]
	v_mfma_f32_16x16x32_bf16 v[132:135], v[144:147], v[174:177], v[132:135]
	v_mfma_f32_16x16x32_bf16 v[120:123], v[156:159], v[174:177], v[120:123]
	v_mfma_f32_16x16x32_bf16 v[100:103], v[144:147], v[186:189], v[100:103]
	v_mfma_f32_16x16x32_bf16 v[96:99], v[156:159], v[186:189], v[96:99]
	v_mfma_f32_16x16x32_bf16 v[84:87], v[144:147], v[198:201], v[84:87]
	v_mfma_f32_16x16x32_bf16 v[80:83], v[156:159], v[198:201], v[80:83]
	v_mfma_f32_16x16x32_bf16 v[68:71], v[144:147], v[208:211], v[68:71]
	v_mfma_f32_16x16x32_bf16 v[64:67], v[156:159], v[208:211], v[64:67]
	s_setprio 0
	s_barrier
; #define PG8_STAGE(bufoff, gbase, voff) do { _Pragma("unroll") for (int _i = 0; _i < 2; ++_i) \
;         __builtin_amdgcn_global_load_lds((const unsigned*)((const char*)(gbase) + (voff)[_i]), (LAS unsigned*)(lds + (bufoff) + ldsw + _i * 8192), 16, 0, 0); } while (0)
; #define PG8_LDA(dst, b, h) do { _Pragma("unroll") for (int m = 0; m < 4; ++m) _Pragma("unroll") for (int k = 0; k < 2; ++k) dst[m][k] = *(const LAS bf16x8*)(lds + PG8_SA(b, h) + aoff + m * 2048 + k * 1024); } while (0)
; #define PG8_MMA(ai, bj, At, Bt) do { __builtin_amdgcn_s_setprio(1); _Pragma("unroll") for (int m = 0; m < 4; ++m) _Pragma("unroll") for (int n = 0; n < 2; ++n) _Pragma("unroll") for (int k = 0; k < 2; ++k) \
;         acc[ai][bj][m][n] = __builtin_amdgcn_mfma_f32_16x16x32_bf16(Bt[n][k], At[m][k], acc[ai][bj][m][n], 0, 0, 0); __builtin_amdgcn_s_setprio(0); } while (0)
; #define PG8_WAIT_V(n) asm volatile("s_waitcnt vmcnt(" #n ")" ::: "memory")
; #define PG8_WAIT_L(n) asm volatile("s_waitcnt lgkmcnt(" #n ")" ::: "memory")
; #define PG8_BAR __builtin_amdgcn_s_barrier()
; #define PG8_SCHED __builtin_amdgcn_sched_barrier(0)
; template <class Epi>
; __device__ __forceinline__ void gemm_phase(LAS unsigned char* lds, const Gemm g, const Sched& S, const Epi& E, const int tid) {
;     ...
;             PG8_LDA(At, 1, 1); PG8_STAGE(PG8_SB(1, 0), b3, voffB); PG8_STAGE(PG8_SB(1, 1), b3 + hB, voffB); PG8_STAGE(PG8_SA(1, 0), a3, voffA);
;             PG8_WAIT_V(8); PG8_WAIT_L(0); PG8_BAR; PG8_MMA(1, 0, At, B0); PG8_MMA(1, 1, At, B1); PG8_BAR; PG8_SCHED;
	s_add_i32 s16, s45, s47
	v_lshl_add_u64 v[190:191], v[190:191], 0, s[94:95]
	s_mov_b32 m0, s16
	ds_read_b128 v[170:173], v185 offset:49152
	ds_read_b128 v[174:177], v185 offset:50176
	ds_read_b128 v[178:181], v185 offset:51200
	ds_read_b128 v[186:189], v185 offset:52224
	ds_read_b128 v[194:197], v185 offset:53248
	ds_read_b128 v[198:201], v185 offset:54272
	ds_read_b128 v[204:207], v185 offset:55296
	ds_read_b128 v[208:211], v185 offset:56320
	global_load_lds_dwordx4 v[190:191], off
	s_add_i32 m0, s16, 0x2000
	s_add_u32 s16, s20, 0x20080
	v_lshl_add_u64 v[190:191], v[212:213], 0, s[94:95]
	s_addc_u32 s17, s21, 0
	s_add_i32 s20, s51, s47
	global_load_lds_dwordx4 v[190:191], off
	v_lshl_add_u64 v[190:191], s[16:17], 0, v[192:193]
	s_mov_b32 m0, s20
	s_nop 0
	global_load_lds_dwordx4 v[190:191], off
	v_lshl_add_u64 v[190:191], s[16:17], 0, v[164:165]
	s_add_i32 m0, s20, 0x2000
	s_nop 0
	global_load_lds_dwordx4 v[190:191], off
	v_lshl_add_u64 v[190:191], v[214:215], 0, s[94:95]
	s_mov_b32 m0, s77
	s_nop 0
	global_load_lds_dwordx4 v[190:191], off
	v_lshl_add_u64 v[190:191], v[216:217], 0, s[94:95]
	s_mov_b32 m0, s78
	s_nop 0
	global_load_lds_dwordx4 v[190:191], off
	s_waitcnt vmcnt(8)
	s_waitcnt lgkmcnt(0)
	s_barrier
	s_setprio 1
	s_waitcnt lgkmcnt(0)
	v_mfma_f32_16x16x32_bf16 v[60:63], v[104:107], v[170:173], v[60:63]
	v_mfma_f32_16x16x32_bf16 v[56:59], v[124:127], v[170:173], v[56:59]
	v_mfma_f32_16x16x32_bf16 v[44:47], v[104:107], v[178:181], v[44:47]
	v_mfma_f32_16x16x32_bf16 v[40:43], v[124:127], v[178:181], v[40:43]
	v_mfma_f32_16x16x32_bf16 v[28:31], v[104:107], v[194:197], v[28:31]
	v_mfma_f32_16x16x32_bf16 v[24:27], v[124:127], v[194:197], v[24:27]
	v_mfma_f32_16x16x32_bf16 v[12:15], v[104:107], v[204:207], v[12:15]
	v_mfma_f32_16x16x32_bf16 v[8:11], v[124:127], v[204:207], v[8:11]
	v_mfma_f32_16x16x32_bf16 v[60:63], v[112:115], v[174:177], v[60:63]
	v_mfma_f32_16x16x32_bf16 v[56:59], v[128:131], v[174:177], v[56:59]
	v_mfma_f32_16x16x32_bf16 v[44:47], v[112:115], v[186:189], v[44:47]
	v_mfma_f32_16x16x32_bf16 v[40:43], v[128:131], v[186:189], v[40:43]
	v_mfma_f32_16x16x32_bf16 v[28:31], v[112:115], v[198:201], v[28:31]
	v_mfma_f32_16x16x32_bf16 v[24:27], v[128:131], v[198:201], v[24:27]
	v_mfma_f32_16x16x32_bf16 v[12:15], v[112:115], v[208:211], v[12:15]
	v_mfma_f32_16x16x32_bf16 v[8:11], v[128:131], v[208:211], v[8:11]
	s_setprio 0
	s_setprio 1
	v_mfma_f32_16x16x32_bf16 v[52:55], v[136:139], v[170:173], v[52:55]
	v_mfma_f32_16x16x32_bf16 v[48:51], v[152:155], v[170:173], v[48:51]
	v_mfma_f32_16x16x32_bf16 v[36:39], v[136:139], v[178:181], v[36:39]
	v_mfma_f32_16x16x32_bf16 v[32:35], v[152:155], v[178:181], v[32:35]
	v_mfma_f32_16x16x32_bf16 v[20:23], v[136:139], v[194:197], v[20:23]
	v_mfma_f32_16x16x32_bf16 v[16:19], v[152:155], v[194:197], v[16:19]
	v_mfma_f32_16x16x32_bf16 v[4:7], v[136:139], v[204:207], v[4:7]
	v_mfma_f32_16x16x32_bf16 v[0:3], v[152:155], v[204:207], v[0:3]
	v_mfma_f32_16x16x32_bf16 v[52:55], v[144:147], v[174:177], v[52:55]
	v_mfma_f32_16x16x32_bf16 v[48:51], v[156:159], v[174:177], v[48:51]
	v_mfma_f32_16x16x32_bf16 v[36:39], v[144:147], v[186:189], v[36:39]
	v_mfma_f32_16x16x32_bf16 v[32:35], v[156:159], v[186:189], v[32:35]
	v_mfma_f32_16x16x32_bf16 v[20:23], v[144:147], v[198:201], v[20:23]
	v_mfma_f32_16x16x32_bf16 v[16:19], v[156:159], v[198:201], v[16:19]
	v_mfma_f32_16x16x32_bf16 v[4:7], v[144:147], v[208:211], v[4:7]
	v_mfma_f32_16x16x32_bf16 v[0:3], v[156:159], v[208:211], v[0:3]
	s_add_i32 s42, s42, 2
	s_add_u32 s13, s13, 0x100
	s_addc_u32 s40, s40, 0
	s_cmp_gt_u32 s42, 5
	s_mov_b64 s[16:17], s[18:19]
	s_setprio 0
	s_barrier
	s_cbranch_scc0 .LBB0_994

; #define PG8_STAGE(bufoff, gbase, voff) do { _Pragma("unroll") for (int _i = 0; _i < 2; ++_i) \
;         __builtin_amdgcn_global_load_lds((const unsigned*)((const char*)(gbase) + (voff)[_i]), (LAS unsigned*)(lds + (bufoff) + ldsw + _i * 8192), 16, 0, 0); } while (0)
; #define PG8_LDA(dst, b, h) do { _Pragma("unroll") for (int m = 0; m < 4; ++m) _Pragma("unroll") for (int k = 0; k < 2; ++k) dst[m][k] = *(const LAS bf16x8*)(lds + PG8_SA(b, h) + aoff + m * 2048 + k * 1024); } while (0)
; #define PG8_LDB(dst, b, h) do { _Pragma("unroll") for (int n = 0; n < 2; ++n) _Pragma("unroll") for (int k = 0; k < 2; ++k) dst[n][k] = *(const LAS bf16x8*)(lds + PG8_SB(b, h) + boff + n * 2048 + k * 1024); } while (0)
; #define PG8_MMA(ai, bj, At, Bt) do { __builtin_amdgcn_s_setprio(1); _Pragma("unroll") for (int m = 0; m < 4; ++m) _Pragma("unroll") for (int n = 0; n < 2; ++n) _Pragma("unroll") for (int k = 0; k < 2; ++k) \
;         acc[ai][bj][m][n] = __builtin_amdgcn_mfma_f32_16x16x32_bf16(Bt[n][k], At[m][k], acc[ai][bj][m][n], 0, 0, 0); __builtin_amdgcn_s_setprio(0); } while (0)
; #define PG8_BAR __builtin_amdgcn_s_barrier()
; template <class Epi>
; __device__ __forceinline__ void gemm_phase(LAS unsigned char* lds, const Gemm g, const Sched& S, const Epi& E, const int tid) {
;     ...
;         for (int t = 0; t < nt; t += 2) {
;             const bool last = (t == nt - 2);
;             const char* a1 = cA + (size_t)(t + 1) * kstep;
;             const char* a2 = last ? nA : cA + (size_t)(t + 2) * kstep; const char* b2 = last ? nB : cB + (size_t)(t + 2) * kstep;
;             const char* a3 = a2 + kstep; const char* b3 = b2 + kstep;
;             PG8_LDB(B0, 0, 0); PG8_LDB(B1, 0, 1); PG8_SCHED; PG8_LDA(At, 0, 0); PG8_STAGE(PG8_SA(1, 1), a1 + hA, voffA);
;             PG8_WAIT_V(8); PG8_WAIT_L(0); PG8_BAR; PG8_MMA(0, 0, At, B0); PG8_MMA(0, 1, At, B1); PG8_BAR; PG8_SCHED;
;             PG8_LDA(At, 0, 1); PG8_STAGE(PG8_SB(0, 0), b2, voffB); PG8_STAGE(PG8_SB(0, 1), b2 + hB, voffB); PG8_STAGE(PG8_SA(0, 0), a2, voffA);
;             PG8_WAIT_V(8); PG8_WAIT_L(0); PG8_BAR; PG8_MMA(1, 0, At, B0); PG8_MMA(1, 1, At, B1); PG8_BAR; PG8_SCHED;
;             PG8_LDB(B0, 1, 0); PG8_LDB(B1, 1, 1); PG8_SCHED; PG8_LDA(At, 1, 0); PG8_STAGE(PG8_SA(0, 1), a2 + hA, voffA);
;             PG8_WAIT_V(8); PG8_WAIT_L(0); PG8_BAR; PG8_MMA(0, 0, At, B0); PG8_MMA(0, 1, At, B1); PG8_BAR; PG8_SCHED;
.LBB0_1028:
	s_add_u32 s13, s22, 0x100
	s_addc_u32 s37, s23, 0
	s_mov_b32 s40, -2
	s_add_u32 s6, s20, 0x100
	s_addc_u32 s7, s21, 0
	s_add_i32 s42, 0, 0x10000
	s_cmp_eq_u32 s40, 4
	s_cselect_b32 s73, s15, s7
	s_cselect_b32 s72, s14, s6
	s_cselect_b32 s23, s17, s37
	s_cselect_b32 s22, s16, s13
	s_add_i32 s45, 0, 0x14000
	v_add_u32_e32 v128, s42, v241
	v_add_u32_e32 v156, s45, v241
	ds_read_b128 v[104:107], v128
	ds_read_b128 v[112:115], v128 offset:1024
	ds_read_b128 v[120:123], v128 offset:2048
	ds_read_b128 v[128:131], v128 offset:3072
	ds_read_b128 v[136:139], v156
	ds_read_b128 v[140:143], v156 offset:1024
	ds_read_b128 v[148:151], v156 offset:2048
	ds_read_b128 v[156:159], v156 offset:3072
	v_lshl_add_u64 v[194:195], s[20:21], 0, v[210:211]
	s_add_i32 m0, s19, 0xc000
	ds_read_b128 v[160:163], v243
	ds_read_b128 v[164:167], v243 offset:1024
	ds_read_b128 v[168:171], v243 offset:2048
	ds_read_b128 v[172:175], v243 offset:3072
	ds_read_b128 v[176:179], v243 offset:4096
	ds_read_b128 v[180:183], v243 offset:5120
	ds_read_b128 v[184:187], v243 offset:6144
	ds_read_b128 v[188:191], v243 offset:7168
	global_load_lds_dwordx4 v[194:195], off
	v_lshl_add_u64 v[194:195], s[20:21], 0, v[212:213]
	s_add_i32 m0, s19, 0xe000
	s_nop 0
	global_load_lds_dwordx4 v[194:195], off
	s_waitcnt vmcnt(8)
	s_waitcnt lgkmcnt(0)
	s_barrier
	s_setprio 1
	s_waitcnt lgkmcnt(0)
	v_mfma_f32_16x16x32_bf16 v[152:155], v[104:107], v[160:163], 0
	v_mfma_f32_16x16x32_bf16 v[144:147], v[120:123], v[160:163], 0
	v_mfma_f32_16x16x32_bf16 v[116:119], v[104:107], v[168:171], 0
	v_mfma_f32_16x16x32_bf16 v[108:111], v[120:123], v[168:171], 0
	v_mfma_f32_16x16x32_bf16 v[92:95], v[104:107], v[176:179], 0
	v_mfma_f32_16x16x32_bf16 v[88:91], v[120:123], v[176:179], 0
	v_mfma_f32_16x16x32_bf16 v[76:79], v[104:107], v[184:187], 0
	v_mfma_f32_16x16x32_bf16 v[72:75], v[120:123], v[184:187], 0
	v_mfma_f32_16x16x32_bf16 v[152:155], v[112:115], v[164:167], v[152:155]
	v_mfma_f32_16x16x32_bf16 v[144:147], v[128:131], v[164:167], v[144:147]
	v_mfma_f32_16x16x32_bf16 v[116:119], v[112:115], v[172:175], v[116:119]
	v_mfma_f32_16x16x32_bf16 v[108:111], v[128:131], v[172:175], v[108:111]
	v_mfma_f32_16x16x32_bf16 v[92:95], v[112:115], v[180:183], v[92:95]
	v_mfma_f32_16x16x32_bf16 v[88:91], v[128:131], v[180:183], v[88:91]
	v_mfma_f32_16x16x32_bf16 v[76:79], v[112:115], v[188:191], v[76:79]
	v_mfma_f32_16x16x32_bf16 v[72:75], v[128:131], v[188:191], v[72:75]
	s_setprio 0
	s_setprio 1
	v_mfma_f32_16x16x32_bf16 v[132:135], v[136:139], v[160:163], 0
	v_mfma_f32_16x16x32_bf16 v[124:127], v[148:151], v[160:163], 0
	v_mfma_f32_16x16x32_bf16 v[100:103], v[136:139], v[168:171], 0
	v_mfma_f32_16x16x32_bf16 v[96:99], v[148:151], v[168:171], 0
	v_mfma_f32_16x16x32_bf16 v[84:87], v[136:139], v[176:179], 0
	v_mfma_f32_16x16x32_bf16 v[80:83], v[148:151], v[176:179], 0
	v_mfma_f32_16x16x32_bf16 v[68:71], v[136:139], v[184:187], 0
	v_mfma_f32_16x16x32_bf16 v[64:67], v[148:151], v[184:187], 0
	v_mfma_f32_16x16x32_bf16 v[132:135], v[140:143], v[164:167], v[132:135]
	v_mfma_f32_16x16x32_bf16 v[124:127], v[156:159], v[164:167], v[124:127]
	v_mfma_f32_16x16x32_bf16 v[100:103], v[140:143], v[172:175], v[100:103]
	v_mfma_f32_16x16x32_bf16 v[96:99], v[156:159], v[172:175], v[96:99]
	v_mfma_f32_16x16x32_bf16 v[84:87], v[140:143], v[180:183], v[84:87]
	v_mfma_f32_16x16x32_bf16 v[80:83], v[156:159], v[180:183], v[80:83]
	v_mfma_f32_16x16x32_bf16 v[68:71], v[140:143], v[188:191], v[68:71]
	v_mfma_f32_16x16x32_bf16 v[64:67], v[156:159], v[188:191], v[64:67]
	s_setprio 0
	s_barrier
	s_add_i32 s20, s42, s35
	v_lshl_add_u64 v[194:195], s[22:23], 0, v[192:193]
	s_mov_b32 m0, s20
	ds_read_b128 v[160:163], v243 offset:16384
	ds_read_b128 v[164:167], v243 offset:17408
	ds_read_b128 v[168:171], v243 offset:18432
	ds_read_b128 v[172:175], v243 offset:19456
	ds_read_b128 v[176:179], v243 offset:20480
	ds_read_b128 v[180:183], v243 offset:21504
	ds_read_b128 v[184:187], v243 offset:22528
	ds_read_b128 v[188:191], v243 offset:23552
	global_load_lds_dwordx4 v[194:195], off
	s_add_i32 m0, s20, 0x2000
	s_add_u32 s20, s22, 0x20000
	v_lshl_add_u64 v[196:197], s[22:23], 0, v[208:209]
	s_addc_u32 s21, s23, 0
	s_add_i32 s42, s45, s35
	global_load_lds_dwordx4 v[196:197], off
	v_lshl_add_u64 v[198:199], s[20:21], 0, v[192:193]
	s_mov_b32 m0, s42
	v_lshl_add_u64 v[200:201], s[72:73], 0, v[206:207]
	global_load_lds_dwordx4 v[198:199], off
	v_lshl_add_u64 v[198:199], s[20:21], 0, v[208:209]
	s_add_i32 m0, s42, 0x2000
	s_nop 0
	global_load_lds_dwordx4 v[198:199], off
	v_lshl_add_u64 v[198:199], s[72:73], 0, v[204:205]
	s_mov_b32 m0, s19
	s_nop 0
	global_load_lds_dwordx4 v[198:199], off
	s_mov_b32 m0, s74
	s_nop 0
	global_load_lds_dwordx4 v[200:201], off
	s_waitcnt vmcnt(8)
	s_waitcnt lgkmcnt(0)
	s_barrier
; #define PG8_STAGE(bufoff, gbase, voff) do { _Pragma("unroll") for (int _i = 0; _i < 2; ++_i) \
;         __builtin_amdgcn_global_load_lds((const unsigned*)((const char*)(gbase) + (voff)[_i]), (LAS unsigned*)(lds + (bufoff) + ldsw + _i * 8192), 16, 0, 0); } while (0)
; #define PG8_LDA(dst, b, h) do { _Pragma("unroll") for (int m = 0; m < 4; ++m) _Pragma("unroll") for (int k = 0; k < 2; ++k) dst[m][k] = *(const LAS bf16x8*)(lds + PG8_SA(b, h) + aoff + m * 2048 + k * 1024); } while (0)
; #define PG8_LDB(dst, b, h) do { _Pragma("unroll") for (int n = 0; n < 2; ++n) _Pragma("unroll") for (int k = 0; k < 2; ++k) dst[n][k] = *(const LAS bf16x8*)(lds + PG8_SB(b, h) + boff + n * 2048 + k * 1024); } while (0)
; #define PG8_MMA(ai, bj, At, Bt) do { __builtin_amdgcn_s_setprio(1); _Pragma("unroll") for (int m = 0; m < 4; ++m) _Pragma("unroll") for (int n = 0; n < 2; ++n) _Pragma("unroll") for (int k = 0; k < 2; ++k) \
;         acc[ai][bj][m][n] = __builtin_amdgcn_mfma_f32_16x16x32_bf16(Bt[n][k], At[m][k], acc[ai][bj][m][n], 0, 0, 0); __builtin_amdgcn_s_setprio(0); } while (0)
; #define PG8_WAIT_V(n) asm volatile("s_waitcnt vmcnt(" #n ")" ::: "memory")
; #define PG8_WAIT_L(n) asm volatile("s_waitcnt lgkmcnt(" #n ")" ::: "memory")
; #define PG8_BAR __builtin_amdgcn_s_barrier()
; #define PG8_SCHED __builtin_amdgcn_sched_barrier(0)
; template <class Epi>
; __device__ __forceinline__ void gemm_phase(LAS unsigned char* lds, const Gemm g, const Sched& S, const Epi& E, const int tid) {
;     ...
;             PG8_WAIT_V(8); PG8_WAIT_L(0); PG8_BAR; PG8_MMA(1, 0, At, B0); PG8_MMA(1, 1, At, B1); PG8_BAR; PG8_SCHED;
;             PG8_LDB(B0, 1, 0); PG8_LDB(B1, 1, 1); PG8_SCHED; PG8_LDA(At, 1, 0); PG8_STAGE(PG8_SA(0, 1), a2 + hA, voffA);
;             PG8_WAIT_V(8); PG8_WAIT_L(0); PG8_BAR; PG8_MMA(0, 0, At, B0); PG8_MMA(0, 1, At, B1); PG8_BAR; PG8_SCHED;
	s_setprio 1
	s_waitcnt lgkmcnt(0)
	v_mfma_f32_16x16x32_bf16 v[60:63], v[104:107], v[160:163], 0
	v_mfma_f32_16x16x32_bf16 v[56:59], v[120:123], v[160:163], 0
	v_mfma_f32_16x16x32_bf16 v[44:47], v[104:107], v[168:171], 0
	v_mfma_f32_16x16x32_bf16 v[40:43], v[120:123], v[168:171], 0
	v_mfma_f32_16x16x32_bf16 v[28:31], v[104:107], v[176:179], 0
	v_mfma_f32_16x16x32_bf16 v[24:27], v[120:123], v[176:179], 0
	v_mfma_f32_16x16x32_bf16 v[12:15], v[104:107], v[184:187], 0
	v_mfma_f32_16x16x32_bf16 v[8:11], v[120:123], v[184:187], 0
	v_mfma_f32_16x16x32_bf16 v[60:63], v[112:115], v[164:167], v[60:63]
	v_mfma_f32_16x16x32_bf16 v[56:59], v[128:131], v[164:167], v[56:59]
	v_mfma_f32_16x16x32_bf16 v[44:47], v[112:115], v[172:175], v[44:47]
	v_mfma_f32_16x16x32_bf16 v[40:43], v[128:131], v[172:175], v[40:43]
	v_mfma_f32_16x16x32_bf16 v[28:31], v[112:115], v[180:183], v[28:31]
	v_mfma_f32_16x16x32_bf16 v[24:27], v[128:131], v[180:183], v[24:27]
	v_mfma_f32_16x16x32_bf16 v[12:15], v[112:115], v[188:191], v[12:15]
	v_mfma_f32_16x16x32_bf16 v[8:11], v[128:131], v[188:191], v[8:11]
	s_setprio 0
	s_setprio 1
	v_mfma_f32_16x16x32_bf16 v[52:55], v[136:139], v[160:163], 0
	v_mfma_f32_16x16x32_bf16 v[48:51], v[148:151], v[160:163], 0
	v_mfma_f32_16x16x32_bf16 v[36:39], v[136:139], v[168:171], 0
	v_mfma_f32_16x16x32_bf16 v[32:35], v[148:151], v[168:171], 0
	v_mfma_f32_16x16x32_bf16 v[20:23], v[136:139], v[176:179], 0
	v_mfma_f32_16x16x32_bf16 v[16:19], v[148:151], v[176:179], 0
	v_mfma_f32_16x16x32_bf16 v[4:7], v[136:139], v[184:187], 0
	v_mfma_f32_16x16x32_bf16 v[0:3], v[148:151], v[184:187], 0
	v_mfma_f32_16x16x32_bf16 v[52:55], v[140:143], v[164:167], v[52:55]
	v_mfma_f32_16x16x32_bf16 v[48:51], v[156:159], v[164:167], v[48:51]
	v_mfma_f32_16x16x32_bf16 v[36:39], v[140:143], v[172:175], v[36:39]
	v_mfma_f32_16x16x32_bf16 v[32:35], v[156:159], v[172:175], v[32:35]
	v_mfma_f32_16x16x32_bf16 v[20:23], v[140:143], v[180:183], v[20:23]
	v_mfma_f32_16x16x32_bf16 v[16:19], v[156:159], v[180:183], v[16:19]
	v_mfma_f32_16x16x32_bf16 v[4:7], v[140:143], v[188:191], v[4:7]
	v_mfma_f32_16x16x32_bf16 v[0:3], v[156:159], v[188:191], v[0:3]
	s_setprio 0
	s_barrier
	s_add_i32 s42, 0, 0x18000
	s_add_i32 s45, 0, 0x1c000
	v_add_u32_e32 v128, s42, v241
	v_add_u32_e32 v156, s45, v241
	ds_read_b128 v[104:107], v128
	ds_read_b128 v[112:115], v128 offset:1024
	ds_read_b128 v[120:123], v128 offset:2048
	ds_read_b128 v[128:131], v128 offset:3072
	ds_read_b128 v[136:139], v156
	ds_read_b128 v[140:143], v156 offset:1024
	ds_read_b128 v[148:151], v156 offset:2048
	ds_read_b128 v[156:159], v156 offset:3072
	s_add_u32 s20, s72, 0x120000
	s_addc_u32 s21, s73, 0
	s_mov_b32 m0, s75
	v_lshl_add_u64 v[214:215], s[20:21], 0, v[204:205]
	ds_read_b128 v[160:163], v243 offset:32768
	ds_read_b128 v[164:167], v243 offset:33792
	ds_read_b128 v[168:171], v243 offset:34816
	ds_read_b128 v[172:175], v243 offset:35840
	ds_read_b128 v[176:179], v243 offset:36864
	ds_read_b128 v[180:183], v243 offset:37888
	ds_read_b128 v[184:187], v243 offset:38912
	ds_read_b128 v[188:191], v243 offset:39936
	global_load_lds_dwordx4 v[214:215], off
	v_lshl_add_u64 v[214:215], s[20:21], 0, v[206:207]
	s_mov_b32 m0, s76
	s_nop 0
	global_load_lds_dwordx4 v[214:215], off
	s_waitcnt vmcnt(8)
	s_waitcnt lgkmcnt(0)
	s_barrier
	s_setprio 1
	s_waitcnt lgkmcnt(0)
	v_mfma_f32_16x16x32_bf16 v[152:155], v[104:107], v[160:163], v[152:155]
	v_mfma_f32_16x16x32_bf16 v[144:147], v[120:123], v[160:163], v[144:147]
	v_mfma_f32_16x16x32_bf16 v[116:119], v[104:107], v[168:171], v[116:119]
	v_mfma_f32_16x16x32_bf16 v[108:111], v[120:123], v[168:171], v[108:111]
	v_mfma_f32_16x16x32_bf16 v[92:95], v[104:107], v[176:179], v[92:95]
	v_mfma_f32_16x16x32_bf16 v[88:91], v[120:123], v[176:179], v[88:91]
	v_mfma_f32_16x16x32_bf16 v[76:79], v[104:107], v[184:187], v[76:79]
	v_mfma_f32_16x16x32_bf16 v[72:75], v[120:123], v[184:187], v[72:75]
	v_mfma_f32_16x16x32_bf16 v[152:155], v[112:115], v[164:167], v[152:155]
	v_mfma_f32_16x16x32_bf16 v[144:147], v[128:131], v[164:167], v[144:147]
	v_mfma_f32_16x16x32_bf16 v[116:119], v[112:115], v[172:175], v[116:119]
	v_mfma_f32_16x16x32_bf16 v[108:111], v[128:131], v[172:175], v[108:111]
	v_mfma_f32_16x16x32_bf16 v[92:95], v[112:115], v[180:183], v[92:95]
	v_mfma_f32_16x16x32_bf16 v[88:91], v[128:131], v[180:183], v[88:91]
	v_mfma_f32_16x16x32_bf16 v[76:79], v[112:115], v[188:191], v[76:79]
	v_mfma_f32_16x16x32_bf16 v[72:75], v[128:131], v[188:191], v[72:75]
	s_setprio 0
	s_setprio 1
	v_mfma_f32_16x16x32_bf16 v[132:135], v[136:139], v[160:163], v[132:135]
	v_mfma_f32_16x16x32_bf16 v[124:127], v[148:151], v[160:163], v[124:127]
	v_mfma_f32_16x16x32_bf16 v[100:103], v[136:139], v[168:171], v[100:103]
	v_mfma_f32_16x16x32_bf16 v[96:99], v[148:151], v[168:171], v[96:99]
	v_mfma_f32_16x16x32_bf16 v[84:87], v[136:139], v[176:179], v[84:87]
	v_mfma_f32_16x16x32_bf16 v[80:83], v[148:151], v[176:179], v[80:83]
	v_mfma_f32_16x16x32_bf16 v[68:71], v[136:139], v[184:187], v[68:71]
	v_mfma_f32_16x16x32_bf16 v[64:67], v[148:151], v[184:187], v[64:67]
	v_mfma_f32_16x16x32_bf16 v[132:135], v[140:143], v[164:167], v[132:135]
	v_mfma_f32_16x16x32_bf16 v[124:127], v[156:159], v[164:167], v[124:127]
	v_mfma_f32_16x16x32_bf16 v[100:103], v[140:143], v[172:175], v[100:103]
	v_mfma_f32_16x16x32_bf16 v[96:99], v[156:159], v[172:175], v[96:99]
	v_mfma_f32_16x16x32_bf16 v[84:87], v[140:143], v[180:183], v[84:87]
	v_mfma_f32_16x16x32_bf16 v[80:83], v[156:159], v[180:183], v[80:83]
	v_mfma_f32_16x16x32_bf16 v[68:71], v[140:143], v[188:191], v[68:71]
	v_mfma_f32_16x16x32_bf16 v[64:67], v[156:159], v[188:191], v[64:67]
	s_setprio 0
	s_barrier
; #define PG8_STAGE(bufoff, gbase, voff) do { _Pragma("unroll") for (int _i = 0; _i < 2; ++_i) \
;         __builtin_amdgcn_global_load_lds((const unsigned*)((const char*)(gbase) + (voff)[_i]), (LAS unsigned*)(lds + (bufoff) + ldsw + _i * 8192), 16, 0, 0); } while (0)
; #define PG8_LDA(dst, b, h) do { _Pragma("unroll") for (int m = 0; m < 4; ++m) _Pragma("unroll") for (int k = 0; k < 2; ++k) dst[m][k] = *(const LAS bf16x8*)(lds + PG8_SA(b, h) + aoff + m * 2048 + k * 1024); } while (0)
; #define PG8_LDB(dst, b, h) do { _Pragma("unroll") for (int n = 0; n < 2; ++n) _Pragma("unroll") for (int k = 0; k < 2; ++k) dst[n][k] = *(const LAS bf16x8*)(lds + PG8_SB(b, h) + boff + n * 2048 + k * 1024); } while (0)
; #define PG8_MMA(ai, bj, At, Bt) do { __builtin_amdgcn_s_setprio(1); _Pragma("unroll") for (int m = 0; m < 4; ++m) _Pragma("unroll") for (int n = 0; n < 2; ++n) _Pragma("unroll") for (int k = 0; k < 2; ++k) \
;         acc[ai][bj][m][n] = __builtin_amdgcn_mfma_f32_16x16x32_bf16(Bt[n][k], At[m][k], acc[ai][bj][m][n], 0, 0, 0); __builtin_amdgcn_s_setprio(0); } while (0)
; #define PG8_WAIT_V(n) asm volatile("s_waitcnt vmcnt(" #n ")" ::: "memory")
; #define PG8_WAIT_L(n) asm volatile("s_waitcnt lgkmcnt(" #n ")" ::: "memory")
; #define PG8_BAR __builtin_amdgcn_s_barrier()
; #define PG8_SCHED __builtin_amdgcn_sched_barrier(0)
; template <class Epi>
; __device__ __forceinline__ void gemm_phase(LAS unsigned char* lds, const Gemm g, const Sched& S, const Epi& E, const int tid) {
;     ...
;         for (int t = 0; t < nt; t += 2) {
;             const bool last = (t == nt - 2);
;             const char* a1 = cA + (size_t)(t + 1) * kstep;
;             const char* a2 = last ? nA : cA + (size_t)(t + 2) * kstep; const char* b2 = last ? nB : cB + (size_t)(t + 2) * kstep;
;             const char* a3 = a2 + kstep; const char* b3 = b2 + kstep;
;             PG8_LDB(B0, 0, 0); PG8_LDB(B1, 0, 1); PG8_SCHED; PG8_LDA(At, 0, 0); PG8_STAGE(PG8_SA(1, 1), a1 + hA, voffA);
;     ...
;             PG8_LDA(At, 1, 1); PG8_STAGE(PG8_SB(1, 0), b3, voffB); PG8_STAGE(PG8_SB(1, 1), b3 + hB, voffB); PG8_STAGE(PG8_SA(1, 0), a3, voffA);
;             PG8_WAIT_V(8); PG8_WAIT_L(0); PG8_BAR; PG8_MMA(1, 0, At, B0); PG8_MMA(1, 1, At, B1); PG8_BAR; PG8_SCHED;
	s_add_i32 s20, s42, s35
	v_lshl_add_u64 v[194:195], v[194:195], 0, s[94:95]
	s_mov_b32 m0, s20
	ds_read_b128 v[160:163], v243 offset:49152
	ds_read_b128 v[164:167], v243 offset:50176
	ds_read_b128 v[168:171], v243 offset:51200
	ds_read_b128 v[172:175], v243 offset:52224
	ds_read_b128 v[176:179], v243 offset:53248
	ds_read_b128 v[180:183], v243 offset:54272
	ds_read_b128 v[184:187], v243 offset:55296
	ds_read_b128 v[188:191], v243 offset:56320
	global_load_lds_dwordx4 v[194:195], off
	s_add_i32 m0, s20, 0x2000
	s_add_u32 s20, s22, 0x20080
	v_lshl_add_u64 v[194:195], v[196:197], 0, s[94:95]
	s_addc_u32 s21, s23, 0
	s_add_i32 s22, s45, s35
	global_load_lds_dwordx4 v[194:195], off
	v_lshl_add_u64 v[194:195], s[20:21], 0, v[192:193]
	s_mov_b32 m0, s22
	s_nop 0
	global_load_lds_dwordx4 v[194:195], off
	v_lshl_add_u64 v[194:195], s[20:21], 0, v[208:209]
	s_add_i32 m0, s22, 0x2000
	s_nop 0
	global_load_lds_dwordx4 v[194:195], off
	v_lshl_add_u64 v[194:195], v[198:199], 0, s[94:95]
	s_mov_b32 m0, s77
	s_nop 0
	global_load_lds_dwordx4 v[194:195], off
	v_lshl_add_u64 v[194:195], v[200:201], 0, s[94:95]
	s_mov_b32 m0, s78
	s_nop 0
	global_load_lds_dwordx4 v[194:195], off
	s_waitcnt vmcnt(8)
	s_waitcnt lgkmcnt(0)
	s_barrier
	s_setprio 1
	s_waitcnt lgkmcnt(0)
	v_mfma_f32_16x16x32_bf16 v[60:63], v[104:107], v[160:163], v[60:63]
	v_mfma_f32_16x16x32_bf16 v[56:59], v[120:123], v[160:163], v[56:59]
	v_mfma_f32_16x16x32_bf16 v[44:47], v[104:107], v[168:171], v[44:47]
	v_mfma_f32_16x16x32_bf16 v[40:43], v[120:123], v[168:171], v[40:43]
	v_mfma_f32_16x16x32_bf16 v[28:31], v[104:107], v[176:179], v[28:31]
	v_mfma_f32_16x16x32_bf16 v[24:27], v[120:123], v[176:179], v[24:27]
	v_mfma_f32_16x16x32_bf16 v[12:15], v[104:107], v[184:187], v[12:15]
	v_mfma_f32_16x16x32_bf16 v[8:11], v[120:123], v[184:187], v[8:11]
	v_mfma_f32_16x16x32_bf16 v[60:63], v[112:115], v[164:167], v[60:63]
	v_mfma_f32_16x16x32_bf16 v[56:59], v[128:131], v[164:167], v[56:59]
	v_mfma_f32_16x16x32_bf16 v[44:47], v[112:115], v[172:175], v[44:47]
	v_mfma_f32_16x16x32_bf16 v[40:43], v[128:131], v[172:175], v[40:43]
	v_mfma_f32_16x16x32_bf16 v[28:31], v[112:115], v[180:183], v[28:31]
	v_mfma_f32_16x16x32_bf16 v[24:27], v[128:131], v[180:183], v[24:27]
	v_mfma_f32_16x16x32_bf16 v[12:15], v[112:115], v[188:191], v[12:15]
	v_mfma_f32_16x16x32_bf16 v[8:11], v[128:131], v[188:191], v[8:11]
	s_setprio 0
	s_setprio 1
	v_mfma_f32_16x16x32_bf16 v[52:55], v[136:139], v[160:163], v[52:55]
	v_mfma_f32_16x16x32_bf16 v[48:51], v[148:151], v[160:163], v[48:51]
	v_mfma_f32_16x16x32_bf16 v[36:39], v[136:139], v[168:171], v[36:39]
	v_mfma_f32_16x16x32_bf16 v[32:35], v[148:151], v[168:171], v[32:35]
	v_mfma_f32_16x16x32_bf16 v[20:23], v[136:139], v[176:179], v[20:23]
	v_mfma_f32_16x16x32_bf16 v[16:19], v[148:151], v[176:179], v[16:19]
	v_mfma_f32_16x16x32_bf16 v[4:7], v[136:139], v[184:187], v[4:7]
	v_mfma_f32_16x16x32_bf16 v[0:3], v[148:151], v[184:187], v[0:3]
	v_mfma_f32_16x16x32_bf16 v[52:55], v[140:143], v[164:167], v[52:55]
	v_mfma_f32_16x16x32_bf16 v[48:51], v[156:159], v[164:167], v[48:51]
	v_mfma_f32_16x16x32_bf16 v[36:39], v[140:143], v[172:175], v[36:39]
	v_mfma_f32_16x16x32_bf16 v[32:35], v[156:159], v[172:175], v[32:35]
	v_mfma_f32_16x16x32_bf16 v[20:23], v[140:143], v[180:183], v[20:23]
	v_mfma_f32_16x16x32_bf16 v[16:19], v[156:159], v[180:183], v[16:19]
	v_mfma_f32_16x16x32_bf16 v[4:7], v[140:143], v[188:191], v[4:7]
	v_mfma_f32_16x16x32_bf16 v[0:3], v[156:159], v[188:191], v[0:3]
	s_add_i32 s40, s40, 2
	s_add_u32 s13, s13, 0x100
	s_addc_u32 s37, s37, 0
	s_cmp_gt_u32 s40, 5
	s_mov_b64 s[20:21], s[6:7]
	s_setprio 0
	s_barrier
	s_cbranch_scc1 .Lgk_exit_2
.LBB0_1029:
	s_add_u32 s6, s20, 0x100
	s_addc_u32 s7, s21, 0
	s_add_i32 s42, 0, 0x10000
	s_cmp_eq_u32 s40, 4
	s_cselect_b32 s73, s15, s7
	s_cselect_b32 s72, s14, s6
	s_cselect_b32 s23, s17, s37
	s_cselect_b32 s22, s16, s13
	s_add_i32 s45, 0, 0x14000
	v_add_u32_e32 v128, s42, v241
	v_add_u32_e32 v156, s45, v241
	ds_read_b128 v[104:107], v128
	ds_read_b128 v[112:115], v128 offset:1024
	ds_read_b128 v[120:123], v128 offset:2048
	ds_read_b128 v[128:131], v128 offset:3072
	ds_read_b128 v[136:139], v156
	ds_read_b128 v[140:143], v156 offset:1024
	ds_read_b128 v[148:151], v156 offset:2048
	ds_read_b128 v[156:159], v156 offset:3072
	v_lshl_add_u64 v[194:195], s[20:21], 0, v[210:211]
	s_add_i32 m0, s19, 0xc000
	ds_read_b128 v[160:163], v243
	ds_read_b128 v[164:167], v243 offset:1024
	ds_read_b128 v[168:171], v243 offset:2048
	ds_read_b128 v[172:175], v243 offset:3072
	ds_read_b128 v[176:179], v243 offset:4096
	ds_read_b128 v[180:183], v243 offset:5120
	ds_read_b128 v[184:187], v243 offset:6144
	ds_read_b128 v[188:191], v243 offset:7168
	global_load_lds_dwordx4 v[194:195], off
	v_lshl_add_u64 v[194:195], s[20:21], 0, v[212:213]
	s_add_i32 m0, s19, 0xe000
	s_nop 0
	global_load_lds_dwordx4 v[194:195], off
	s_waitcnt vmcnt(8)
	s_waitcnt lgkmcnt(0)
	s_barrier
; #define PG8_STAGE(bufoff, gbase, voff) do { _Pragma("unroll") for (int _i = 0; _i < 2; ++_i) \
;         __builtin_amdgcn_global_load_lds((const unsigned*)((const char*)(gbase) + (voff)[_i]), (LAS unsigned*)(lds + (bufoff) + ldsw + _i * 8192), 16, 0, 0); } while (0)
; #define PG8_LDA(dst, b, h) do { _Pragma("unroll") for (int m = 0; m < 4; ++m) _Pragma("unroll") for (int k = 0; k < 2; ++k) dst[m][k] = *(const LAS bf16x8*)(lds + PG8_SA(b, h) + aoff + m * 2048 + k * 1024); } while (0)
; #define PG8_MMA(ai, bj, At, Bt) do { __builtin_amdgcn_s_setprio(1); _Pragma("unroll") for (int m = 0; m < 4; ++m) _Pragma("unroll") for (int n = 0; n < 2; ++n) _Pragma("unroll") for (int k = 0; k < 2; ++k) \
;         acc[ai][bj][m][n] = __builtin_amdgcn_mfma_f32_16x16x32_bf16(Bt[n][k], At[m][k], acc[ai][bj][m][n], 0, 0, 0); __builtin_amdgcn_s_setprio(0); } while (0)
; #define PG8_WAIT_V(n) asm volatile("s_waitcnt vmcnt(" #n ")" ::: "memory")
; #define PG8_WAIT_L(n) asm volatile("s_waitcnt lgkmcnt(" #n ")" ::: "memory")
; #define PG8_BAR __builtin_amdgcn_s_barrier()
; #define PG8_SCHED __builtin_amdgcn_sched_barrier(0)
; template <class Epi>
; __device__ __forceinline__ void gemm_phase(LAS unsigned char* lds, const Gemm g, const Sched& S, const Epi& E, const int tid) {
;     ...
;             PG8_WAIT_V(8); PG8_WAIT_L(0); PG8_BAR; PG8_MMA(0, 0, At, B0); PG8_MMA(0, 1, At, B1); PG8_BAR; PG8_SCHED;
;             PG8_LDA(At, 0, 1); PG8_STAGE(PG8_SB(0, 0), b2, voffB); PG8_STAGE(PG8_SB(0, 1), b2 + hB, voffB); PG8_STAGE(PG8_SA(0, 0), a2, voffA);
;             PG8_WAIT_V(8); PG8_WAIT_L(0); PG8_BAR; PG8_MMA(1, 0, At, B0); PG8_MMA(1, 1, At, B1); PG8_BAR; PG8_SCHED;
	s_setprio 1
	s_waitcnt lgkmcnt(0)
	v_mfma_f32_16x16x32_bf16 v[152:155], v[104:107], v[160:163], v[152:155]
	v_mfma_f32_16x16x32_bf16 v[144:147], v[120:123], v[160:163], v[144:147]
	v_mfma_f32_16x16x32_bf16 v[116:119], v[104:107], v[168:171], v[116:119]
	v_mfma_f32_16x16x32_bf16 v[108:111], v[120:123], v[168:171], v[108:111]
	v_mfma_f32_16x16x32_bf16 v[92:95], v[104:107], v[176:179], v[92:95]
	v_mfma_f32_16x16x32_bf16 v[88:91], v[120:123], v[176:179], v[88:91]
	v_mfma_f32_16x16x32_bf16 v[76:79], v[104:107], v[184:187], v[76:79]
	v_mfma_f32_16x16x32_bf16 v[72:75], v[120:123], v[184:187], v[72:75]
	v_mfma_f32_16x16x32_bf16 v[152:155], v[112:115], v[164:167], v[152:155]
	v_mfma_f32_16x16x32_bf16 v[144:147], v[128:131], v[164:167], v[144:147]
	v_mfma_f32_16x16x32_bf16 v[116:119], v[112:115], v[172:175], v[116:119]
	v_mfma_f32_16x16x32_bf16 v[108:111], v[128:131], v[172:175], v[108:111]
	v_mfma_f32_16x16x32_bf16 v[92:95], v[112:115], v[180:183], v[92:95]
	v_mfma_f32_16x16x32_bf16 v[88:91], v[128:131], v[180:183], v[88:91]
	v_mfma_f32_16x16x32_bf16 v[76:79], v[112:115], v[188:191], v[76:79]
	v_mfma_f32_16x16x32_bf16 v[72:75], v[128:131], v[188:191], v[72:75]
	s_setprio 0
	s_setprio 1
	v_mfma_f32_16x16x32_bf16 v[132:135], v[136:139], v[160:163], v[132:135]
	v_mfma_f32_16x16x32_bf16 v[124:127], v[148:151], v[160:163], v[124:127]
	v_mfma_f32_16x16x32_bf16 v[100:103], v[136:139], v[168:171], v[100:103]
	v_mfma_f32_16x16x32_bf16 v[96:99], v[148:151], v[168:171], v[96:99]
	v_mfma_f32_16x16x32_bf16 v[84:87], v[136:139], v[176:179], v[84:87]
	v_mfma_f32_16x16x32_bf16 v[80:83], v[148:151], v[176:179], v[80:83]
	v_mfma_f32_16x16x32_bf16 v[68:71], v[136:139], v[184:187], v[68:71]
	v_mfma_f32_16x16x32_bf16 v[64:67], v[148:151], v[184:187], v[64:67]
	v_mfma_f32_16x16x32_bf16 v[132:135], v[140:143], v[164:167], v[132:135]
	v_mfma_f32_16x16x32_bf16 v[124:127], v[156:159], v[164:167], v[124:127]
	v_mfma_f32_16x16x32_bf16 v[100:103], v[140:143], v[172:175], v[100:103]
	v_mfma_f32_16x16x32_bf16 v[96:99], v[156:159], v[172:175], v[96:99]
	v_mfma_f32_16x16x32_bf16 v[84:87], v[140:143], v[180:183], v[84:87]
	v_mfma_f32_16x16x32_bf16 v[80:83], v[156:159], v[180:183], v[80:83]
	v_mfma_f32_16x16x32_bf16 v[68:71], v[140:143], v[188:191], v[68:71]
	v_mfma_f32_16x16x32_bf16 v[64:67], v[156:159], v[188:191], v[64:67]
	s_setprio 0
	s_barrier
	s_add_i32 s20, s42, s35
	v_lshl_add_u64 v[194:195], s[22:23], 0, v[192:193]
	s_mov_b32 m0, s20
	ds_read_b128 v[160:163], v243 offset:16384
	ds_read_b128 v[164:167], v243 offset:17408
	ds_read_b128 v[168:171], v243 offset:18432
	ds_read_b128 v[172:175], v243 offset:19456
	ds_read_b128 v[176:179], v243 offset:20480
	ds_read_b128 v[180:183], v243 offset:21504
	ds_read_b128 v[184:187], v243 offset:22528
	ds_read_b128 v[188:191], v243 offset:23552
	global_load_lds_dwordx4 v[194:195], off
	s_add_i32 m0, s20, 0x2000
	s_add_u32 s20, s22, 0x20000
	v_lshl_add_u64 v[196:197], s[22:23], 0, v[208:209]
	s_addc_u32 s21, s23, 0
	s_add_i32 s42, s45, s35
	global_load_lds_dwordx4 v[196:197], off
	v_lshl_add_u64 v[198:199], s[20:21], 0, v[192:193]
	s_mov_b32 m0, s42
	v_lshl_add_u64 v[200:201], s[72:73], 0, v[206:207]
	global_load_lds_dwordx4 v[198:199], off
	v_lshl_add_u64 v[198:199], s[20:21], 0, v[208:209]
	s_add_i32 m0, s42, 0x2000
	s_nop 0
	global_load_lds_dwordx4 v[198:199], off
	v_lshl_add_u64 v[198:199], s[72:73], 0, v[204:205]
	s_mov_b32 m0, s19
	s_nop 0
	global_load_lds_dwordx4 v[198:199], off
	s_mov_b32 m0, s74
	s_nop 0
	global_load_lds_dwordx4 v[200:201], off
	s_waitcnt vmcnt(8)
	s_waitcnt lgkmcnt(0)
	s_barrier
	s_setprio 1
	s_waitcnt lgkmcnt(0)
	v_mfma_f32_16x16x32_bf16 v[60:63], v[104:107], v[160:163], v[60:63]
	v_mfma_f32_16x16x32_bf16 v[56:59], v[120:123], v[160:163], v[56:59]
	v_mfma_f32_16x16x32_bf16 v[44:47], v[104:107], v[168:171], v[44:47]
	v_mfma_f32_16x16x32_bf16 v[40:43], v[120:123], v[168:171], v[40:43]
	v_mfma_f32_16x16x32_bf16 v[28:31], v[104:107], v[176:179], v[28:31]
	v_mfma_f32_16x16x32_bf16 v[24:27], v[120:123], v[176:179], v[24:27]
	v_mfma_f32_16x16x32_bf16 v[12:15], v[104:107], v[184:187], v[12:15]
	v_mfma_f32_16x16x32_bf16 v[8:11], v[120:123], v[184:187], v[8:11]
	v_mfma_f32_16x16x32_bf16 v[60:63], v[112:115], v[164:167], v[60:63]
	v_mfma_f32_16x16x32_bf16 v[56:59], v[128:131], v[164:167], v[56:59]
	v_mfma_f32_16x16x32_bf16 v[44:47], v[112:115], v[172:175], v[44:47]
	v_mfma_f32_16x16x32_bf16 v[40:43], v[128:131], v[172:175], v[40:43]
	v_mfma_f32_16x16x32_bf16 v[28:31], v[112:115], v[180:183], v[28:31]
	v_mfma_f32_16x16x32_bf16 v[24:27], v[128:131], v[180:183], v[24:27]
	v_mfma_f32_16x16x32_bf16 v[12:15], v[112:115], v[188:191], v[12:15]
	v_mfma_f32_16x16x32_bf16 v[8:11], v[128:131], v[188:191], v[8:11]
	s_setprio 0
	s_setprio 1
	v_mfma_f32_16x16x32_bf16 v[52:55], v[136:139], v[160:163], v[52:55]
	v_mfma_f32_16x16x32_bf16 v[48:51], v[148:151], v[160:163], v[48:51]
	v_mfma_f32_16x16x32_bf16 v[36:39], v[136:139], v[168:171], v[36:39]
	v_mfma_f32_16x16x32_bf16 v[32:35], v[148:151], v[168:171], v[32:35]
	v_mfma_f32_16x16x32_bf16 v[20:23], v[136:139], v[176:179], v[20:23]
	v_mfma_f32_16x16x32_bf16 v[16:19], v[148:151], v[176:179], v[16:19]
	v_mfma_f32_16x16x32_bf16 v[4:7], v[136:139], v[184:187], v[4:7]
	v_mfma_f32_16x16x32_bf16 v[0:3], v[148:151], v[184:187], v[0:3]
	v_mfma_f32_16x16x32_bf16 v[52:55], v[140:143], v[164:167], v[52:55]
	v_mfma_f32_16x16x32_bf16 v[48:51], v[156:159], v[164:167], v[48:51]
	v_mfma_f32_16x16x32_bf16 v[36:39], v[140:143], v[172:175], v[36:39]
	v_mfma_f32_16x16x32_bf16 v[32:35], v[156:159], v[172:175], v[32:35]
	v_mfma_f32_16x16x32_bf16 v[20:23], v[140:143], v[180:183], v[20:23]
	v_mfma_f32_16x16x32_bf16 v[16:19], v[156:159], v[180:183], v[16:19]
	v_mfma_f32_16x16x32_bf16 v[4:7], v[140:143], v[188:191], v[4:7]
	v_mfma_f32_16x16x32_bf16 v[0:3], v[156:159], v[188:191], v[0:3]
	s_setprio 0
	s_barrier
; #define PG8_STAGE(bufoff, gbase, voff) do { _Pragma("unroll") for (int _i = 0; _i < 2; ++_i) \
;         __builtin_amdgcn_global_load_lds((const unsigned*)((const char*)(gbase) + (voff)[_i]), (LAS unsigned*)(lds + (bufoff) + ldsw + _i * 8192), 16, 0, 0); } while (0)
; #define PG8_LDA(dst, b, h) do { _Pragma("unroll") for (int m = 0; m < 4; ++m) _Pragma("unroll") for (int k = 0; k < 2; ++k) dst[m][k] = *(const LAS bf16x8*)(lds + PG8_SA(b, h) + aoff + m * 2048 + k * 1024); } while (0)
; #define PG8_LDB(dst, b, h) do { _Pragma("unroll") for (int n = 0; n < 2; ++n) _Pragma("unroll") for (int k = 0; k < 2; ++k) dst[n][k] = *(const LAS bf16x8*)(lds + PG8_SB(b, h) + boff + n * 2048 + k * 1024); } while (0)
; #define PG8_MMA(ai, bj, At, Bt) do { __builtin_amdgcn_s_setprio(1); _Pragma("unroll") for (int m = 0; m < 4; ++m) _Pragma("unroll") for (int n = 0; n < 2; ++n) _Pragma("unroll") for (int k = 0; k < 2; ++k) \
;         acc[ai][bj][m][n] = __builtin_amdgcn_mfma_f32_16x16x32_bf16(Bt[n][k], At[m][k], acc[ai][bj][m][n], 0, 0, 0); __builtin_amdgcn_s_setprio(0); } while (0)
; #define PG8_WAIT_V(n) asm volatile("s_waitcnt vmcnt(" #n ")" ::: "memory")
; #define PG8_WAIT_L(n) asm volatile("s_waitcnt lgkmcnt(" #n ")" ::: "memory")
; #define PG8_BAR __builtin_amdgcn_s_barrier()
; #define PG8_SCHED __builtin_amdgcn_sched_barrier(0)
; template <class Epi>
; __device__ __forceinline__ void gemm_phase(LAS unsigned char* lds, const Gemm g, const Sched& S, const Epi& E, const int tid) {
;     ...
;             PG8_LDB(B0, 1, 0); PG8_LDB(B1, 1, 1); PG8_SCHED; PG8_LDA(At, 1, 0); PG8_STAGE(PG8_SA(0, 1), a2 + hA, voffA);
;             PG8_WAIT_V(8); PG8_WAIT_L(0); PG8_BAR; PG8_MMA(0, 0, At, B0); PG8_MMA(0, 1, At, B1); PG8_BAR; PG8_SCHED;
	s_add_i32 s42, 0, 0x18000
	s_add_i32 s45, 0, 0x1c000
	v_add_u32_e32 v128, s42, v241
	v_add_u32_e32 v156, s45, v241
	ds_read_b128 v[104:107], v128
	ds_read_b128 v[112:115], v128 offset:1024
	ds_read_b128 v[120:123], v128 offset:2048
	ds_read_b128 v[128:131], v128 offset:3072
	ds_read_b128 v[136:139], v156
	ds_read_b128 v[140:143], v156 offset:1024
	ds_read_b128 v[148:151], v156 offset:2048
	ds_read_b128 v[156:159], v156 offset:3072
	s_add_u32 s20, s72, 0x120000
	s_addc_u32 s21, s73, 0
	s_mov_b32 m0, s75
	v_lshl_add_u64 v[214:215], s[20:21], 0, v[204:205]
	ds_read_b128 v[160:163], v243 offset:32768
	ds_read_b128 v[164:167], v243 offset:33792
	ds_read_b128 v[168:171], v243 offset:34816
	ds_read_b128 v[172:175], v243 offset:35840
	ds_read_b128 v[176:179], v243 offset:36864
	ds_read_b128 v[180:183], v243 offset:37888
	ds_read_b128 v[184:187], v243 offset:38912
	ds_read_b128 v[188:191], v243 offset:39936
	global_load_lds_dwordx4 v[214:215], off
	v_lshl_add_u64 v[214:215], s[20:21], 0, v[206:207]
	s_mov_b32 m0, s76
	s_nop 0
	global_load_lds_dwordx4 v[214:215], off
	s_waitcnt vmcnt(8)
	s_waitcnt lgkmcnt(0)
	s_barrier
	s_setprio 1
	s_waitcnt lgkmcnt(0)
	v_mfma_f32_16x16x32_bf16 v[152:155], v[104:107], v[160:163], v[152:155]
	v_mfma_f32_16x16x32_bf16 v[144:147], v[120:123], v[160:163], v[144:147]
	v_mfma_f32_16x16x32_bf16 v[116:119], v[104:107], v[168:171], v[116:119]
	v_mfma_f32_16x16x32_bf16 v[108:111], v[120:123], v[168:171], v[108:111]
	v_mfma_f32_16x16x32_bf16 v[92:95], v[104:107], v[176:179], v[92:95]
	v_mfma_f32_16x16x32_bf16 v[88:91], v[120:123], v[176:179], v[88:91]
	v_mfma_f32_16x16x32_bf16 v[76:79], v[104:107], v[184:187], v[76:79]
	v_mfma_f32_16x16x32_bf16 v[72:75], v[120:123], v[184:187], v[72:75]
	v_mfma_f32_16x16x32_bf16 v[152:155], v[112:115], v[164:167], v[152:155]
	v_mfma_f32_16x16x32_bf16 v[144:147], v[128:131], v[164:167], v[144:147]
	v_mfma_f32_16x16x32_bf16 v[116:119], v[112:115], v[172:175], v[116:119]
	v_mfma_f32_16x16x32_bf16 v[108:111], v[128:131], v[172:175], v[108:111]
	v_mfma_f32_16x16x32_bf16 v[92:95], v[112:115], v[180:183], v[92:95]
	v_mfma_f32_16x16x32_bf16 v[88:91], v[128:131], v[180:183], v[88:91]
	v_mfma_f32_16x16x32_bf16 v[76:79], v[112:115], v[188:191], v[76:79]
	v_mfma_f32_16x16x32_bf16 v[72:75], v[128:131], v[188:191], v[72:75]
	s_setprio 0
	s_setprio 1
	v_mfma_f32_16x16x32_bf16 v[132:135], v[136:139], v[160:163], v[132:135]
	v_mfma_f32_16x16x32_bf16 v[124:127], v[148:151], v[160:163], v[124:127]
	v_mfma_f32_16x16x32_bf16 v[100:103], v[136:139], v[168:171], v[100:103]
	v_mfma_f32_16x16x32_bf16 v[96:99], v[148:151], v[168:171], v[96:99]
	v_mfma_f32_16x16x32_bf16 v[84:87], v[136:139], v[176:179], v[84:87]
	v_mfma_f32_16x16x32_bf16 v[80:83], v[148:151], v[176:179], v[80:83]
	v_mfma_f32_16x16x32_bf16 v[68:71], v[136:139], v[184:187], v[68:71]
	v_mfma_f32_16x16x32_bf16 v[64:67], v[148:151], v[184:187], v[64:67]
	v_mfma_f32_16x16x32_bf16 v[132:135], v[140:143], v[164:167], v[132:135]
	v_mfma_f32_16x16x32_bf16 v[124:127], v[156:159], v[164:167], v[124:127]
	v_mfma_f32_16x16x32_bf16 v[100:103], v[140:143], v[172:175], v[100:103]
	v_mfma_f32_16x16x32_bf16 v[96:99], v[156:159], v[172:175], v[96:99]
	v_mfma_f32_16x16x32_bf16 v[84:87], v[140:143], v[180:183], v[84:87]
	v_mfma_f32_16x16x32_bf16 v[80:83], v[156:159], v[180:183], v[80:83]
	v_mfma_f32_16x16x32_bf16 v[68:71], v[140:143], v[188:191], v[68:71]
	v_mfma_f32_16x16x32_bf16 v[64:67], v[156:159], v[188:191], v[64:67]
	s_setprio 0
	s_barrier
; #define PG8_STAGE(bufoff, gbase, voff) do { _Pragma("unroll") for (int _i = 0; _i < 2; ++_i) \
;         __builtin_amdgcn_global_load_lds((const unsigned*)((const char*)(gbase) + (voff)[_i]), (LAS unsigned*)(lds + (bufoff) + ldsw + _i * 8192), 16, 0, 0); } while (0)
; #define PG8_LDA(dst, b, h) do { _Pragma("unroll") for (int m = 0; m < 4; ++m) _Pragma("unroll") for (int k = 0; k < 2; ++k) dst[m][k] = *(const LAS bf16x8*)(lds + PG8_SA(b, h) + aoff + m * 2048 + k * 1024); } while (0)
; #define PG8_MMA(ai, bj, At, Bt) do { __builtin_amdgcn_s_setprio(1); _Pragma("unroll") for (int m = 0; m < 4; ++m) _Pragma("unroll") for (int n = 0; n < 2; ++n) _Pragma("unroll") for (int k = 0; k < 2; ++k) \
;         acc[ai][bj][m][n] = __builtin_amdgcn_mfma_f32_16x16x32_bf16(Bt[n][k], At[m][k], acc[ai][bj][m][n], 0, 0, 0); __builtin_amdgcn_s_setprio(0); } while (0)
; #define PG8_WAIT_V(n) asm volatile("s_waitcnt vmcnt(" #n ")" ::: "memory")
; #define PG8_WAIT_L(n) asm volatile("s_waitcnt lgkmcnt(" #n ")" ::: "memory")
; #define PG8_BAR __builtin_amdgcn_s_barrier()
; #define PG8_SCHED __builtin_amdgcn_sched_barrier(0)
; template <class Epi>
; __device__ __forceinline__ void gemm_phase(LAS unsigned char* lds, const Gemm g, const Sched& S, const Epi& E, const int tid) {
;     ...
;             PG8_LDA(At, 1, 1); PG8_STAGE(PG8_SB(1, 0), b3, voffB); PG8_STAGE(PG8_SB(1, 1), b3 + hB, voffB); PG8_STAGE(PG8_SA(1, 0), a3, voffA);
;             PG8_WAIT_V(8); PG8_WAIT_L(0); PG8_BAR; PG8_MMA(1, 0, At, B0); PG8_MMA(1, 1, At, B1); PG8_BAR; PG8_SCHED;
;         }
	s_add_i32 s20, s42, s35
	v_lshl_add_u64 v[194:195], v[194:195], 0, s[94:95]
	s_mov_b32 m0, s20
	ds_read_b128 v[160:163], v243 offset:49152
	ds_read_b128 v[164:167], v243 offset:50176
	ds_read_b128 v[168:171], v243 offset:51200
	ds_read_b128 v[172:175], v243 offset:52224
	ds_read_b128 v[176:179], v243 offset:53248
	ds_read_b128 v[180:183], v243 offset:54272
	ds_read_b128 v[184:187], v243 offset:55296
	ds_read_b128 v[188:191], v243 offset:56320
	global_load_lds_dwordx4 v[194:195], off
	s_add_i32 m0, s20, 0x2000
	s_add_u32 s20, s22, 0x20080
	v_lshl_add_u64 v[194:195], v[196:197], 0, s[94:95]
	s_addc_u32 s21, s23, 0
	s_add_i32 s22, s45, s35
	global_load_lds_dwordx4 v[194:195], off
	v_lshl_add_u64 v[194:195], s[20:21], 0, v[192:193]
	s_mov_b32 m0, s22
	s_nop 0
	global_load_lds_dwordx4 v[194:195], off
	v_lshl_add_u64 v[194:195], s[20:21], 0, v[208:209]
	s_add_i32 m0, s22, 0x2000
	s_nop 0
	global_load_lds_dwordx4 v[194:195], off
	v_lshl_add_u64 v[194:195], v[198:199], 0, s[94:95]
	s_mov_b32 m0, s77
	s_nop 0
	global_load_lds_dwordx4 v[194:195], off
	v_lshl_add_u64 v[194:195], v[200:201], 0, s[94:95]
	s_mov_b32 m0, s78
	s_nop 0
	global_load_lds_dwordx4 v[194:195], off
	s_waitcnt vmcnt(8)
	s_waitcnt lgkmcnt(0)
	s_barrier
	s_setprio 1
	s_waitcnt lgkmcnt(0)
	v_mfma_f32_16x16x32_bf16 v[60:63], v[104:107], v[160:163], v[60:63]
	v_mfma_f32_16x16x32_bf16 v[56:59], v[120:123], v[160:163], v[56:59]
	v_mfma_f32_16x16x32_bf16 v[44:47], v[104:107], v[168:171], v[44:47]
	v_mfma_f32_16x16x32_bf16 v[40:43], v[120:123], v[168:171], v[40:43]
	v_mfma_f32_16x16x32_bf16 v[28:31], v[104:107], v[176:179], v[28:31]
	v_mfma_f32_16x16x32_bf16 v[24:27], v[120:123], v[176:179], v[24:27]
	v_mfma_f32_16x16x32_bf16 v[12:15], v[104:107], v[184:187], v[12:15]
	v_mfma_f32_16x16x32_bf16 v[8:11], v[120:123], v[184:187], v[8:11]
	v_mfma_f32_16x16x32_bf16 v[60:63], v[112:115], v[164:167], v[60:63]
	v_mfma_f32_16x16x32_bf16 v[56:59], v[128:131], v[164:167], v[56:59]
	v_mfma_f32_16x16x32_bf16 v[44:47], v[112:115], v[172:175], v[44:47]
	v_mfma_f32_16x16x32_bf16 v[40:43], v[128:131], v[172:175], v[40:43]
	v_mfma_f32_16x16x32_bf16 v[28:31], v[112:115], v[180:183], v[28:31]
	v_mfma_f32_16x16x32_bf16 v[24:27], v[128:131], v[180:183], v[24:27]
	v_mfma_f32_16x16x32_bf16 v[12:15], v[112:115], v[188:191], v[12:15]
	v_mfma_f32_16x16x32_bf16 v[8:11], v[128:131], v[188:191], v[8:11]
	s_setprio 0
	s_setprio 1
	v_mfma_f32_16x16x32_bf16 v[52:55], v[136:139], v[160:163], v[52:55]
	v_mfma_f32_16x16x32_bf16 v[48:51], v[148:151], v[160:163], v[48:51]
	v_mfma_f32_16x16x32_bf16 v[36:39], v[136:139], v[168:171], v[36:39]
	v_mfma_f32_16x16x32_bf16 v[32:35], v[148:151], v[168:171], v[32:35]
	v_mfma_f32_16x16x32_bf16 v[20:23], v[136:139], v[176:179], v[20:23]
	v_mfma_f32_16x16x32_bf16 v[16:19], v[148:151], v[176:179], v[16:19]
	v_mfma_f32_16x16x32_bf16 v[4:7], v[136:139], v[184:187], v[4:7]
	v_mfma_f32_16x16x32_bf16 v[0:3], v[148:151], v[184:187], v[0:3]
	v_mfma_f32_16x16x32_bf16 v[52:55], v[140:143], v[164:167], v[52:55]
	v_mfma_f32_16x16x32_bf16 v[48:51], v[156:159], v[164:167], v[48:51]
	v_mfma_f32_16x16x32_bf16 v[36:39], v[140:143], v[172:175], v[36:39]
	v_mfma_f32_16x16x32_bf16 v[32:35], v[156:159], v[172:175], v[32:35]
	v_mfma_f32_16x16x32_bf16 v[20:23], v[140:143], v[180:183], v[20:23]
	v_mfma_f32_16x16x32_bf16 v[16:19], v[156:159], v[180:183], v[16:19]
	v_mfma_f32_16x16x32_bf16 v[4:7], v[140:143], v[188:191], v[4:7]
	v_mfma_f32_16x16x32_bf16 v[0:3], v[156:159], v[188:191], v[0:3]
	s_add_i32 s40, s40, 2
	s_add_u32 s13, s13, 0x100
	s_addc_u32 s37, s37, 0
	s_cmp_gt_u32 s40, 5
	s_mov_b64 s[20:21], s[6:7]
	s_setprio 0
	s_barrier
	s_cbranch_scc0 .LBB0_1029

; #define PG8_STAGE(bufoff, gbase, voff) do { _Pragma("unroll") for (int _i = 0; _i < 2; ++_i) \
;         __builtin_amdgcn_global_load_lds((const unsigned*)((const char*)(gbase) + (voff)[_i]), (LAS unsigned*)(lds + (bufoff) + ldsw + _i * 8192), 16, 0, 0); } while (0)
; #define PG8_LDA(dst, b, h) do { _Pragma("unroll") for (int m = 0; m < 4; ++m) _Pragma("unroll") for (int k = 0; k < 2; ++k) dst[m][k] = *(const LAS bf16x8*)(lds + PG8_SA(b, h) + aoff + m * 2048 + k * 1024); } while (0)
; #define PG8_LDB(dst, b, h) do { _Pragma("unroll") for (int n = 0; n < 2; ++n) _Pragma("unroll") for (int k = 0; k < 2; ++k) dst[n][k] = *(const LAS bf16x8*)(lds + PG8_SB(b, h) + boff + n * 2048 + k * 1024); } while (0)
; #define PG8_MMA(ai, bj, At, Bt) do { __builtin_amdgcn_s_setprio(1); _Pragma("unroll") for (int m = 0; m < 4; ++m) _Pragma("unroll") for (int n = 0; n < 2; ++n) _Pragma("unroll") for (int k = 0; k < 2; ++k) \
;         acc[ai][bj][m][n] = __builtin_amdgcn_mfma_f32_16x16x32_bf16(Bt[n][k], At[m][k], acc[ai][bj][m][n], 0, 0, 0); __builtin_amdgcn_s_setprio(0); } while (0)
; #define PG8_WAIT_V(n) asm volatile("s_waitcnt vmcnt(" #n ")" ::: "memory")
; #define PG8_WAIT_L(n) asm volatile("s_waitcnt lgkmcnt(" #n ")" ::: "memory")
; #define PG8_BAR __builtin_amdgcn_s_barrier()
; #define PG8_SCHED __builtin_amdgcn_sched_barrier(0)
; template <class Epi>
; __device__ __forceinline__ void gemm_phase(LAS unsigned char* lds, const Gemm g, const Sched& S, const Epi& E, const int tid) {
;     ...
;         for (int t = 0; t < nt; t += 2) {
;             const bool last = (t == nt - 2);
;             const char* a1 = cA + (size_t)(t + 1) * kstep;
;             const char* a2 = last ? nA : cA + (size_t)(t + 2) * kstep; const char* b2 = last ? nB : cB + (size_t)(t + 2) * kstep;
;             const char* a3 = a2 + kstep; const char* b3 = b2 + kstep;
;             PG8_LDB(B0, 0, 0); PG8_LDB(B1, 0, 1); PG8_SCHED; PG8_LDA(At, 0, 0); PG8_STAGE(PG8_SA(1, 1), a1 + hA, voffA);
;             PG8_WAIT_V(8); PG8_WAIT_L(0); PG8_BAR; PG8_MMA(0, 0, At, B0); PG8_MMA(0, 1, At, B1); PG8_BAR; PG8_SCHED;
;             PG8_LDA(At, 0, 1); PG8_STAGE(PG8_SB(0, 0), b2, voffB); PG8_STAGE(PG8_SB(0, 1), b2 + hB, voffB); PG8_STAGE(PG8_SA(0, 0), a2, voffA);
;             PG8_WAIT_V(8); PG8_WAIT_L(0); PG8_BAR; PG8_MMA(1, 0, At, B0); PG8_MMA(1, 1, At, B1); PG8_BAR; PG8_SCHED;
.LBB0_1142:
	s_add_u32 s17, s22, 0x100
	s_addc_u32 vcc_lo, s23, 0
	s_mov_b32 vcc_hi, -2
	s_add_u32 s22, s20, 0x100
	s_addc_u32 s23, s21, 0
	s_add_i32 s43, 0, 0x10000
	s_cmp_eq_u32 vcc_hi, 12
	s_cselect_b32 s75, s7, s23
	s_cselect_b32 s74, s6, s22
	s_cselect_b32 s73, s19, vcc_lo
	s_cselect_b32 s72, s18, s17
	s_add_i32 s44, 0, 0x14000
	v_add_u32_e32 v100, s43, v159
	v_add_u32_e32 v170, s44, v159
	ds_read_b128 v[64:67], v100
	ds_read_b128 v[68:71], v100 offset:1024
	ds_read_b128 v[72:75], v100 offset:2048
	ds_read_b128 v[100:103], v100 offset:3072
	ds_read_b128 v[154:157], v170
	ds_read_b128 v[162:165], v170 offset:1024
	ds_read_b128 v[166:169], v170 offset:2048
	ds_read_b128 v[170:173], v170 offset:3072
	v_lshl_add_u64 v[190:191], s[20:21], 0, v[150:151]
	s_add_i32 m0, s80, 0xc000
	ds_read_b128 v[174:177], v161
	ds_read_b128 v[178:181], v161 offset:1024
	ds_read_b128 v[182:185], v161 offset:2048
	ds_read_b128 v[186:189], v161 offset:3072
	ds_read_b128 v[194:197], v161 offset:4096
	ds_read_b128 v[198:201], v161 offset:5120
	ds_read_b128 v[204:207], v161 offset:6144
	ds_read_b128 v[208:211], v161 offset:7168
	global_load_lds_dwordx4 v[190:191], off
	v_lshl_add_u64 v[190:191], s[20:21], 0, v[152:153]
	s_add_i32 m0, s80, 0xe000
	s_nop 0
	global_load_lds_dwordx4 v[190:191], off
	s_waitcnt vmcnt(8)
	s_waitcnt lgkmcnt(0)
	s_barrier
	s_setprio 1
	s_waitcnt lgkmcnt(0)
	v_mfma_f32_16x16x32_bf16 v[140:143], v[64:67], v[174:177], 0
	v_mfma_f32_16x16x32_bf16 v[136:139], v[72:75], v[174:177], 0
	v_mfma_f32_16x16x32_bf16 v[132:135], v[64:67], v[182:185], 0
	v_mfma_f32_16x16x32_bf16 v[120:123], v[72:75], v[182:185], 0
	v_mfma_f32_16x16x32_bf16 v[108:111], v[64:67], v[194:197], 0
	v_mfma_f32_16x16x32_bf16 v[104:107], v[72:75], v[194:197], 0
	v_mfma_f32_16x16x32_bf16 v[96:99], v[64:67], v[204:207], 0
	v_mfma_f32_16x16x32_bf16 v[84:87], v[72:75], v[204:207], 0
	v_mfma_f32_16x16x32_bf16 v[140:143], v[68:71], v[178:181], v[140:143]
	v_mfma_f32_16x16x32_bf16 v[136:139], v[100:103], v[178:181], v[136:139]
	v_mfma_f32_16x16x32_bf16 v[132:135], v[68:71], v[186:189], v[132:135]
	v_mfma_f32_16x16x32_bf16 v[120:123], v[100:103], v[186:189], v[120:123]
	v_mfma_f32_16x16x32_bf16 v[108:111], v[68:71], v[198:201], v[108:111]
	v_mfma_f32_16x16x32_bf16 v[104:107], v[100:103], v[198:201], v[104:107]
	v_mfma_f32_16x16x32_bf16 v[96:99], v[68:71], v[208:211], v[96:99]
	v_mfma_f32_16x16x32_bf16 v[84:87], v[100:103], v[208:211], v[84:87]
	s_setprio 0
	s_setprio 1
	v_mfma_f32_16x16x32_bf16 v[128:131], v[154:157], v[174:177], 0
	v_mfma_f32_16x16x32_bf16 v[124:127], v[166:169], v[174:177], 0
	v_mfma_f32_16x16x32_bf16 v[116:119], v[154:157], v[182:185], 0
	v_mfma_f32_16x16x32_bf16 v[112:115], v[166:169], v[182:185], 0
	v_mfma_f32_16x16x32_bf16 v[92:95], v[154:157], v[194:197], 0
	v_mfma_f32_16x16x32_bf16 v[88:91], v[166:169], v[194:197], 0
	v_mfma_f32_16x16x32_bf16 v[80:83], v[154:157], v[204:207], 0
	v_mfma_f32_16x16x32_bf16 v[76:79], v[166:169], v[204:207], 0
	v_mfma_f32_16x16x32_bf16 v[128:131], v[162:165], v[178:181], v[128:131]
	v_mfma_f32_16x16x32_bf16 v[124:127], v[170:173], v[178:181], v[124:127]
	v_mfma_f32_16x16x32_bf16 v[116:119], v[162:165], v[186:189], v[116:119]
	v_mfma_f32_16x16x32_bf16 v[112:115], v[170:173], v[186:189], v[112:115]
	v_mfma_f32_16x16x32_bf16 v[92:95], v[162:165], v[198:201], v[92:95]
	v_mfma_f32_16x16x32_bf16 v[88:91], v[170:173], v[198:201], v[88:91]
	v_mfma_f32_16x16x32_bf16 v[80:83], v[162:165], v[208:211], v[80:83]
	v_mfma_f32_16x16x32_bf16 v[76:79], v[170:173], v[208:211], v[76:79]
	s_setprio 0
	s_barrier
	s_add_i32 s20, s43, s76
	v_lshl_add_u64 v[190:191], s[72:73], 0, v[192:193]
	s_mov_b32 m0, s20
	ds_read_b128 v[174:177], v161 offset:16384
	ds_read_b128 v[178:181], v161 offset:17408
	ds_read_b128 v[182:185], v161 offset:18432
	ds_read_b128 v[186:189], v161 offset:19456
	ds_read_b128 v[194:197], v161 offset:20480
	ds_read_b128 v[198:201], v161 offset:21504
	ds_read_b128 v[204:207], v161 offset:22528
	ds_read_b128 v[208:211], v161 offset:23552
	global_load_lds_dwordx4 v[190:191], off
	s_add_i32 m0, s20, 0x2000
	s_add_u32 s20, s72, 0x40000
	v_lshl_add_u64 v[212:213], s[72:73], 0, v[144:145]
	s_addc_u32 s21, s73, 0
	s_add_i32 s43, s44, s76
	global_load_lds_dwordx4 v[212:213], off
	v_lshl_add_u64 v[214:215], s[20:21], 0, v[192:193]
	s_mov_b32 m0, s43
	v_lshl_add_u64 v[216:217], s[74:75], 0, v[146:147]
	global_load_lds_dwordx4 v[214:215], off
	v_lshl_add_u64 v[214:215], s[20:21], 0, v[144:145]
	s_add_i32 m0, s43, 0x2000
	s_nop 0
	global_load_lds_dwordx4 v[214:215], off
	v_lshl_add_u64 v[214:215], s[74:75], 0, v[148:149]
	s_mov_b32 m0, s80
	s_nop 0
	global_load_lds_dwordx4 v[214:215], off
	s_mov_b32 m0, s81
	s_nop 0
	global_load_lds_dwordx4 v[216:217], off
	s_waitcnt vmcnt(8)
	s_waitcnt lgkmcnt(0)
	s_barrier
; #define PG8_STAGE(bufoff, gbase, voff) do { _Pragma("unroll") for (int _i = 0; _i < 2; ++_i) \
;         __builtin_amdgcn_global_load_lds((const unsigned*)((const char*)(gbase) + (voff)[_i]), (LAS unsigned*)(lds + (bufoff) + ldsw + _i * 8192), 16, 0, 0); } while (0)
; #define PG8_LDA(dst, b, h) do { _Pragma("unroll") for (int m = 0; m < 4; ++m) _Pragma("unroll") for (int k = 0; k < 2; ++k) dst[m][k] = *(const LAS bf16x8*)(lds + PG8_SA(b, h) + aoff + m * 2048 + k * 1024); } while (0)
; #define PG8_LDB(dst, b, h) do { _Pragma("unroll") for (int n = 0; n < 2; ++n) _Pragma("unroll") for (int k = 0; k < 2; ++k) dst[n][k] = *(const LAS bf16x8*)(lds + PG8_SB(b, h) + boff + n * 2048 + k * 1024); } while (0)
; #define PG8_MMA(ai, bj, At, Bt) do { __builtin_amdgcn_s_setprio(1); _Pragma("unroll") for (int m = 0; m < 4; ++m) _Pragma("unroll") for (int n = 0; n < 2; ++n) _Pragma("unroll") for (int k = 0; k < 2; ++k) \
;         acc[ai][bj][m][n] = __builtin_amdgcn_mfma_f32_16x16x32_bf16(Bt[n][k], At[m][k], acc[ai][bj][m][n], 0, 0, 0); __builtin_amdgcn_s_setprio(0); } while (0)
; #define PG8_WAIT_V(n) asm volatile("s_waitcnt vmcnt(" #n ")" ::: "memory")
; #define PG8_WAIT_L(n) asm volatile("s_waitcnt lgkmcnt(" #n ")" ::: "memory")
; #define PG8_BAR __builtin_amdgcn_s_barrier()
; #define PG8_SCHED __builtin_amdgcn_sched_barrier(0)
; template <class Epi>
; __device__ __forceinline__ void gemm_phase(LAS unsigned char* lds, const Gemm g, const Sched& S, const Epi& E, const int tid) {
;     ...
;             PG8_WAIT_V(8); PG8_WAIT_L(0); PG8_BAR; PG8_MMA(1, 0, At, B0); PG8_MMA(1, 1, At, B1); PG8_BAR; PG8_SCHED;
;             PG8_LDB(B0, 1, 0); PG8_LDB(B1, 1, 1); PG8_SCHED; PG8_LDA(At, 1, 0); PG8_STAGE(PG8_SA(0, 1), a2 + hA, voffA);
;             PG8_WAIT_V(8); PG8_WAIT_L(0); PG8_BAR; PG8_MMA(0, 0, At, B0); PG8_MMA(0, 1, At, B1); PG8_BAR; PG8_SCHED;
	s_setprio 1
	s_waitcnt lgkmcnt(0)
	v_mfma_f32_16x16x32_bf16 v[60:63], v[64:67], v[174:177], 0
	v_mfma_f32_16x16x32_bf16 v[56:59], v[72:75], v[174:177], 0
	v_mfma_f32_16x16x32_bf16 v[52:55], v[64:67], v[182:185], 0
	v_mfma_f32_16x16x32_bf16 v[40:43], v[72:75], v[182:185], 0
	v_mfma_f32_16x16x32_bf16 v[28:31], v[64:67], v[194:197], 0
	v_mfma_f32_16x16x32_bf16 v[24:27], v[72:75], v[194:197], 0
	v_mfma_f32_16x16x32_bf16 v[20:23], v[64:67], v[204:207], 0
	v_mfma_f32_16x16x32_bf16 v[8:11], v[72:75], v[204:207], 0
	v_mfma_f32_16x16x32_bf16 v[60:63], v[68:71], v[178:181], v[60:63]
	v_mfma_f32_16x16x32_bf16 v[56:59], v[100:103], v[178:181], v[56:59]
	v_mfma_f32_16x16x32_bf16 v[52:55], v[68:71], v[186:189], v[52:55]
	v_mfma_f32_16x16x32_bf16 v[40:43], v[100:103], v[186:189], v[40:43]
	v_mfma_f32_16x16x32_bf16 v[28:31], v[68:71], v[198:201], v[28:31]
	v_mfma_f32_16x16x32_bf16 v[24:27], v[100:103], v[198:201], v[24:27]
	v_mfma_f32_16x16x32_bf16 v[20:23], v[68:71], v[208:211], v[20:23]
	v_mfma_f32_16x16x32_bf16 v[8:11], v[100:103], v[208:211], v[8:11]
	s_setprio 0
	s_setprio 1
	v_mfma_f32_16x16x32_bf16 v[48:51], v[154:157], v[174:177], 0
	v_mfma_f32_16x16x32_bf16 v[44:47], v[166:169], v[174:177], 0
	v_mfma_f32_16x16x32_bf16 v[36:39], v[154:157], v[182:185], 0
	v_mfma_f32_16x16x32_bf16 v[32:35], v[166:169], v[182:185], 0
	v_mfma_f32_16x16x32_bf16 v[16:19], v[154:157], v[194:197], 0
	v_mfma_f32_16x16x32_bf16 v[12:15], v[166:169], v[194:197], 0
	v_mfma_f32_16x16x32_bf16 v[4:7], v[154:157], v[204:207], 0
	v_mfma_f32_16x16x32_bf16 v[0:3], v[166:169], v[204:207], 0
	v_mfma_f32_16x16x32_bf16 v[48:51], v[162:165], v[178:181], v[48:51]
	v_mfma_f32_16x16x32_bf16 v[44:47], v[170:173], v[178:181], v[44:47]
	v_mfma_f32_16x16x32_bf16 v[36:39], v[162:165], v[186:189], v[36:39]
	v_mfma_f32_16x16x32_bf16 v[32:35], v[170:173], v[186:189], v[32:35]
	v_mfma_f32_16x16x32_bf16 v[16:19], v[162:165], v[198:201], v[16:19]
	v_mfma_f32_16x16x32_bf16 v[12:15], v[170:173], v[198:201], v[12:15]
	v_mfma_f32_16x16x32_bf16 v[4:7], v[162:165], v[208:211], v[4:7]
	v_mfma_f32_16x16x32_bf16 v[0:3], v[170:173], v[208:211], v[0:3]
	s_setprio 0
	s_barrier
	s_add_i32 s43, 0, 0x18000
	s_add_i32 s44, 0, 0x1c000
	v_add_u32_e32 v100, s43, v159
	v_add_u32_e32 v170, s44, v159
	ds_read_b128 v[64:67], v100
	ds_read_b128 v[68:71], v100 offset:1024
	ds_read_b128 v[72:75], v100 offset:2048
	ds_read_b128 v[100:103], v100 offset:3072
	ds_read_b128 v[154:157], v170
	ds_read_b128 v[162:165], v170 offset:1024
	ds_read_b128 v[166:169], v170 offset:2048
	ds_read_b128 v[170:173], v170 offset:3072
	s_add_u32 s20, s74, 0x120000
	s_addc_u32 s21, s75, 0
	s_mov_b32 m0, s3
	v_lshl_add_u64 v[218:219], s[20:21], 0, v[148:149]
	ds_read_b128 v[174:177], v161 offset:32768
	ds_read_b128 v[178:181], v161 offset:33792
	ds_read_b128 v[182:185], v161 offset:34816
	ds_read_b128 v[186:189], v161 offset:35840
	ds_read_b128 v[194:197], v161 offset:36864
	ds_read_b128 v[198:201], v161 offset:37888
	ds_read_b128 v[204:207], v161 offset:38912
	ds_read_b128 v[208:211], v161 offset:39936
	global_load_lds_dwordx4 v[218:219], off
	v_lshl_add_u64 v[218:219], s[20:21], 0, v[146:147]
	s_mov_b32 m0, s34
	s_nop 0
	global_load_lds_dwordx4 v[218:219], off
	s_waitcnt vmcnt(8)
	s_waitcnt lgkmcnt(0)
	s_barrier
	s_setprio 1
	s_waitcnt lgkmcnt(0)
	v_mfma_f32_16x16x32_bf16 v[140:143], v[64:67], v[174:177], v[140:143]
	v_mfma_f32_16x16x32_bf16 v[136:139], v[72:75], v[174:177], v[136:139]
	v_mfma_f32_16x16x32_bf16 v[132:135], v[64:67], v[182:185], v[132:135]
	v_mfma_f32_16x16x32_bf16 v[120:123], v[72:75], v[182:185], v[120:123]
	v_mfma_f32_16x16x32_bf16 v[108:111], v[64:67], v[194:197], v[108:111]
	v_mfma_f32_16x16x32_bf16 v[104:107], v[72:75], v[194:197], v[104:107]
	v_mfma_f32_16x16x32_bf16 v[96:99], v[64:67], v[204:207], v[96:99]
	v_mfma_f32_16x16x32_bf16 v[84:87], v[72:75], v[204:207], v[84:87]
	v_mfma_f32_16x16x32_bf16 v[140:143], v[68:71], v[178:181], v[140:143]
	v_mfma_f32_16x16x32_bf16 v[136:139], v[100:103], v[178:181], v[136:139]
	v_mfma_f32_16x16x32_bf16 v[132:135], v[68:71], v[186:189], v[132:135]
	v_mfma_f32_16x16x32_bf16 v[120:123], v[100:103], v[186:189], v[120:123]
	v_mfma_f32_16x16x32_bf16 v[108:111], v[68:71], v[198:201], v[108:111]
	v_mfma_f32_16x16x32_bf16 v[104:107], v[100:103], v[198:201], v[104:107]
	v_mfma_f32_16x16x32_bf16 v[96:99], v[68:71], v[208:211], v[96:99]
	v_mfma_f32_16x16x32_bf16 v[84:87], v[100:103], v[208:211], v[84:87]
	s_setprio 0
	s_setprio 1
	v_mfma_f32_16x16x32_bf16 v[128:131], v[154:157], v[174:177], v[128:131]
	v_mfma_f32_16x16x32_bf16 v[124:127], v[166:169], v[174:177], v[124:127]
	v_mfma_f32_16x16x32_bf16 v[116:119], v[154:157], v[182:185], v[116:119]
	v_mfma_f32_16x16x32_bf16 v[112:115], v[166:169], v[182:185], v[112:115]
	v_mfma_f32_16x16x32_bf16 v[92:95], v[154:157], v[194:197], v[92:95]
	v_mfma_f32_16x16x32_bf16 v[88:91], v[166:169], v[194:197], v[88:91]
	v_mfma_f32_16x16x32_bf16 v[80:83], v[154:157], v[204:207], v[80:83]
	v_mfma_f32_16x16x32_bf16 v[76:79], v[166:169], v[204:207], v[76:79]
	v_mfma_f32_16x16x32_bf16 v[128:131], v[162:165], v[178:181], v[128:131]
	v_mfma_f32_16x16x32_bf16 v[124:127], v[170:173], v[178:181], v[124:127]
	v_mfma_f32_16x16x32_bf16 v[116:119], v[162:165], v[186:189], v[116:119]
	v_mfma_f32_16x16x32_bf16 v[112:115], v[170:173], v[186:189], v[112:115]
	v_mfma_f32_16x16x32_bf16 v[92:95], v[162:165], v[198:201], v[92:95]
	v_mfma_f32_16x16x32_bf16 v[88:91], v[170:173], v[198:201], v[88:91]
	v_mfma_f32_16x16x32_bf16 v[80:83], v[162:165], v[208:211], v[80:83]
	v_mfma_f32_16x16x32_bf16 v[76:79], v[170:173], v[208:211], v[76:79]
	s_setprio 0
	s_barrier
; #define PG8_STAGE(bufoff, gbase, voff) do { _Pragma("unroll") for (int _i = 0; _i < 2; ++_i) \
;         __builtin_amdgcn_global_load_lds((const unsigned*)((const char*)(gbase) + (voff)[_i]), (LAS unsigned*)(lds + (bufoff) + ldsw + _i * 8192), 16, 0, 0); } while (0)
; #define PG8_LDA(dst, b, h) do { _Pragma("unroll") for (int m = 0; m < 4; ++m) _Pragma("unroll") for (int k = 0; k < 2; ++k) dst[m][k] = *(const LAS bf16x8*)(lds + PG8_SA(b, h) + aoff + m * 2048 + k * 1024); } while (0)
; #define PG8_LDB(dst, b, h) do { _Pragma("unroll") for (int n = 0; n < 2; ++n) _Pragma("unroll") for (int k = 0; k < 2; ++k) dst[n][k] = *(const LAS bf16x8*)(lds + PG8_SB(b, h) + boff + n * 2048 + k * 1024); } while (0)
; #define PG8_MMA(ai, bj, At, Bt) do { __builtin_amdgcn_s_setprio(1); _Pragma("unroll") for (int m = 0; m < 4; ++m) _Pragma("unroll") for (int n = 0; n < 2; ++n) _Pragma("unroll") for (int k = 0; k < 2; ++k) \
;         acc[ai][bj][m][n] = __builtin_amdgcn_mfma_f32_16x16x32_bf16(Bt[n][k], At[m][k], acc[ai][bj][m][n], 0, 0, 0); __builtin_amdgcn_s_setprio(0); } while (0)
; #define PG8_WAIT_V(n) asm volatile("s_waitcnt vmcnt(" #n ")" ::: "memory")
; #define PG8_WAIT_L(n) asm volatile("s_waitcnt lgkmcnt(" #n ")" ::: "memory")
; #define PG8_BAR __builtin_amdgcn_s_barrier()
; #define PG8_SCHED __builtin_amdgcn_sched_barrier(0)
; template <class Epi>
; __device__ __forceinline__ void gemm_phase(LAS unsigned char* lds, const Gemm g, const Sched& S, const Epi& E, const int tid) {
;     ...
;         for (int t = 0; t < nt; t += 2) {
;             const bool last = (t == nt - 2);
;             const char* a1 = cA + (size_t)(t + 1) * kstep;
;             const char* a2 = last ? nA : cA + (size_t)(t + 2) * kstep; const char* b2 = last ? nB : cB + (size_t)(t + 2) * kstep;
;             const char* a3 = a2 + kstep; const char* b3 = b2 + kstep;
;             PG8_LDB(B0, 0, 0); PG8_LDB(B1, 0, 1); PG8_SCHED; PG8_LDA(At, 0, 0); PG8_STAGE(PG8_SA(1, 1), a1 + hA, voffA);
;     ...
;             PG8_LDA(At, 1, 1); PG8_STAGE(PG8_SB(1, 0), b3, voffB); PG8_STAGE(PG8_SB(1, 1), b3 + hB, voffB); PG8_STAGE(PG8_SA(1, 0), a3, voffA);
;             PG8_WAIT_V(8); PG8_WAIT_L(0); PG8_BAR; PG8_MMA(1, 0, At, B0); PG8_MMA(1, 1, At, B1); PG8_BAR; PG8_SCHED;
	s_add_i32 s20, s43, s76
	v_lshl_add_u64 v[190:191], v[190:191], 0, s[94:95]
	s_mov_b32 m0, s20
	ds_read_b128 v[174:177], v161 offset:49152
	ds_read_b128 v[178:181], v161 offset:50176
	ds_read_b128 v[182:185], v161 offset:51200
	ds_read_b128 v[186:189], v161 offset:52224
	ds_read_b128 v[194:197], v161 offset:53248
	ds_read_b128 v[198:201], v161 offset:54272
	ds_read_b128 v[204:207], v161 offset:55296
	ds_read_b128 v[208:211], v161 offset:56320
	global_load_lds_dwordx4 v[190:191], off
	s_add_i32 m0, s20, 0x2000
	s_add_u32 s20, s72, 0x40080
	v_lshl_add_u64 v[190:191], v[212:213], 0, s[94:95]
	s_addc_u32 s21, s73, 0
	s_add_i32 s43, s44, s76
	global_load_lds_dwordx4 v[190:191], off
	v_lshl_add_u64 v[190:191], s[20:21], 0, v[192:193]
	s_mov_b32 m0, s43
	s_nop 0
	global_load_lds_dwordx4 v[190:191], off
	v_lshl_add_u64 v[190:191], s[20:21], 0, v[144:145]
	s_add_i32 m0, s43, 0x2000
	s_nop 0
	global_load_lds_dwordx4 v[190:191], off
	v_lshl_add_u64 v[190:191], v[214:215], 0, s[94:95]
	s_mov_b32 m0, s47
	s_nop 0
	global_load_lds_dwordx4 v[190:191], off
	v_lshl_add_u64 v[190:191], v[216:217], 0, s[94:95]
	s_mov_b32 m0, s40
	s_nop 0
	global_load_lds_dwordx4 v[190:191], off
	s_waitcnt vmcnt(8)
	s_waitcnt lgkmcnt(0)
	s_barrier
	s_setprio 1
	s_waitcnt lgkmcnt(0)
	v_mfma_f32_16x16x32_bf16 v[60:63], v[64:67], v[174:177], v[60:63]
	v_mfma_f32_16x16x32_bf16 v[56:59], v[72:75], v[174:177], v[56:59]
	v_mfma_f32_16x16x32_bf16 v[52:55], v[64:67], v[182:185], v[52:55]
	v_mfma_f32_16x16x32_bf16 v[40:43], v[72:75], v[182:185], v[40:43]
	v_mfma_f32_16x16x32_bf16 v[28:31], v[64:67], v[194:197], v[28:31]
	v_mfma_f32_16x16x32_bf16 v[24:27], v[72:75], v[194:197], v[24:27]
	v_mfma_f32_16x16x32_bf16 v[20:23], v[64:67], v[204:207], v[20:23]
	v_mfma_f32_16x16x32_bf16 v[8:11], v[72:75], v[204:207], v[8:11]
	v_mfma_f32_16x16x32_bf16 v[60:63], v[68:71], v[178:181], v[60:63]
	v_mfma_f32_16x16x32_bf16 v[56:59], v[100:103], v[178:181], v[56:59]
	v_mfma_f32_16x16x32_bf16 v[52:55], v[68:71], v[186:189], v[52:55]
	v_mfma_f32_16x16x32_bf16 v[40:43], v[100:103], v[186:189], v[40:43]
	v_mfma_f32_16x16x32_bf16 v[28:31], v[68:71], v[198:201], v[28:31]
	v_mfma_f32_16x16x32_bf16 v[24:27], v[100:103], v[198:201], v[24:27]
	v_mfma_f32_16x16x32_bf16 v[20:23], v[68:71], v[208:211], v[20:23]
	v_mfma_f32_16x16x32_bf16 v[8:11], v[100:103], v[208:211], v[8:11]
	s_setprio 0
	s_setprio 1
	v_mfma_f32_16x16x32_bf16 v[48:51], v[154:157], v[174:177], v[48:51]
	v_mfma_f32_16x16x32_bf16 v[44:47], v[166:169], v[174:177], v[44:47]
	v_mfma_f32_16x16x32_bf16 v[36:39], v[154:157], v[182:185], v[36:39]
	v_mfma_f32_16x16x32_bf16 v[32:35], v[166:169], v[182:185], v[32:35]
	v_mfma_f32_16x16x32_bf16 v[16:19], v[154:157], v[194:197], v[16:19]
	v_mfma_f32_16x16x32_bf16 v[12:15], v[166:169], v[194:197], v[12:15]
	v_mfma_f32_16x16x32_bf16 v[4:7], v[154:157], v[204:207], v[4:7]
	v_mfma_f32_16x16x32_bf16 v[0:3], v[166:169], v[204:207], v[0:3]
	v_mfma_f32_16x16x32_bf16 v[48:51], v[162:165], v[178:181], v[48:51]
	v_mfma_f32_16x16x32_bf16 v[44:47], v[170:173], v[178:181], v[44:47]
	v_mfma_f32_16x16x32_bf16 v[36:39], v[162:165], v[186:189], v[36:39]
	v_mfma_f32_16x16x32_bf16 v[32:35], v[170:173], v[186:189], v[32:35]
	v_mfma_f32_16x16x32_bf16 v[16:19], v[162:165], v[198:201], v[16:19]
	v_mfma_f32_16x16x32_bf16 v[12:15], v[170:173], v[198:201], v[12:15]
	v_mfma_f32_16x16x32_bf16 v[4:7], v[162:165], v[208:211], v[4:7]
	v_mfma_f32_16x16x32_bf16 v[0:3], v[170:173], v[208:211], v[0:3]
	s_add_i32 vcc_hi, vcc_hi, 2
	s_add_u32 s17, s17, 0x100
	s_addc_u32 vcc_lo, vcc_lo, 0
	s_cmp_gt_u32 vcc_hi, 13
	s_mov_b64 s[20:21], s[22:23]
	s_setprio 0
	s_barrier
	s_cbranch_scc1 .Lgk_exit_3
.LBB0_1143:
	s_add_u32 s22, s20, 0x100
	s_addc_u32 s23, s21, 0
	s_add_i32 s43, 0, 0x10000
	s_cmp_eq_u32 vcc_hi, 12
	s_cselect_b32 s75, s7, s23
	s_cselect_b32 s74, s6, s22
	s_cselect_b32 s73, s19, vcc_lo
	s_cselect_b32 s72, s18, s17
	s_add_i32 s44, 0, 0x14000
	v_add_u32_e32 v100, s43, v159
	v_add_u32_e32 v170, s44, v159
	ds_read_b128 v[64:67], v100
	ds_read_b128 v[68:71], v100 offset:1024
	ds_read_b128 v[72:75], v100 offset:2048
	ds_read_b128 v[100:103], v100 offset:3072
	ds_read_b128 v[154:157], v170
	ds_read_b128 v[162:165], v170 offset:1024
	ds_read_b128 v[166:169], v170 offset:2048
	ds_read_b128 v[170:173], v170 offset:3072
	v_lshl_add_u64 v[190:191], s[20:21], 0, v[150:151]
	s_add_i32 m0, s80, 0xc000
	ds_read_b128 v[174:177], v161
	ds_read_b128 v[178:181], v161 offset:1024
	ds_read_b128 v[182:185], v161 offset:2048
	ds_read_b128 v[186:189], v161 offset:3072
	ds_read_b128 v[194:197], v161 offset:4096
	ds_read_b128 v[198:201], v161 offset:5120
	ds_read_b128 v[204:207], v161 offset:6144
	ds_read_b128 v[208:211], v161 offset:7168
	global_load_lds_dwordx4 v[190:191], off
	v_lshl_add_u64 v[190:191], s[20:21], 0, v[152:153]
	s_add_i32 m0, s80, 0xe000
	s_nop 0
	global_load_lds_dwordx4 v[190:191], off
	s_waitcnt vmcnt(8)
	s_waitcnt lgkmcnt(0)
	s_barrier
; #define PG8_STAGE(bufoff, gbase, voff) do { _Pragma("unroll") for (int _i = 0; _i < 2; ++_i) \
;         __builtin_amdgcn_global_load_lds((const unsigned*)((const char*)(gbase) + (voff)[_i]), (LAS unsigned*)(lds + (bufoff) + ldsw + _i * 8192), 16, 0, 0); } while (0)
; #define PG8_LDA(dst, b, h) do { _Pragma("unroll") for (int m = 0; m < 4; ++m) _Pragma("unroll") for (int k = 0; k < 2; ++k) dst[m][k] = *(const LAS bf16x8*)(lds + PG8_SA(b, h) + aoff + m * 2048 + k * 1024); } while (0)
; #define PG8_MMA(ai, bj, At, Bt) do { __builtin_amdgcn_s_setprio(1); _Pragma("unroll") for (int m = 0; m < 4; ++m) _Pragma("unroll") for (int n = 0; n < 2; ++n) _Pragma("unroll") for (int k = 0; k < 2; ++k) \
;         acc[ai][bj][m][n] = __builtin_amdgcn_mfma_f32_16x16x32_bf16(Bt[n][k], At[m][k], acc[ai][bj][m][n], 0, 0, 0); __builtin_amdgcn_s_setprio(0); } while (0)
; #define PG8_WAIT_V(n) asm volatile("s_waitcnt vmcnt(" #n ")" ::: "memory")
; #define PG8_WAIT_L(n) asm volatile("s_waitcnt lgkmcnt(" #n ")" ::: "memory")
; #define PG8_BAR __builtin_amdgcn_s_barrier()
; #define PG8_SCHED __builtin_amdgcn_sched_barrier(0)
; template <class Epi>
; __device__ __forceinline__ void gemm_phase(LAS unsigned char* lds, const Gemm g, const Sched& S, const Epi& E, const int tid) {
;     ...
;             PG8_WAIT_V(8); PG8_WAIT_L(0); PG8_BAR; PG8_MMA(0, 0, At, B0); PG8_MMA(0, 1, At, B1); PG8_BAR; PG8_SCHED;
;             PG8_LDA(At, 0, 1); PG8_STAGE(PG8_SB(0, 0), b2, voffB); PG8_STAGE(PG8_SB(0, 1), b2 + hB, voffB); PG8_STAGE(PG8_SA(0, 0), a2, voffA);
;             PG8_WAIT_V(8); PG8_WAIT_L(0); PG8_BAR; PG8_MMA(1, 0, At, B0); PG8_MMA(1, 1, At, B1); PG8_BAR; PG8_SCHED;
	s_setprio 1
	s_waitcnt lgkmcnt(0)
	v_mfma_f32_16x16x32_bf16 v[140:143], v[64:67], v[174:177], v[140:143]
	v_mfma_f32_16x16x32_bf16 v[136:139], v[72:75], v[174:177], v[136:139]
	v_mfma_f32_16x16x32_bf16 v[132:135], v[64:67], v[182:185], v[132:135]
	v_mfma_f32_16x16x32_bf16 v[120:123], v[72:75], v[182:185], v[120:123]
	v_mfma_f32_16x16x32_bf16 v[108:111], v[64:67], v[194:197], v[108:111]
	v_mfma_f32_16x16x32_bf16 v[104:107], v[72:75], v[194:197], v[104:107]
	v_mfma_f32_16x16x32_bf16 v[96:99], v[64:67], v[204:207], v[96:99]
	v_mfma_f32_16x16x32_bf16 v[84:87], v[72:75], v[204:207], v[84:87]
	v_mfma_f32_16x16x32_bf16 v[140:143], v[68:71], v[178:181], v[140:143]
	v_mfma_f32_16x16x32_bf16 v[136:139], v[100:103], v[178:181], v[136:139]
	v_mfma_f32_16x16x32_bf16 v[132:135], v[68:71], v[186:189], v[132:135]
	v_mfma_f32_16x16x32_bf16 v[120:123], v[100:103], v[186:189], v[120:123]
	v_mfma_f32_16x16x32_bf16 v[108:111], v[68:71], v[198:201], v[108:111]
	v_mfma_f32_16x16x32_bf16 v[104:107], v[100:103], v[198:201], v[104:107]
	v_mfma_f32_16x16x32_bf16 v[96:99], v[68:71], v[208:211], v[96:99]
	v_mfma_f32_16x16x32_bf16 v[84:87], v[100:103], v[208:211], v[84:87]
	s_setprio 0
	s_setprio 1
	v_mfma_f32_16x16x32_bf16 v[128:131], v[154:157], v[174:177], v[128:131]
	v_mfma_f32_16x16x32_bf16 v[124:127], v[166:169], v[174:177], v[124:127]
	v_mfma_f32_16x16x32_bf16 v[116:119], v[154:157], v[182:185], v[116:119]
	v_mfma_f32_16x16x32_bf16 v[112:115], v[166:169], v[182:185], v[112:115]
	v_mfma_f32_16x16x32_bf16 v[92:95], v[154:157], v[194:197], v[92:95]
	v_mfma_f32_16x16x32_bf16 v[88:91], v[166:169], v[194:197], v[88:91]
	v_mfma_f32_16x16x32_bf16 v[80:83], v[154:157], v[204:207], v[80:83]
	v_mfma_f32_16x16x32_bf16 v[76:79], v[166:169], v[204:207], v[76:79]
	v_mfma_f32_16x16x32_bf16 v[128:131], v[162:165], v[178:181], v[128:131]
	v_mfma_f32_16x16x32_bf16 v[124:127], v[170:173], v[178:181], v[124:127]
	v_mfma_f32_16x16x32_bf16 v[116:119], v[162:165], v[186:189], v[116:119]
	v_mfma_f32_16x16x32_bf16 v[112:115], v[170:173], v[186:189], v[112:115]
	v_mfma_f32_16x16x32_bf16 v[92:95], v[162:165], v[198:201], v[92:95]
	v_mfma_f32_16x16x32_bf16 v[88:91], v[170:173], v[198:201], v[88:91]
	v_mfma_f32_16x16x32_bf16 v[80:83], v[162:165], v[208:211], v[80:83]
	v_mfma_f32_16x16x32_bf16 v[76:79], v[170:173], v[208:211], v[76:79]
	s_setprio 0
	s_barrier
	s_add_i32 s20, s43, s76
	v_lshl_add_u64 v[190:191], s[72:73], 0, v[192:193]
	s_mov_b32 m0, s20
	ds_read_b128 v[174:177], v161 offset:16384
	ds_read_b128 v[178:181], v161 offset:17408
	ds_read_b128 v[182:185], v161 offset:18432
	ds_read_b128 v[186:189], v161 offset:19456
	ds_read_b128 v[194:197], v161 offset:20480
	ds_read_b128 v[198:201], v161 offset:21504
	ds_read_b128 v[204:207], v161 offset:22528
	ds_read_b128 v[208:211], v161 offset:23552
	global_load_lds_dwordx4 v[190:191], off
	s_add_i32 m0, s20, 0x2000
	s_add_u32 s20, s72, 0x40000
	v_lshl_add_u64 v[212:213], s[72:73], 0, v[144:145]
	s_addc_u32 s21, s73, 0
	s_add_i32 s43, s44, s76
	global_load_lds_dwordx4 v[212:213], off
	v_lshl_add_u64 v[214:215], s[20:21], 0, v[192:193]
	s_mov_b32 m0, s43
	v_lshl_add_u64 v[216:217], s[74:75], 0, v[146:147]
	global_load_lds_dwordx4 v[214:215], off
	v_lshl_add_u64 v[214:215], s[20:21], 0, v[144:145]
	s_add_i32 m0, s43, 0x2000
	s_nop 0
	global_load_lds_dwordx4 v[214:215], off
	v_lshl_add_u64 v[214:215], s[74:75], 0, v[148:149]
	s_mov_b32 m0, s80
	s_nop 0
	global_load_lds_dwordx4 v[214:215], off
	s_mov_b32 m0, s81
	s_nop 0
	global_load_lds_dwordx4 v[216:217], off
	s_waitcnt vmcnt(8)
	s_waitcnt lgkmcnt(0)
	s_barrier
	s_setprio 1
	s_waitcnt lgkmcnt(0)
	v_mfma_f32_16x16x32_bf16 v[60:63], v[64:67], v[174:177], v[60:63]
	v_mfma_f32_16x16x32_bf16 v[56:59], v[72:75], v[174:177], v[56:59]
	v_mfma_f32_16x16x32_bf16 v[52:55], v[64:67], v[182:185], v[52:55]
	v_mfma_f32_16x16x32_bf16 v[40:43], v[72:75], v[182:185], v[40:43]
	v_mfma_f32_16x16x32_bf16 v[28:31], v[64:67], v[194:197], v[28:31]
	v_mfma_f32_16x16x32_bf16 v[24:27], v[72:75], v[194:197], v[24:27]
	v_mfma_f32_16x16x32_bf16 v[20:23], v[64:67], v[204:207], v[20:23]
	v_mfma_f32_16x16x32_bf16 v[8:11], v[72:75], v[204:207], v[8:11]
	v_mfma_f32_16x16x32_bf16 v[60:63], v[68:71], v[178:181], v[60:63]
	v_mfma_f32_16x16x32_bf16 v[56:59], v[100:103], v[178:181], v[56:59]
	v_mfma_f32_16x16x32_bf16 v[52:55], v[68:71], v[186:189], v[52:55]
	v_mfma_f32_16x16x32_bf16 v[40:43], v[100:103], v[186:189], v[40:43]
	v_mfma_f32_16x16x32_bf16 v[28:31], v[68:71], v[198:201], v[28:31]
	v_mfma_f32_16x16x32_bf16 v[24:27], v[100:103], v[198:201], v[24:27]
	v_mfma_f32_16x16x32_bf16 v[20:23], v[68:71], v[208:211], v[20:23]
	v_mfma_f32_16x16x32_bf16 v[8:11], v[100:103], v[208:211], v[8:11]
	s_setprio 0
	s_setprio 1
	v_mfma_f32_16x16x32_bf16 v[48:51], v[154:157], v[174:177], v[48:51]
	v_mfma_f32_16x16x32_bf16 v[44:47], v[166:169], v[174:177], v[44:47]
	v_mfma_f32_16x16x32_bf16 v[36:39], v[154:157], v[182:185], v[36:39]
	v_mfma_f32_16x16x32_bf16 v[32:35], v[166:169], v[182:185], v[32:35]
	v_mfma_f32_16x16x32_bf16 v[16:19], v[154:157], v[194:197], v[16:19]
	v_mfma_f32_16x16x32_bf16 v[12:15], v[166:169], v[194:197], v[12:15]
	v_mfma_f32_16x16x32_bf16 v[4:7], v[154:157], v[204:207], v[4:7]
	v_mfma_f32_16x16x32_bf16 v[0:3], v[166:169], v[204:207], v[0:3]
	v_mfma_f32_16x16x32_bf16 v[48:51], v[162:165], v[178:181], v[48:51]
	v_mfma_f32_16x16x32_bf16 v[44:47], v[170:173], v[178:181], v[44:47]
	v_mfma_f32_16x16x32_bf16 v[36:39], v[162:165], v[186:189], v[36:39]
	v_mfma_f32_16x16x32_bf16 v[32:35], v[170:173], v[186:189], v[32:35]
	v_mfma_f32_16x16x32_bf16 v[16:19], v[162:165], v[198:201], v[16:19]
	v_mfma_f32_16x16x32_bf16 v[12:15], v[170:173], v[198:201], v[12:15]
	v_mfma_f32_16x16x32_bf16 v[4:7], v[162:165], v[208:211], v[4:7]
	v_mfma_f32_16x16x32_bf16 v[0:3], v[170:173], v[208:211], v[0:3]
	s_setprio 0
	s_barrier
; #define PG8_STAGE(bufoff, gbase, voff) do { _Pragma("unroll") for (int _i = 0; _i < 2; ++_i) \
;         __builtin_amdgcn_global_load_lds((const unsigned*)((const char*)(gbase) + (voff)[_i]), (LAS unsigned*)(lds + (bufoff) + ldsw + _i * 8192), 16, 0, 0); } while (0)
; #define PG8_LDA(dst, b, h) do { _Pragma("unroll") for (int m = 0; m < 4; ++m) _Pragma("unroll") for (int k = 0; k < 2; ++k) dst[m][k] = *(const LAS bf16x8*)(lds + PG8_SA(b, h) + aoff + m * 2048 + k * 1024); } while (0)
; #define PG8_LDB(dst, b, h) do { _Pragma("unroll") for (int n = 0; n < 2; ++n) _Pragma("unroll") for (int k = 0; k < 2; ++k) dst[n][k] = *(const LAS bf16x8*)(lds + PG8_SB(b, h) + boff + n * 2048 + k * 1024); } while (0)
; #define PG8_MMA(ai, bj, At, Bt) do { __builtin_amdgcn_s_setprio(1); _Pragma("unroll") for (int m = 0; m < 4; ++m) _Pragma("unroll") for (int n = 0; n < 2; ++n) _Pragma("unroll") for (int k = 0; k < 2; ++k) \
;         acc[ai][bj][m][n] = __builtin_amdgcn_mfma_f32_16x16x32_bf16(Bt[n][k], At[m][k], acc[ai][bj][m][n], 0, 0, 0); __builtin_amdgcn_s_setprio(0); } while (0)
; #define PG8_WAIT_V(n) asm volatile("s_waitcnt vmcnt(" #n ")" ::: "memory")
; #define PG8_WAIT_L(n) asm volatile("s_waitcnt lgkmcnt(" #n ")" ::: "memory")
; #define PG8_BAR __builtin_amdgcn_s_barrier()
; #define PG8_SCHED __builtin_amdgcn_sched_barrier(0)
; template <class Epi>
; __device__ __forceinline__ void gemm_phase(LAS unsigned char* lds, const Gemm g, const Sched& S, const Epi& E, const int tid) {
;     ...
;             PG8_LDB(B0, 1, 0); PG8_LDB(B1, 1, 1); PG8_SCHED; PG8_LDA(At, 1, 0); PG8_STAGE(PG8_SA(0, 1), a2 + hA, voffA);
;             PG8_WAIT_V(8); PG8_WAIT_L(0); PG8_BAR; PG8_MMA(0, 0, At, B0); PG8_MMA(0, 1, At, B1); PG8_BAR; PG8_SCHED;
	s_add_i32 s43, 0, 0x18000
	s_add_i32 s44, 0, 0x1c000
	v_add_u32_e32 v100, s43, v159
	v_add_u32_e32 v170, s44, v159
	ds_read_b128 v[64:67], v100
	ds_read_b128 v[68:71], v100 offset:1024
	ds_read_b128 v[72:75], v100 offset:2048
	ds_read_b128 v[100:103], v100 offset:3072
	ds_read_b128 v[154:157], v170
	ds_read_b128 v[162:165], v170 offset:1024
	ds_read_b128 v[166:169], v170 offset:2048
	ds_read_b128 v[170:173], v170 offset:3072
	s_add_u32 s20, s74, 0x120000
	s_addc_u32 s21, s75, 0
	s_mov_b32 m0, s3
	v_lshl_add_u64 v[218:219], s[20:21], 0, v[148:149]
	ds_read_b128 v[174:177], v161 offset:32768
	ds_read_b128 v[178:181], v161 offset:33792
	ds_read_b128 v[182:185], v161 offset:34816
	ds_read_b128 v[186:189], v161 offset:35840
	ds_read_b128 v[194:197], v161 offset:36864
	ds_read_b128 v[198:201], v161 offset:37888
	ds_read_b128 v[204:207], v161 offset:38912
	ds_read_b128 v[208:211], v161 offset:39936
	global_load_lds_dwordx4 v[218:219], off
	v_lshl_add_u64 v[218:219], s[20:21], 0, v[146:147]
	s_mov_b32 m0, s34
	s_nop 0
	global_load_lds_dwordx4 v[218:219], off
	s_waitcnt vmcnt(8)
	s_waitcnt lgkmcnt(0)
	s_barrier
	s_setprio 1
	s_waitcnt lgkmcnt(0)
	v_mfma_f32_16x16x32_bf16 v[140:143], v[64:67], v[174:177], v[140:143]
	v_mfma_f32_16x16x32_bf16 v[136:139], v[72:75], v[174:177], v[136:139]
	v_mfma_f32_16x16x32_bf16 v[132:135], v[64:67], v[182:185], v[132:135]
	v_mfma_f32_16x16x32_bf16 v[120:123], v[72:75], v[182:185], v[120:123]
	v_mfma_f32_16x16x32_bf16 v[108:111], v[64:67], v[194:197], v[108:111]
	v_mfma_f32_16x16x32_bf16 v[104:107], v[72:75], v[194:197], v[104:107]
	v_mfma_f32_16x16x32_bf16 v[96:99], v[64:67], v[204:207], v[96:99]
	v_mfma_f32_16x16x32_bf16 v[84:87], v[72:75], v[204:207], v[84:87]
	v_mfma_f32_16x16x32_bf16 v[140:143], v[68:71], v[178:181], v[140:143]
	v_mfma_f32_16x16x32_bf16 v[136:139], v[100:103], v[178:181], v[136:139]
	v_mfma_f32_16x16x32_bf16 v[132:135], v[68:71], v[186:189], v[132:135]
	v_mfma_f32_16x16x32_bf16 v[120:123], v[100:103], v[186:189], v[120:123]
	v_mfma_f32_16x16x32_bf16 v[108:111], v[68:71], v[198:201], v[108:111]
	v_mfma_f32_16x16x32_bf16 v[104:107], v[100:103], v[198:201], v[104:107]
	v_mfma_f32_16x16x32_bf16 v[96:99], v[68:71], v[208:211], v[96:99]
	v_mfma_f32_16x16x32_bf16 v[84:87], v[100:103], v[208:211], v[84:87]
	s_setprio 0
	s_setprio 1
	v_mfma_f32_16x16x32_bf16 v[128:131], v[154:157], v[174:177], v[128:131]
	v_mfma_f32_16x16x32_bf16 v[124:127], v[166:169], v[174:177], v[124:127]
	v_mfma_f32_16x16x32_bf16 v[116:119], v[154:157], v[182:185], v[116:119]
	v_mfma_f32_16x16x32_bf16 v[112:115], v[166:169], v[182:185], v[112:115]
	v_mfma_f32_16x16x32_bf16 v[92:95], v[154:157], v[194:197], v[92:95]
	v_mfma_f32_16x16x32_bf16 v[88:91], v[166:169], v[194:197], v[88:91]
	v_mfma_f32_16x16x32_bf16 v[80:83], v[154:157], v[204:207], v[80:83]
	v_mfma_f32_16x16x32_bf16 v[76:79], v[166:169], v[204:207], v[76:79]
	v_mfma_f32_16x16x32_bf16 v[128:131], v[162:165], v[178:181], v[128:131]
	v_mfma_f32_16x16x32_bf16 v[124:127], v[170:173], v[178:181], v[124:127]
	v_mfma_f32_16x16x32_bf16 v[116:119], v[162:165], v[186:189], v[116:119]
	v_mfma_f32_16x16x32_bf16 v[112:115], v[170:173], v[186:189], v[112:115]
	v_mfma_f32_16x16x32_bf16 v[92:95], v[162:165], v[198:201], v[92:95]
	v_mfma_f32_16x16x32_bf16 v[88:91], v[170:173], v[198:201], v[88:91]
	v_mfma_f32_16x16x32_bf16 v[80:83], v[162:165], v[208:211], v[80:83]
	v_mfma_f32_16x16x32_bf16 v[76:79], v[170:173], v[208:211], v[76:79]
	s_setprio 0
	s_barrier
; #define PG8_STAGE(bufoff, gbase, voff) do { _Pragma("unroll") for (int _i = 0; _i < 2; ++_i) \
;         __builtin_amdgcn_global_load_lds((const unsigned*)((const char*)(gbase) + (voff)[_i]), (LAS unsigned*)(lds + (bufoff) + ldsw + _i * 8192), 16, 0, 0); } while (0)
; #define PG8_LDA(dst, b, h) do { _Pragma("unroll") for (int m = 0; m < 4; ++m) _Pragma("unroll") for (int k = 0; k < 2; ++k) dst[m][k] = *(const LAS bf16x8*)(lds + PG8_SA(b, h) + aoff + m * 2048 + k * 1024); } while (0)
; #define PG8_MMA(ai, bj, At, Bt) do { __builtin_amdgcn_s_setprio(1); _Pragma("unroll") for (int m = 0; m < 4; ++m) _Pragma("unroll") for (int n = 0; n < 2; ++n) _Pragma("unroll") for (int k = 0; k < 2; ++k) \
;         acc[ai][bj][m][n] = __builtin_amdgcn_mfma_f32_16x16x32_bf16(Bt[n][k], At[m][k], acc[ai][bj][m][n], 0, 0, 0); __builtin_amdgcn_s_setprio(0); } while (0)
; #define PG8_WAIT_V(n) asm volatile("s_waitcnt vmcnt(" #n ")" ::: "memory")
; #define PG8_WAIT_L(n) asm volatile("s_waitcnt lgkmcnt(" #n ")" ::: "memory")
; #define PG8_BAR __builtin_amdgcn_s_barrier()
; #define PG8_SCHED __builtin_amdgcn_sched_barrier(0)
; template <class Epi>
; __device__ __forceinline__ void gemm_phase(LAS unsigned char* lds, const Gemm g, const Sched& S, const Epi& E, const int tid) {
;     ...
;             PG8_LDA(At, 1, 1); PG8_STAGE(PG8_SB(1, 0), b3, voffB); PG8_STAGE(PG8_SB(1, 1), b3 + hB, voffB); PG8_STAGE(PG8_SA(1, 0), a3, voffA);
;             PG8_WAIT_V(8); PG8_WAIT_L(0); PG8_BAR; PG8_MMA(1, 0, At, B0); PG8_MMA(1, 1, At, B1); PG8_BAR; PG8_SCHED;
;         }
	s_add_i32 s20, s43, s76
	v_lshl_add_u64 v[190:191], v[190:191], 0, s[94:95]
	s_mov_b32 m0, s20
	ds_read_b128 v[174:177], v161 offset:49152
	ds_read_b128 v[178:181], v161 offset:50176
	ds_read_b128 v[182:185], v161 offset:51200
	ds_read_b128 v[186:189], v161 offset:52224
	ds_read_b128 v[194:197], v161 offset:53248
	ds_read_b128 v[198:201], v161 offset:54272
	ds_read_b128 v[204:207], v161 offset:55296
	ds_read_b128 v[208:211], v161 offset:56320
	global_load_lds_dwordx4 v[190:191], off
	s_add_i32 m0, s20, 0x2000
	s_add_u32 s20, s72, 0x40080
	v_lshl_add_u64 v[190:191], v[212:213], 0, s[94:95]
	s_addc_u32 s21, s73, 0
	s_add_i32 s43, s44, s76
	global_load_lds_dwordx4 v[190:191], off
	v_lshl_add_u64 v[190:191], s[20:21], 0, v[192:193]
	s_mov_b32 m0, s43
	s_nop 0
	global_load_lds_dwordx4 v[190:191], off
	v_lshl_add_u64 v[190:191], s[20:21], 0, v[144:145]
	s_add_i32 m0, s43, 0x2000
	s_nop 0
	global_load_lds_dwordx4 v[190:191], off
	v_lshl_add_u64 v[190:191], v[214:215], 0, s[94:95]
	s_mov_b32 m0, s47
	s_nop 0
	global_load_lds_dwordx4 v[190:191], off
	v_lshl_add_u64 v[190:191], v[216:217], 0, s[94:95]
	s_mov_b32 m0, s40
	s_nop 0
	global_load_lds_dwordx4 v[190:191], off
	s_waitcnt vmcnt(8)
	s_waitcnt lgkmcnt(0)
	s_barrier
	s_setprio 1
	s_waitcnt lgkmcnt(0)
	v_mfma_f32_16x16x32_bf16 v[60:63], v[64:67], v[174:177], v[60:63]
	v_mfma_f32_16x16x32_bf16 v[56:59], v[72:75], v[174:177], v[56:59]
	v_mfma_f32_16x16x32_bf16 v[52:55], v[64:67], v[182:185], v[52:55]
	v_mfma_f32_16x16x32_bf16 v[40:43], v[72:75], v[182:185], v[40:43]
	v_mfma_f32_16x16x32_bf16 v[28:31], v[64:67], v[194:197], v[28:31]
	v_mfma_f32_16x16x32_bf16 v[24:27], v[72:75], v[194:197], v[24:27]
	v_mfma_f32_16x16x32_bf16 v[20:23], v[64:67], v[204:207], v[20:23]
	v_mfma_f32_16x16x32_bf16 v[8:11], v[72:75], v[204:207], v[8:11]
	v_mfma_f32_16x16x32_bf16 v[60:63], v[68:71], v[178:181], v[60:63]
	v_mfma_f32_16x16x32_bf16 v[56:59], v[100:103], v[178:181], v[56:59]
	v_mfma_f32_16x16x32_bf16 v[52:55], v[68:71], v[186:189], v[52:55]
	v_mfma_f32_16x16x32_bf16 v[40:43], v[100:103], v[186:189], v[40:43]
	v_mfma_f32_16x16x32_bf16 v[28:31], v[68:71], v[198:201], v[28:31]
	v_mfma_f32_16x16x32_bf16 v[24:27], v[100:103], v[198:201], v[24:27]
	v_mfma_f32_16x16x32_bf16 v[20:23], v[68:71], v[208:211], v[20:23]
	v_mfma_f32_16x16x32_bf16 v[8:11], v[100:103], v[208:211], v[8:11]
	s_setprio 0
	s_setprio 1
	v_mfma_f32_16x16x32_bf16 v[48:51], v[154:157], v[174:177], v[48:51]
	v_mfma_f32_16x16x32_bf16 v[44:47], v[166:169], v[174:177], v[44:47]
	v_mfma_f32_16x16x32_bf16 v[36:39], v[154:157], v[182:185], v[36:39]
	v_mfma_f32_16x16x32_bf16 v[32:35], v[166:169], v[182:185], v[32:35]
	v_mfma_f32_16x16x32_bf16 v[16:19], v[154:157], v[194:197], v[16:19]
	v_mfma_f32_16x16x32_bf16 v[12:15], v[166:169], v[194:197], v[12:15]
	v_mfma_f32_16x16x32_bf16 v[4:7], v[154:157], v[204:207], v[4:7]
	v_mfma_f32_16x16x32_bf16 v[0:3], v[166:169], v[204:207], v[0:3]
	v_mfma_f32_16x16x32_bf16 v[48:51], v[162:165], v[178:181], v[48:51]
	v_mfma_f32_16x16x32_bf16 v[44:47], v[170:173], v[178:181], v[44:47]
	v_mfma_f32_16x16x32_bf16 v[36:39], v[162:165], v[186:189], v[36:39]
	v_mfma_f32_16x16x32_bf16 v[32:35], v[170:173], v[186:189], v[32:35]
	v_mfma_f32_16x16x32_bf16 v[16:19], v[162:165], v[198:201], v[16:19]
	v_mfma_f32_16x16x32_bf16 v[12:15], v[170:173], v[198:201], v[12:15]
	v_mfma_f32_16x16x32_bf16 v[4:7], v[162:165], v[208:211], v[4:7]
	v_mfma_f32_16x16x32_bf16 v[0:3], v[170:173], v[208:211], v[0:3]
	s_add_i32 vcc_hi, vcc_hi, 2
	s_add_u32 s17, s17, 0x100
	s_addc_u32 vcc_lo, vcc_lo, 0
	s_cmp_gt_u32 vcc_hi, 13
	s_mov_b64 s[20:21], s[22:23]
	s_setprio 0
	s_barrier
	s_cbranch_scc0 .LBB0_1143

; #define PG8_STAGE(bufoff, gbase, voff) do { _Pragma("unroll") for (int _i = 0; _i < 2; ++_i) \
;         __builtin_amdgcn_global_load_lds((const unsigned*)((const char*)(gbase) + (voff)[_i]), (LAS unsigned*)(lds + (bufoff) + ldsw + _i * 8192), 16, 0, 0); } while (0)
; #define PG8_LDA(dst, b, h) do { _Pragma("unroll") for (int m = 0; m < 4; ++m) _Pragma("unroll") for (int k = 0; k < 2; ++k) dst[m][k] = *(const LAS bf16x8*)(lds + PG8_SA(b, h) + aoff + m * 2048 + k * 1024); } while (0)
; #define PG8_LDB(dst, b, h) do { _Pragma("unroll") for (int n = 0; n < 2; ++n) _Pragma("unroll") for (int k = 0; k < 2; ++k) dst[n][k] = *(const LAS bf16x8*)(lds + PG8_SB(b, h) + boff + n * 2048 + k * 1024); } while (0)
; #define PG8_MMA(ai, bj, At, Bt) do { __builtin_amdgcn_s_setprio(1); _Pragma("unroll") for (int m = 0; m < 4; ++m) _Pragma("unroll") for (int n = 0; n < 2; ++n) _Pragma("unroll") for (int k = 0; k < 2; ++k) \
;         acc[ai][bj][m][n] = __builtin_amdgcn_mfma_f32_16x16x32_bf16(Bt[n][k], At[m][k], acc[ai][bj][m][n], 0, 0, 0); __builtin_amdgcn_s_setprio(0); } while (0)
; #define PG8_WAIT_V(n) asm volatile("s_waitcnt vmcnt(" #n ")" ::: "memory")
; #define PG8_WAIT_L(n) asm volatile("s_waitcnt lgkmcnt(" #n ")" ::: "memory")
; #define PG8_BAR __builtin_amdgcn_s_barrier()
; #define PG8_SCHED __builtin_amdgcn_sched_barrier(0)
; template <class Epi>
; __device__ __forceinline__ void gemm_phase(LAS unsigned char* lds, const Gemm g, const Sched& S, const Epi& E, const int tid) {
;     ...
;         for (int t = 0; t < nt; t += 2) {
;             const bool last = (t == nt - 2);
;             const char* a1 = cA + (size_t)(t + 1) * kstep;
;             const char* a2 = last ? nA : cA + (size_t)(t + 2) * kstep; const char* b2 = last ? nB : cB + (size_t)(t + 2) * kstep;
;             const char* a3 = a2 + kstep; const char* b3 = b2 + kstep;
;             PG8_LDB(B0, 0, 0); PG8_LDB(B1, 0, 1); PG8_SCHED; PG8_LDA(At, 0, 0); PG8_STAGE(PG8_SA(1, 1), a1 + hA, voffA);
;             PG8_WAIT_V(8); PG8_WAIT_L(0); PG8_BAR; PG8_MMA(0, 0, At, B0); PG8_MMA(0, 1, At, B1); PG8_BAR; PG8_SCHED;
;             PG8_LDA(At, 0, 1); PG8_STAGE(PG8_SB(0, 0), b2, voffB); PG8_STAGE(PG8_SB(0, 1), b2 + hB, voffB); PG8_STAGE(PG8_SA(0, 0), a2, voffA);
;             PG8_WAIT_V(8); PG8_WAIT_L(0); PG8_BAR; PG8_MMA(1, 0, At, B0); PG8_MMA(1, 1, At, B1); PG8_BAR; PG8_SCHED;
.LBB0_1335:
	s_add_u32 s20, s20, 0x40080
	s_addc_u32 s21, s21, 0
	s_add_u32 s13, s22, 0x100
	s_addc_u32 s15, s23, 0
	s_mov_b32 s42, -2
	s_add_u32 s22, s20, 0xfffc0080
	s_addc_u32 s23, s21, -1
	s_add_i32 s43, 0, 0x10000
	s_cmp_eq_u32 s42, 12
	s_cselect_b32 s73, s7, s23
	s_cselect_b32 s72, s6, s22
	v_add_u32_e32 v138, s43, v141
	s_cselect_b32 s23, s17, s15
	s_cselect_b32 s22, s16, s13
	s_add_i32 s44, 0, 0x14000
	ds_read_b128 v[144:147], v138
	ds_read_b128 v[148:151], v138 offset:1024
	ds_read_b128 v[152:155], v138 offset:2048
	ds_read_b128 v[156:159], v138 offset:3072
	v_add_u32_e32 v138, s44, v141
	ds_read_b128 v[160:163], v138
	ds_read_b128 v[164:167], v138 offset:1024
	ds_read_b128 v[168:171], v138 offset:2048
	ds_read_b128 v[172:175], v138 offset:3072
	v_lshl_add_u64 v[138:139], s[20:21], 0, v[134:135]
	s_add_i32 m0, s19, 0xc000
	ds_read_b128 v[176:179], v143
	ds_read_b128 v[180:183], v143 offset:1024
	ds_read_b128 v[184:187], v143 offset:2048
	ds_read_b128 v[188:191], v143 offset:3072
	ds_read_b128 v[194:197], v143 offset:4096
	ds_read_b128 v[198:201], v143 offset:5120
	ds_read_b128 v[204:207], v143 offset:6144
	ds_read_b128 v[208:211], v143 offset:7168
	global_load_lds_dwordx4 v[138:139], off
	v_lshl_add_u64 v[138:139], s[20:21], 0, v[136:137]
	s_add_i32 m0, s19, 0xe000
	s_nop 0
	global_load_lds_dwordx4 v[138:139], off
	s_waitcnt vmcnt(8)
	s_waitcnt lgkmcnt(0)
	s_barrier
	s_setprio 1
	s_waitcnt lgkmcnt(0)
	v_mfma_f32_16x16x32_bf16 v[124:127], v[144:147], v[176:179], 0
	v_mfma_f32_16x16x32_bf16 v[120:123], v[152:155], v[176:179], 0
	v_mfma_f32_16x16x32_bf16 v[108:111], v[144:147], v[184:187], 0
	v_mfma_f32_16x16x32_bf16 v[104:107], v[152:155], v[184:187], 0
	v_mfma_f32_16x16x32_bf16 v[92:95], v[144:147], v[194:197], 0
	v_mfma_f32_16x16x32_bf16 v[88:91], v[152:155], v[194:197], 0
	v_mfma_f32_16x16x32_bf16 v[76:79], v[144:147], v[204:207], 0
	v_mfma_f32_16x16x32_bf16 v[72:75], v[152:155], v[204:207], 0
	v_mfma_f32_16x16x32_bf16 v[124:127], v[148:151], v[180:183], v[124:127]
	v_mfma_f32_16x16x32_bf16 v[120:123], v[156:159], v[180:183], v[120:123]
	v_mfma_f32_16x16x32_bf16 v[108:111], v[148:151], v[188:191], v[108:111]
	v_mfma_f32_16x16x32_bf16 v[104:107], v[156:159], v[188:191], v[104:107]
	v_mfma_f32_16x16x32_bf16 v[92:95], v[148:151], v[198:201], v[92:95]
	v_mfma_f32_16x16x32_bf16 v[88:91], v[156:159], v[198:201], v[88:91]
	v_mfma_f32_16x16x32_bf16 v[76:79], v[148:151], v[208:211], v[76:79]
	v_mfma_f32_16x16x32_bf16 v[72:75], v[156:159], v[208:211], v[72:75]
	s_setprio 0
	s_setprio 1
	v_mfma_f32_16x16x32_bf16 v[116:119], v[160:163], v[176:179], 0
	v_mfma_f32_16x16x32_bf16 v[112:115], v[168:171], v[176:179], 0
	v_mfma_f32_16x16x32_bf16 v[100:103], v[160:163], v[184:187], 0
	v_mfma_f32_16x16x32_bf16 v[96:99], v[168:171], v[184:187], 0
	v_mfma_f32_16x16x32_bf16 v[84:87], v[160:163], v[194:197], 0
	v_mfma_f32_16x16x32_bf16 v[80:83], v[168:171], v[194:197], 0
	v_mfma_f32_16x16x32_bf16 v[68:71], v[160:163], v[204:207], 0
	v_mfma_f32_16x16x32_bf16 v[64:67], v[168:171], v[204:207], 0
	v_mfma_f32_16x16x32_bf16 v[116:119], v[164:167], v[180:183], v[116:119]
	v_mfma_f32_16x16x32_bf16 v[112:115], v[172:175], v[180:183], v[112:115]
	v_mfma_f32_16x16x32_bf16 v[100:103], v[164:167], v[188:191], v[100:103]
	v_mfma_f32_16x16x32_bf16 v[96:99], v[172:175], v[188:191], v[96:99]
	v_mfma_f32_16x16x32_bf16 v[84:87], v[164:167], v[198:201], v[84:87]
	v_mfma_f32_16x16x32_bf16 v[80:83], v[172:175], v[198:201], v[80:83]
	v_mfma_f32_16x16x32_bf16 v[68:71], v[164:167], v[208:211], v[68:71]
	v_mfma_f32_16x16x32_bf16 v[64:67], v[172:175], v[208:211], v[64:67]
	s_setprio 0
	s_barrier
	s_add_i32 s43, s43, s35
	v_lshl_add_u64 v[138:139], s[22:23], 0, v[192:193]
	s_mov_b32 m0, s43
	ds_read_b128 v[176:179], v143 offset:16384
	ds_read_b128 v[180:183], v143 offset:17408
	ds_read_b128 v[184:187], v143 offset:18432
	ds_read_b128 v[188:191], v143 offset:19456
	ds_read_b128 v[194:197], v143 offset:20480
	ds_read_b128 v[198:201], v143 offset:21504
	ds_read_b128 v[204:207], v143 offset:22528
	ds_read_b128 v[208:211], v143 offset:23552
	global_load_lds_dwordx4 v[138:139], off
	s_add_i32 m0, s43, 0x2000
	s_add_u32 s76, s22, 0x40000
	v_lshl_add_u64 v[212:213], s[22:23], 0, v[128:129]
	s_addc_u32 s77, s23, 0
	s_add_i32 s43, s44, s35
	global_load_lds_dwordx4 v[212:213], off
	v_lshl_add_u64 v[214:215], s[76:77], 0, v[192:193]
	s_mov_b32 m0, s43
	v_lshl_add_u64 v[216:217], s[72:73], 0, v[130:131]
	global_load_lds_dwordx4 v[214:215], off
	v_lshl_add_u64 v[214:215], s[76:77], 0, v[128:129]
	s_add_i32 m0, s43, 0x2000
	s_nop 0
	global_load_lds_dwordx4 v[214:215], off
	v_lshl_add_u64 v[214:215], s[72:73], 0, v[132:133]
	s_mov_b32 m0, s19
	s_nop 0
	global_load_lds_dwordx4 v[214:215], off
	s_mov_b32 m0, s39
	s_nop 0
	global_load_lds_dwordx4 v[216:217], off
	s_waitcnt vmcnt(8)
	s_waitcnt lgkmcnt(0)
	s_barrier
; #define PG8_STAGE(bufoff, gbase, voff) do { _Pragma("unroll") for (int _i = 0; _i < 2; ++_i) \
;         __builtin_amdgcn_global_load_lds((const unsigned*)((const char*)(gbase) + (voff)[_i]), (LAS unsigned*)(lds + (bufoff) + ldsw + _i * 8192), 16, 0, 0); } while (0)
; #define PG8_LDA(dst, b, h) do { _Pragma("unroll") for (int m = 0; m < 4; ++m) _Pragma("unroll") for (int k = 0; k < 2; ++k) dst[m][k] = *(const LAS bf16x8*)(lds + PG8_SA(b, h) + aoff + m * 2048 + k * 1024); } while (0)
; #define PG8_LDB(dst, b, h) do { _Pragma("unroll") for (int n = 0; n < 2; ++n) _Pragma("unroll") for (int k = 0; k < 2; ++k) dst[n][k] = *(const LAS bf16x8*)(lds + PG8_SB(b, h) + boff + n * 2048 + k * 1024); } while (0)
; #define PG8_MMA(ai, bj, At, Bt) do { __builtin_amdgcn_s_setprio(1); _Pragma("unroll") for (int m = 0; m < 4; ++m) _Pragma("unroll") for (int n = 0; n < 2; ++n) _Pragma("unroll") for (int k = 0; k < 2; ++k) \
;         acc[ai][bj][m][n] = __builtin_amdgcn_mfma_f32_16x16x32_bf16(Bt[n][k], At[m][k], acc[ai][bj][m][n], 0, 0, 0); __builtin_amdgcn_s_setprio(0); } while (0)
; #define PG8_WAIT_V(n) asm volatile("s_waitcnt vmcnt(" #n ")" ::: "memory")
; #define PG8_WAIT_L(n) asm volatile("s_waitcnt lgkmcnt(" #n ")" ::: "memory")
; #define PG8_BAR __builtin_amdgcn_s_barrier()
; #define PG8_SCHED __builtin_amdgcn_sched_barrier(0)
; template <class Epi>
; __device__ __forceinline__ void gemm_phase(LAS unsigned char* lds, const Gemm g, const Sched& S, const Epi& E, const int tid) {
;     ...
;             PG8_WAIT_V(8); PG8_WAIT_L(0); PG8_BAR; PG8_MMA(1, 0, At, B0); PG8_MMA(1, 1, At, B1); PG8_BAR; PG8_SCHED;
;             PG8_LDB(B0, 1, 0); PG8_LDB(B1, 1, 1); PG8_SCHED; PG8_LDA(At, 1, 0); PG8_STAGE(PG8_SA(0, 1), a2 + hA, voffA);
;             PG8_WAIT_V(8); PG8_WAIT_L(0); PG8_BAR; PG8_MMA(0, 0, At, B0); PG8_MMA(0, 1, At, B1); PG8_BAR; PG8_SCHED;
	s_setprio 1
	s_waitcnt lgkmcnt(0)
	v_mfma_f32_16x16x32_bf16 v[60:63], v[144:147], v[176:179], 0
	v_mfma_f32_16x16x32_bf16 v[56:59], v[152:155], v[176:179], 0
	v_mfma_f32_16x16x32_bf16 v[44:47], v[144:147], v[184:187], 0
	v_mfma_f32_16x16x32_bf16 v[40:43], v[152:155], v[184:187], 0
	v_mfma_f32_16x16x32_bf16 v[28:31], v[144:147], v[194:197], 0
	v_mfma_f32_16x16x32_bf16 v[24:27], v[152:155], v[194:197], 0
	v_mfma_f32_16x16x32_bf16 v[12:15], v[144:147], v[204:207], 0
	v_mfma_f32_16x16x32_bf16 v[8:11], v[152:155], v[204:207], 0
	v_mfma_f32_16x16x32_bf16 v[60:63], v[148:151], v[180:183], v[60:63]
	v_mfma_f32_16x16x32_bf16 v[56:59], v[156:159], v[180:183], v[56:59]
	v_mfma_f32_16x16x32_bf16 v[44:47], v[148:151], v[188:191], v[44:47]
	v_mfma_f32_16x16x32_bf16 v[40:43], v[156:159], v[188:191], v[40:43]
	v_mfma_f32_16x16x32_bf16 v[28:31], v[148:151], v[198:201], v[28:31]
	v_mfma_f32_16x16x32_bf16 v[24:27], v[156:159], v[198:201], v[24:27]
	v_mfma_f32_16x16x32_bf16 v[12:15], v[148:151], v[208:211], v[12:15]
	v_mfma_f32_16x16x32_bf16 v[8:11], v[156:159], v[208:211], v[8:11]
	s_setprio 0
	s_setprio 1
	v_mfma_f32_16x16x32_bf16 v[52:55], v[160:163], v[176:179], 0
	v_mfma_f32_16x16x32_bf16 v[48:51], v[168:171], v[176:179], 0
	v_mfma_f32_16x16x32_bf16 v[36:39], v[160:163], v[184:187], 0
	v_mfma_f32_16x16x32_bf16 v[32:35], v[168:171], v[184:187], 0
	v_mfma_f32_16x16x32_bf16 v[20:23], v[160:163], v[194:197], 0
	v_mfma_f32_16x16x32_bf16 v[16:19], v[168:171], v[194:197], 0
	v_mfma_f32_16x16x32_bf16 v[4:7], v[160:163], v[204:207], 0
	v_mfma_f32_16x16x32_bf16 v[0:3], v[168:171], v[204:207], 0
	v_mfma_f32_16x16x32_bf16 v[52:55], v[164:167], v[180:183], v[52:55]
	v_mfma_f32_16x16x32_bf16 v[48:51], v[172:175], v[180:183], v[48:51]
	v_mfma_f32_16x16x32_bf16 v[36:39], v[164:167], v[188:191], v[36:39]
	v_mfma_f32_16x16x32_bf16 v[32:35], v[172:175], v[188:191], v[32:35]
	v_mfma_f32_16x16x32_bf16 v[20:23], v[164:167], v[198:201], v[20:23]
	v_mfma_f32_16x16x32_bf16 v[16:19], v[172:175], v[198:201], v[16:19]
	v_mfma_f32_16x16x32_bf16 v[4:7], v[164:167], v[208:211], v[4:7]
	v_mfma_f32_16x16x32_bf16 v[0:3], v[172:175], v[208:211], v[0:3]
	s_setprio 0
	s_barrier
	s_add_i32 s43, 0, 0x18000
	s_add_i32 s44, 0, 0x1c000
	v_add_u32_e32 v156, s43, v141
	v_add_u32_e32 v172, s44, v141
	ds_read_b128 v[144:147], v156
	ds_read_b128 v[148:151], v156 offset:1024
	ds_read_b128 v[152:155], v156 offset:2048
	ds_read_b128 v[156:159], v156 offset:3072
	ds_read_b128 v[160:163], v172
	ds_read_b128 v[164:167], v172 offset:1024
	ds_read_b128 v[168:171], v172 offset:2048
	ds_read_b128 v[172:175], v172 offset:3072
	s_add_u32 s72, s72, 0x40000
	s_addc_u32 s73, s73, 0
	s_mov_b32 m0, s40
	v_lshl_add_u64 v[218:219], s[72:73], 0, v[132:133]
	ds_read_b128 v[176:179], v143 offset:32768
	ds_read_b128 v[180:183], v143 offset:33792
	ds_read_b128 v[184:187], v143 offset:34816
	ds_read_b128 v[188:191], v143 offset:35840
	ds_read_b128 v[194:197], v143 offset:36864
	ds_read_b128 v[198:201], v143 offset:37888
	ds_read_b128 v[204:207], v143 offset:38912
	ds_read_b128 v[208:211], v143 offset:39936
	global_load_lds_dwordx4 v[218:219], off
	v_lshl_add_u64 v[218:219], s[72:73], 0, v[130:131]
	s_mov_b32 m0, s45
	s_nop 0
	global_load_lds_dwordx4 v[218:219], off
	s_waitcnt vmcnt(8)
	s_waitcnt lgkmcnt(0)
	s_barrier
	s_setprio 1
	s_waitcnt lgkmcnt(0)
	v_mfma_f32_16x16x32_bf16 v[124:127], v[144:147], v[176:179], v[124:127]
	v_mfma_f32_16x16x32_bf16 v[120:123], v[152:155], v[176:179], v[120:123]
	v_mfma_f32_16x16x32_bf16 v[108:111], v[144:147], v[184:187], v[108:111]
	v_mfma_f32_16x16x32_bf16 v[104:107], v[152:155], v[184:187], v[104:107]
	v_mfma_f32_16x16x32_bf16 v[92:95], v[144:147], v[194:197], v[92:95]
	v_mfma_f32_16x16x32_bf16 v[88:91], v[152:155], v[194:197], v[88:91]
	v_mfma_f32_16x16x32_bf16 v[76:79], v[144:147], v[204:207], v[76:79]
	v_mfma_f32_16x16x32_bf16 v[72:75], v[152:155], v[204:207], v[72:75]
	v_mfma_f32_16x16x32_bf16 v[124:127], v[148:151], v[180:183], v[124:127]
	v_mfma_f32_16x16x32_bf16 v[120:123], v[156:159], v[180:183], v[120:123]
	v_mfma_f32_16x16x32_bf16 v[108:111], v[148:151], v[188:191], v[108:111]
	v_mfma_f32_16x16x32_bf16 v[104:107], v[156:159], v[188:191], v[104:107]
	v_mfma_f32_16x16x32_bf16 v[92:95], v[148:151], v[198:201], v[92:95]
	v_mfma_f32_16x16x32_bf16 v[88:91], v[156:159], v[198:201], v[88:91]
	v_mfma_f32_16x16x32_bf16 v[76:79], v[148:151], v[208:211], v[76:79]
	v_mfma_f32_16x16x32_bf16 v[72:75], v[156:159], v[208:211], v[72:75]
	s_setprio 0
	s_setprio 1
	v_mfma_f32_16x16x32_bf16 v[116:119], v[160:163], v[176:179], v[116:119]
	v_mfma_f32_16x16x32_bf16 v[112:115], v[168:171], v[176:179], v[112:115]
	v_mfma_f32_16x16x32_bf16 v[100:103], v[160:163], v[184:187], v[100:103]
	v_mfma_f32_16x16x32_bf16 v[96:99], v[168:171], v[184:187], v[96:99]
	v_mfma_f32_16x16x32_bf16 v[84:87], v[160:163], v[194:197], v[84:87]
	v_mfma_f32_16x16x32_bf16 v[80:83], v[168:171], v[194:197], v[80:83]
	v_mfma_f32_16x16x32_bf16 v[68:71], v[160:163], v[204:207], v[68:71]
	v_mfma_f32_16x16x32_bf16 v[64:67], v[168:171], v[204:207], v[64:67]
	v_mfma_f32_16x16x32_bf16 v[116:119], v[164:167], v[180:183], v[116:119]
	v_mfma_f32_16x16x32_bf16 v[112:115], v[172:175], v[180:183], v[112:115]
	v_mfma_f32_16x16x32_bf16 v[100:103], v[164:167], v[188:191], v[100:103]
	v_mfma_f32_16x16x32_bf16 v[96:99], v[172:175], v[188:191], v[96:99]
	v_mfma_f32_16x16x32_bf16 v[84:87], v[164:167], v[198:201], v[84:87]
	v_mfma_f32_16x16x32_bf16 v[80:83], v[172:175], v[198:201], v[80:83]
	v_mfma_f32_16x16x32_bf16 v[68:71], v[164:167], v[208:211], v[68:71]
	v_mfma_f32_16x16x32_bf16 v[64:67], v[172:175], v[208:211], v[64:67]
	s_setprio 0
	s_barrier
; #define PG8_STAGE(bufoff, gbase, voff) do { _Pragma("unroll") for (int _i = 0; _i < 2; ++_i) \
;         __builtin_amdgcn_global_load_lds((const unsigned*)((const char*)(gbase) + (voff)[_i]), (LAS unsigned*)(lds + (bufoff) + ldsw + _i * 8192), 16, 0, 0); } while (0)
; #define PG8_LDA(dst, b, h) do { _Pragma("unroll") for (int m = 0; m < 4; ++m) _Pragma("unroll") for (int k = 0; k < 2; ++k) dst[m][k] = *(const LAS bf16x8*)(lds + PG8_SA(b, h) + aoff + m * 2048 + k * 1024); } while (0)
; #define PG8_LDB(dst, b, h) do { _Pragma("unroll") for (int n = 0; n < 2; ++n) _Pragma("unroll") for (int k = 0; k < 2; ++k) dst[n][k] = *(const LAS bf16x8*)(lds + PG8_SB(b, h) + boff + n * 2048 + k * 1024); } while (0)
; #define PG8_MMA(ai, bj, At, Bt) do { __builtin_amdgcn_s_setprio(1); _Pragma("unroll") for (int m = 0; m < 4; ++m) _Pragma("unroll") for (int n = 0; n < 2; ++n) _Pragma("unroll") for (int k = 0; k < 2; ++k) \
;         acc[ai][bj][m][n] = __builtin_amdgcn_mfma_f32_16x16x32_bf16(Bt[n][k], At[m][k], acc[ai][bj][m][n], 0, 0, 0); __builtin_amdgcn_s_setprio(0); } while (0)
; #define PG8_WAIT_V(n) asm volatile("s_waitcnt vmcnt(" #n ")" ::: "memory")
; #define PG8_WAIT_L(n) asm volatile("s_waitcnt lgkmcnt(" #n ")" ::: "memory")
; #define PG8_BAR __builtin_amdgcn_s_barrier()
; #define PG8_SCHED __builtin_amdgcn_sched_barrier(0)
; template <class Epi>
; __device__ __forceinline__ void gemm_phase(LAS unsigned char* lds, const Gemm g, const Sched& S, const Epi& E, const int tid) {
;     ...
;         for (int t = 0; t < nt; t += 2) {
;             const bool last = (t == nt - 2);
;             const char* a1 = cA + (size_t)(t + 1) * kstep;
;             const char* a2 = last ? nA : cA + (size_t)(t + 2) * kstep; const char* b2 = last ? nB : cB + (size_t)(t + 2) * kstep;
;             const char* a3 = a2 + kstep; const char* b3 = b2 + kstep;
;             PG8_LDB(B0, 0, 0); PG8_LDB(B1, 0, 1); PG8_SCHED; PG8_LDA(At, 0, 0); PG8_STAGE(PG8_SA(1, 1), a1 + hA, voffA);
;     ...
;             PG8_LDA(At, 1, 1); PG8_STAGE(PG8_SB(1, 0), b3, voffB); PG8_STAGE(PG8_SB(1, 1), b3 + hB, voffB); PG8_STAGE(PG8_SA(1, 0), a3, voffA);
;             PG8_WAIT_V(8); PG8_WAIT_L(0); PG8_BAR; PG8_MMA(1, 0, At, B0); PG8_MMA(1, 1, At, B1); PG8_BAR; PG8_SCHED;
	s_add_i32 s43, s43, s35
	v_lshl_add_u64 v[138:139], v[138:139], 0, s[94:95]
	s_mov_b32 m0, s43
	ds_read_b128 v[176:179], v143 offset:49152
	ds_read_b128 v[180:183], v143 offset:50176
	ds_read_b128 v[184:187], v143 offset:51200
	ds_read_b128 v[188:191], v143 offset:52224
	ds_read_b128 v[194:197], v143 offset:53248
	ds_read_b128 v[198:201], v143 offset:54272
	ds_read_b128 v[204:207], v143 offset:55296
	ds_read_b128 v[208:211], v143 offset:56320
	global_load_lds_dwordx4 v[138:139], off
	s_add_i32 m0, s43, 0x2000
	s_add_u32 s22, s22, 0x40080
	v_lshl_add_u64 v[138:139], v[212:213], 0, s[94:95]
	s_addc_u32 s23, s23, 0
	s_add_i32 s43, s44, s35
	global_load_lds_dwordx4 v[138:139], off
	v_lshl_add_u64 v[138:139], s[22:23], 0, v[192:193]
	s_mov_b32 m0, s43
	s_nop 0
	global_load_lds_dwordx4 v[138:139], off
	v_lshl_add_u64 v[138:139], s[22:23], 0, v[128:129]
	s_add_i32 m0, s43, 0x2000
	s_nop 0
	global_load_lds_dwordx4 v[138:139], off
	v_lshl_add_u64 v[138:139], v[214:215], 0, s[94:95]
	s_mov_b32 m0, s47
	s_nop 0
	global_load_lds_dwordx4 v[138:139], off
	v_lshl_add_u64 v[138:139], v[216:217], 0, s[94:95]
	s_mov_b32 m0, s51
	s_nop 0
	global_load_lds_dwordx4 v[138:139], off
	s_waitcnt vmcnt(8)
	s_waitcnt lgkmcnt(0)
	s_barrier
	s_setprio 1
	s_waitcnt lgkmcnt(0)
	v_mfma_f32_16x16x32_bf16 v[60:63], v[144:147], v[176:179], v[60:63]
	v_mfma_f32_16x16x32_bf16 v[56:59], v[152:155], v[176:179], v[56:59]
	v_mfma_f32_16x16x32_bf16 v[44:47], v[144:147], v[184:187], v[44:47]
	v_mfma_f32_16x16x32_bf16 v[40:43], v[152:155], v[184:187], v[40:43]
	v_mfma_f32_16x16x32_bf16 v[28:31], v[144:147], v[194:197], v[28:31]
	v_mfma_f32_16x16x32_bf16 v[24:27], v[152:155], v[194:197], v[24:27]
	v_mfma_f32_16x16x32_bf16 v[12:15], v[144:147], v[204:207], v[12:15]
	v_mfma_f32_16x16x32_bf16 v[8:11], v[152:155], v[204:207], v[8:11]
	v_mfma_f32_16x16x32_bf16 v[60:63], v[148:151], v[180:183], v[60:63]
	v_mfma_f32_16x16x32_bf16 v[56:59], v[156:159], v[180:183], v[56:59]
	v_mfma_f32_16x16x32_bf16 v[44:47], v[148:151], v[188:191], v[44:47]
	v_mfma_f32_16x16x32_bf16 v[40:43], v[156:159], v[188:191], v[40:43]
	v_mfma_f32_16x16x32_bf16 v[28:31], v[148:151], v[198:201], v[28:31]
	v_mfma_f32_16x16x32_bf16 v[24:27], v[156:159], v[198:201], v[24:27]
	v_mfma_f32_16x16x32_bf16 v[12:15], v[148:151], v[208:211], v[12:15]
	v_mfma_f32_16x16x32_bf16 v[8:11], v[156:159], v[208:211], v[8:11]
	s_setprio 0
	s_setprio 1
	v_mfma_f32_16x16x32_bf16 v[52:55], v[160:163], v[176:179], v[52:55]
	v_mfma_f32_16x16x32_bf16 v[48:51], v[168:171], v[176:179], v[48:51]
	v_mfma_f32_16x16x32_bf16 v[36:39], v[160:163], v[184:187], v[36:39]
	v_mfma_f32_16x16x32_bf16 v[32:35], v[168:171], v[184:187], v[32:35]
	v_mfma_f32_16x16x32_bf16 v[20:23], v[160:163], v[194:197], v[20:23]
	v_mfma_f32_16x16x32_bf16 v[16:19], v[168:171], v[194:197], v[16:19]
	v_mfma_f32_16x16x32_bf16 v[4:7], v[160:163], v[204:207], v[4:7]
	v_mfma_f32_16x16x32_bf16 v[0:3], v[168:171], v[204:207], v[0:3]
	v_mfma_f32_16x16x32_bf16 v[52:55], v[164:167], v[180:183], v[52:55]
	v_mfma_f32_16x16x32_bf16 v[48:51], v[172:175], v[180:183], v[48:51]
	v_mfma_f32_16x16x32_bf16 v[36:39], v[164:167], v[188:191], v[36:39]
	v_mfma_f32_16x16x32_bf16 v[32:35], v[172:175], v[188:191], v[32:35]
	v_mfma_f32_16x16x32_bf16 v[20:23], v[164:167], v[198:201], v[20:23]
	v_mfma_f32_16x16x32_bf16 v[16:19], v[172:175], v[198:201], v[16:19]
	v_mfma_f32_16x16x32_bf16 v[4:7], v[164:167], v[208:211], v[4:7]
	v_mfma_f32_16x16x32_bf16 v[0:3], v[172:175], v[208:211], v[0:3]
	s_add_i32 s42, s42, 2
	s_add_u32 s20, s20, 0x100
	s_addc_u32 s21, s21, 0
	s_add_u32 s13, s13, 0x100
	s_addc_u32 s15, s15, 0
	s_cmp_gt_u32 s42, 13
	s_setprio 0
	s_barrier
	s_cbranch_scc1 .Lgk_exit_4
.LBB0_1336:
	s_add_u32 s22, s20, 0xfffc0080
	s_addc_u32 s23, s21, -1
	s_add_i32 s43, 0, 0x10000
	s_cmp_eq_u32 s42, 12
	s_cselect_b32 s73, s7, s23
	s_cselect_b32 s72, s6, s22
	v_add_u32_e32 v138, s43, v141
	s_cselect_b32 s23, s17, s15
	s_cselect_b32 s22, s16, s13
	s_add_i32 s44, 0, 0x14000
	ds_read_b128 v[144:147], v138
	ds_read_b128 v[148:151], v138 offset:1024
	ds_read_b128 v[152:155], v138 offset:2048
	ds_read_b128 v[156:159], v138 offset:3072
	v_add_u32_e32 v138, s44, v141
	ds_read_b128 v[160:163], v138
	ds_read_b128 v[164:167], v138 offset:1024
	ds_read_b128 v[168:171], v138 offset:2048
	ds_read_b128 v[172:175], v138 offset:3072
	v_lshl_add_u64 v[138:139], s[20:21], 0, v[134:135]
	s_add_i32 m0, s19, 0xc000
	ds_read_b128 v[176:179], v143
	ds_read_b128 v[180:183], v143 offset:1024
	ds_read_b128 v[184:187], v143 offset:2048
	ds_read_b128 v[188:191], v143 offset:3072
	ds_read_b128 v[194:197], v143 offset:4096
	ds_read_b128 v[198:201], v143 offset:5120
	ds_read_b128 v[204:207], v143 offset:6144
	ds_read_b128 v[208:211], v143 offset:7168
	global_load_lds_dwordx4 v[138:139], off
	v_lshl_add_u64 v[138:139], s[20:21], 0, v[136:137]
	s_add_i32 m0, s19, 0xe000
	s_nop 0
	global_load_lds_dwordx4 v[138:139], off
	s_waitcnt vmcnt(8)
	s_waitcnt lgkmcnt(0)
	s_barrier
; #define PG8_STAGE(bufoff, gbase, voff) do { _Pragma("unroll") for (int _i = 0; _i < 2; ++_i) \
;         __builtin_amdgcn_global_load_lds((const unsigned*)((const char*)(gbase) + (voff)[_i]), (LAS unsigned*)(lds + (bufoff) + ldsw + _i * 8192), 16, 0, 0); } while (0)
; #define PG8_LDA(dst, b, h) do { _Pragma("unroll") for (int m = 0; m < 4; ++m) _Pragma("unroll") for (int k = 0; k < 2; ++k) dst[m][k] = *(const LAS bf16x8*)(lds + PG8_SA(b, h) + aoff + m * 2048 + k * 1024); } while (0)
; #define PG8_MMA(ai, bj, At, Bt) do { __builtin_amdgcn_s_setprio(1); _Pragma("unroll") for (int m = 0; m < 4; ++m) _Pragma("unroll") for (int n = 0; n < 2; ++n) _Pragma("unroll") for (int k = 0; k < 2; ++k) \
;         acc[ai][bj][m][n] = __builtin_amdgcn_mfma_f32_16x16x32_bf16(Bt[n][k], At[m][k], acc[ai][bj][m][n], 0, 0, 0); __builtin_amdgcn_s_setprio(0); } while (0)
; #define PG8_WAIT_V(n) asm volatile("s_waitcnt vmcnt(" #n ")" ::: "memory")
; #define PG8_WAIT_L(n) asm volatile("s_waitcnt lgkmcnt(" #n ")" ::: "memory")
; #define PG8_BAR __builtin_amdgcn_s_barrier()
; #define PG8_SCHED __builtin_amdgcn_sched_barrier(0)
; template <class Epi>
; __device__ __forceinline__ void gemm_phase(LAS unsigned char* lds, const Gemm g, const Sched& S, const Epi& E, const int tid) {
;     ...
;             PG8_WAIT_V(8); PG8_WAIT_L(0); PG8_BAR; PG8_MMA(0, 0, At, B0); PG8_MMA(0, 1, At, B1); PG8_BAR; PG8_SCHED;
;             PG8_LDA(At, 0, 1); PG8_STAGE(PG8_SB(0, 0), b2, voffB); PG8_STAGE(PG8_SB(0, 1), b2 + hB, voffB); PG8_STAGE(PG8_SA(0, 0), a2, voffA);
;             PG8_WAIT_V(8); PG8_WAIT_L(0); PG8_BAR; PG8_MMA(1, 0, At, B0); PG8_MMA(1, 1, At, B1); PG8_BAR; PG8_SCHED;
	s_setprio 1
	s_waitcnt lgkmcnt(0)
	v_mfma_f32_16x16x32_bf16 v[124:127], v[144:147], v[176:179], v[124:127]
	v_mfma_f32_16x16x32_bf16 v[120:123], v[152:155], v[176:179], v[120:123]
	v_mfma_f32_16x16x32_bf16 v[108:111], v[144:147], v[184:187], v[108:111]
	v_mfma_f32_16x16x32_bf16 v[104:107], v[152:155], v[184:187], v[104:107]
	v_mfma_f32_16x16x32_bf16 v[92:95], v[144:147], v[194:197], v[92:95]
	v_mfma_f32_16x16x32_bf16 v[88:91], v[152:155], v[194:197], v[88:91]
	v_mfma_f32_16x16x32_bf16 v[76:79], v[144:147], v[204:207], v[76:79]
	v_mfma_f32_16x16x32_bf16 v[72:75], v[152:155], v[204:207], v[72:75]
	v_mfma_f32_16x16x32_bf16 v[124:127], v[148:151], v[180:183], v[124:127]
	v_mfma_f32_16x16x32_bf16 v[120:123], v[156:159], v[180:183], v[120:123]
	v_mfma_f32_16x16x32_bf16 v[108:111], v[148:151], v[188:191], v[108:111]
	v_mfma_f32_16x16x32_bf16 v[104:107], v[156:159], v[188:191], v[104:107]
	v_mfma_f32_16x16x32_bf16 v[92:95], v[148:151], v[198:201], v[92:95]
	v_mfma_f32_16x16x32_bf16 v[88:91], v[156:159], v[198:201], v[88:91]
	v_mfma_f32_16x16x32_bf16 v[76:79], v[148:151], v[208:211], v[76:79]
	v_mfma_f32_16x16x32_bf16 v[72:75], v[156:159], v[208:211], v[72:75]
	s_setprio 0
	s_setprio 1
	v_mfma_f32_16x16x32_bf16 v[116:119], v[160:163], v[176:179], v[116:119]
	v_mfma_f32_16x16x32_bf16 v[112:115], v[168:171], v[176:179], v[112:115]
	v_mfma_f32_16x16x32_bf16 v[100:103], v[160:163], v[184:187], v[100:103]
	v_mfma_f32_16x16x32_bf16 v[96:99], v[168:171], v[184:187], v[96:99]
	v_mfma_f32_16x16x32_bf16 v[84:87], v[160:163], v[194:197], v[84:87]
	v_mfma_f32_16x16x32_bf16 v[80:83], v[168:171], v[194:197], v[80:83]
	v_mfma_f32_16x16x32_bf16 v[68:71], v[160:163], v[204:207], v[68:71]
	v_mfma_f32_16x16x32_bf16 v[64:67], v[168:171], v[204:207], v[64:67]
	v_mfma_f32_16x16x32_bf16 v[116:119], v[164:167], v[180:183], v[116:119]
	v_mfma_f32_16x16x32_bf16 v[112:115], v[172:175], v[180:183], v[112:115]
	v_mfma_f32_16x16x32_bf16 v[100:103], v[164:167], v[188:191], v[100:103]
	v_mfma_f32_16x16x32_bf16 v[96:99], v[172:175], v[188:191], v[96:99]
	v_mfma_f32_16x16x32_bf16 v[84:87], v[164:167], v[198:201], v[84:87]
	v_mfma_f32_16x16x32_bf16 v[80:83], v[172:175], v[198:201], v[80:83]
	v_mfma_f32_16x16x32_bf16 v[68:71], v[164:167], v[208:211], v[68:71]
	v_mfma_f32_16x16x32_bf16 v[64:67], v[172:175], v[208:211], v[64:67]
	s_setprio 0
	s_barrier
	s_add_i32 s43, s43, s35
	v_lshl_add_u64 v[138:139], s[22:23], 0, v[192:193]
	s_mov_b32 m0, s43
	ds_read_b128 v[176:179], v143 offset:16384
	ds_read_b128 v[180:183], v143 offset:17408
	ds_read_b128 v[184:187], v143 offset:18432
	ds_read_b128 v[188:191], v143 offset:19456
	ds_read_b128 v[194:197], v143 offset:20480
	ds_read_b128 v[198:201], v143 offset:21504
	ds_read_b128 v[204:207], v143 offset:22528
	ds_read_b128 v[208:211], v143 offset:23552
	global_load_lds_dwordx4 v[138:139], off
	s_add_i32 m0, s43, 0x2000
	s_add_u32 s76, s22, 0x40000
	v_lshl_add_u64 v[212:213], s[22:23], 0, v[128:129]
	s_addc_u32 s77, s23, 0
	s_add_i32 s43, s44, s35
	global_load_lds_dwordx4 v[212:213], off
	v_lshl_add_u64 v[214:215], s[76:77], 0, v[192:193]
	s_mov_b32 m0, s43
	v_lshl_add_u64 v[216:217], s[72:73], 0, v[130:131]
	global_load_lds_dwordx4 v[214:215], off
	v_lshl_add_u64 v[214:215], s[76:77], 0, v[128:129]
	s_add_i32 m0, s43, 0x2000
	s_nop 0
	global_load_lds_dwordx4 v[214:215], off
	v_lshl_add_u64 v[214:215], s[72:73], 0, v[132:133]
	s_mov_b32 m0, s19
	s_nop 0
	global_load_lds_dwordx4 v[214:215], off
	s_mov_b32 m0, s39
	s_nop 0
	global_load_lds_dwordx4 v[216:217], off
	s_waitcnt vmcnt(8)
	s_waitcnt lgkmcnt(0)
	s_barrier
	s_setprio 1
	s_waitcnt lgkmcnt(0)
	v_mfma_f32_16x16x32_bf16 v[60:63], v[144:147], v[176:179], v[60:63]
	v_mfma_f32_16x16x32_bf16 v[56:59], v[152:155], v[176:179], v[56:59]
	v_mfma_f32_16x16x32_bf16 v[44:47], v[144:147], v[184:187], v[44:47]
	v_mfma_f32_16x16x32_bf16 v[40:43], v[152:155], v[184:187], v[40:43]
	v_mfma_f32_16x16x32_bf16 v[28:31], v[144:147], v[194:197], v[28:31]
	v_mfma_f32_16x16x32_bf16 v[24:27], v[152:155], v[194:197], v[24:27]
	v_mfma_f32_16x16x32_bf16 v[12:15], v[144:147], v[204:207], v[12:15]
	v_mfma_f32_16x16x32_bf16 v[8:11], v[152:155], v[204:207], v[8:11]
	v_mfma_f32_16x16x32_bf16 v[60:63], v[148:151], v[180:183], v[60:63]
	v_mfma_f32_16x16x32_bf16 v[56:59], v[156:159], v[180:183], v[56:59]
	v_mfma_f32_16x16x32_bf16 v[44:47], v[148:151], v[188:191], v[44:47]
	v_mfma_f32_16x16x32_bf16 v[40:43], v[156:159], v[188:191], v[40:43]
	v_mfma_f32_16x16x32_bf16 v[28:31], v[148:151], v[198:201], v[28:31]
	v_mfma_f32_16x16x32_bf16 v[24:27], v[156:159], v[198:201], v[24:27]
	v_mfma_f32_16x16x32_bf16 v[12:15], v[148:151], v[208:211], v[12:15]
	v_mfma_f32_16x16x32_bf16 v[8:11], v[156:159], v[208:211], v[8:11]
	s_setprio 0
	s_setprio 1
	v_mfma_f32_16x16x32_bf16 v[52:55], v[160:163], v[176:179], v[52:55]
	v_mfma_f32_16x16x32_bf16 v[48:51], v[168:171], v[176:179], v[48:51]
	v_mfma_f32_16x16x32_bf16 v[36:39], v[160:163], v[184:187], v[36:39]
	v_mfma_f32_16x16x32_bf16 v[32:35], v[168:171], v[184:187], v[32:35]
	v_mfma_f32_16x16x32_bf16 v[20:23], v[160:163], v[194:197], v[20:23]
	v_mfma_f32_16x16x32_bf16 v[16:19], v[168:171], v[194:197], v[16:19]
	v_mfma_f32_16x16x32_bf16 v[4:7], v[160:163], v[204:207], v[4:7]
	v_mfma_f32_16x16x32_bf16 v[0:3], v[168:171], v[204:207], v[0:3]
	v_mfma_f32_16x16x32_bf16 v[52:55], v[164:167], v[180:183], v[52:55]
	v_mfma_f32_16x16x32_bf16 v[48:51], v[172:175], v[180:183], v[48:51]
	v_mfma_f32_16x16x32_bf16 v[36:39], v[164:167], v[188:191], v[36:39]
	v_mfma_f32_16x16x32_bf16 v[32:35], v[172:175], v[188:191], v[32:35]
	v_mfma_f32_16x16x32_bf16 v[20:23], v[164:167], v[198:201], v[20:23]
	v_mfma_f32_16x16x32_bf16 v[16:19], v[172:175], v[198:201], v[16:19]
	v_mfma_f32_16x16x32_bf16 v[4:7], v[164:167], v[208:211], v[4:7]
	v_mfma_f32_16x16x32_bf16 v[0:3], v[172:175], v[208:211], v[0:3]
	s_setprio 0
	s_barrier
; #define PG8_STAGE(bufoff, gbase, voff) do { _Pragma("unroll") for (int _i = 0; _i < 2; ++_i) \
;         __builtin_amdgcn_global_load_lds((const unsigned*)((const char*)(gbase) + (voff)[_i]), (LAS unsigned*)(lds + (bufoff) + ldsw + _i * 8192), 16, 0, 0); } while (0)
; #define PG8_LDA(dst, b, h) do { _Pragma("unroll") for (int m = 0; m < 4; ++m) _Pragma("unroll") for (int k = 0; k < 2; ++k) dst[m][k] = *(const LAS bf16x8*)(lds + PG8_SA(b, h) + aoff + m * 2048 + k * 1024); } while (0)
; #define PG8_LDB(dst, b, h) do { _Pragma("unroll") for (int n = 0; n < 2; ++n) _Pragma("unroll") for (int k = 0; k < 2; ++k) dst[n][k] = *(const LAS bf16x8*)(lds + PG8_SB(b, h) + boff + n * 2048 + k * 1024); } while (0)
; #define PG8_MMA(ai, bj, At, Bt) do { __builtin_amdgcn_s_setprio(1); _Pragma("unroll") for (int m = 0; m < 4; ++m) _Pragma("unroll") for (int n = 0; n < 2; ++n) _Pragma("unroll") for (int k = 0; k < 2; ++k) \
;         acc[ai][bj][m][n] = __builtin_amdgcn_mfma_f32_16x16x32_bf16(Bt[n][k], At[m][k], acc[ai][bj][m][n], 0, 0, 0); __builtin_amdgcn_s_setprio(0); } while (0)
; #define PG8_WAIT_V(n) asm volatile("s_waitcnt vmcnt(" #n ")" ::: "memory")
; #define PG8_WAIT_L(n) asm volatile("s_waitcnt lgkmcnt(" #n ")" ::: "memory")
; #define PG8_BAR __builtin_amdgcn_s_barrier()
; #define PG8_SCHED __builtin_amdgcn_sched_barrier(0)
; template <class Epi>
; __device__ __forceinline__ void gemm_phase(LAS unsigned char* lds, const Gemm g, const Sched& S, const Epi& E, const int tid) {
;     ...
;             PG8_LDB(B0, 1, 0); PG8_LDB(B1, 1, 1); PG8_SCHED; PG8_LDA(At, 1, 0); PG8_STAGE(PG8_SA(0, 1), a2 + hA, voffA);
;             PG8_WAIT_V(8); PG8_WAIT_L(0); PG8_BAR; PG8_MMA(0, 0, At, B0); PG8_MMA(0, 1, At, B1); PG8_BAR; PG8_SCHED;
	s_add_i32 s43, 0, 0x18000
	s_add_i32 s44, 0, 0x1c000
	v_add_u32_e32 v156, s43, v141
	v_add_u32_e32 v172, s44, v141
	ds_read_b128 v[144:147], v156
	ds_read_b128 v[148:151], v156 offset:1024
	ds_read_b128 v[152:155], v156 offset:2048
	ds_read_b128 v[156:159], v156 offset:3072
	ds_read_b128 v[160:163], v172
	ds_read_b128 v[164:167], v172 offset:1024
	ds_read_b128 v[168:171], v172 offset:2048
	ds_read_b128 v[172:175], v172 offset:3072
	s_add_u32 s72, s72, 0x40000
	s_addc_u32 s73, s73, 0
	s_mov_b32 m0, s40
	v_lshl_add_u64 v[218:219], s[72:73], 0, v[132:133]
	ds_read_b128 v[176:179], v143 offset:32768
	ds_read_b128 v[180:183], v143 offset:33792
	ds_read_b128 v[184:187], v143 offset:34816
	ds_read_b128 v[188:191], v143 offset:35840
	ds_read_b128 v[194:197], v143 offset:36864
	ds_read_b128 v[198:201], v143 offset:37888
	ds_read_b128 v[204:207], v143 offset:38912
	ds_read_b128 v[208:211], v143 offset:39936
	global_load_lds_dwordx4 v[218:219], off
	v_lshl_add_u64 v[218:219], s[72:73], 0, v[130:131]
	s_mov_b32 m0, s45
	s_nop 0
	global_load_lds_dwordx4 v[218:219], off
	s_waitcnt vmcnt(8)
	s_waitcnt lgkmcnt(0)
	s_barrier
	s_setprio 1
	s_waitcnt lgkmcnt(0)
	v_mfma_f32_16x16x32_bf16 v[124:127], v[144:147], v[176:179], v[124:127]
	v_mfma_f32_16x16x32_bf16 v[120:123], v[152:155], v[176:179], v[120:123]
	v_mfma_f32_16x16x32_bf16 v[108:111], v[144:147], v[184:187], v[108:111]
	v_mfma_f32_16x16x32_bf16 v[104:107], v[152:155], v[184:187], v[104:107]
	v_mfma_f32_16x16x32_bf16 v[92:95], v[144:147], v[194:197], v[92:95]
	v_mfma_f32_16x16x32_bf16 v[88:91], v[152:155], v[194:197], v[88:91]
	v_mfma_f32_16x16x32_bf16 v[76:79], v[144:147], v[204:207], v[76:79]
	v_mfma_f32_16x16x32_bf16 v[72:75], v[152:155], v[204:207], v[72:75]
	v_mfma_f32_16x16x32_bf16 v[124:127], v[148:151], v[180:183], v[124:127]
	v_mfma_f32_16x16x32_bf16 v[120:123], v[156:159], v[180:183], v[120:123]
	v_mfma_f32_16x16x32_bf16 v[108:111], v[148:151], v[188:191], v[108:111]
	v_mfma_f32_16x16x32_bf16 v[104:107], v[156:159], v[188:191], v[104:107]
	v_mfma_f32_16x16x32_bf16 v[92:95], v[148:151], v[198:201], v[92:95]
	v_mfma_f32_16x16x32_bf16 v[88:91], v[156:159], v[198:201], v[88:91]
	v_mfma_f32_16x16x32_bf16 v[76:79], v[148:151], v[208:211], v[76:79]
	v_mfma_f32_16x16x32_bf16 v[72:75], v[156:159], v[208:211], v[72:75]
	s_setprio 0
	s_setprio 1
	v_mfma_f32_16x16x32_bf16 v[116:119], v[160:163], v[176:179], v[116:119]
	v_mfma_f32_16x16x32_bf16 v[112:115], v[168:171], v[176:179], v[112:115]
	v_mfma_f32_16x16x32_bf16 v[100:103], v[160:163], v[184:187], v[100:103]
	v_mfma_f32_16x16x32_bf16 v[96:99], v[168:171], v[184:187], v[96:99]
	v_mfma_f32_16x16x32_bf16 v[84:87], v[160:163], v[194:197], v[84:87]
	v_mfma_f32_16x16x32_bf16 v[80:83], v[168:171], v[194:197], v[80:83]
	v_mfma_f32_16x16x32_bf16 v[68:71], v[160:163], v[204:207], v[68:71]
	v_mfma_f32_16x16x32_bf16 v[64:67], v[168:171], v[204:207], v[64:67]
	v_mfma_f32_16x16x32_bf16 v[116:119], v[164:167], v[180:183], v[116:119]
	v_mfma_f32_16x16x32_bf16 v[112:115], v[172:175], v[180:183], v[112:115]
	v_mfma_f32_16x16x32_bf16 v[100:103], v[164:167], v[188:191], v[100:103]
	v_mfma_f32_16x16x32_bf16 v[96:99], v[172:175], v[188:191], v[96:99]
	v_mfma_f32_16x16x32_bf16 v[84:87], v[164:167], v[198:201], v[84:87]
	v_mfma_f32_16x16x32_bf16 v[80:83], v[172:175], v[198:201], v[80:83]
	v_mfma_f32_16x16x32_bf16 v[68:71], v[164:167], v[208:211], v[68:71]
	v_mfma_f32_16x16x32_bf16 v[64:67], v[172:175], v[208:211], v[64:67]
	s_setprio 0
	s_barrier
; #define PG8_STAGE(bufoff, gbase, voff) do { _Pragma("unroll") for (int _i = 0; _i < 2; ++_i) \
;         __builtin_amdgcn_global_load_lds((const unsigned*)((const char*)(gbase) + (voff)[_i]), (LAS unsigned*)(lds + (bufoff) + ldsw + _i * 8192), 16, 0, 0); } while (0)
; #define PG8_LDA(dst, b, h) do { _Pragma("unroll") for (int m = 0; m < 4; ++m) _Pragma("unroll") for (int k = 0; k < 2; ++k) dst[m][k] = *(const LAS bf16x8*)(lds + PG8_SA(b, h) + aoff + m * 2048 + k * 1024); } while (0)
; #define PG8_MMA(ai, bj, At, Bt) do { __builtin_amdgcn_s_setprio(1); _Pragma("unroll") for (int m = 0; m < 4; ++m) _Pragma("unroll") for (int n = 0; n < 2; ++n) _Pragma("unroll") for (int k = 0; k < 2; ++k) \
;         acc[ai][bj][m][n] = __builtin_amdgcn_mfma_f32_16x16x32_bf16(Bt[n][k], At[m][k], acc[ai][bj][m][n], 0, 0, 0); __builtin_amdgcn_s_setprio(0); } while (0)
; #define PG8_WAIT_V(n) asm volatile("s_waitcnt vmcnt(" #n ")" ::: "memory")
; #define PG8_WAIT_L(n) asm volatile("s_waitcnt lgkmcnt(" #n ")" ::: "memory")
; #define PG8_BAR __builtin_amdgcn_s_barrier()
; #define PG8_SCHED __builtin_amdgcn_sched_barrier(0)
; template <class Epi>
; __device__ __forceinline__ void gemm_phase(LAS unsigned char* lds, const Gemm g, const Sched& S, const Epi& E, const int tid) {
;     ...
;             PG8_LDA(At, 1, 1); PG8_STAGE(PG8_SB(1, 0), b3, voffB); PG8_STAGE(PG8_SB(1, 1), b3 + hB, voffB); PG8_STAGE(PG8_SA(1, 0), a3, voffA);
;             PG8_WAIT_V(8); PG8_WAIT_L(0); PG8_BAR; PG8_MMA(1, 0, At, B0); PG8_MMA(1, 1, At, B1); PG8_BAR; PG8_SCHED;
;         }
	s_add_i32 s43, s43, s35
	v_lshl_add_u64 v[138:139], v[138:139], 0, s[94:95]
	s_mov_b32 m0, s43
	ds_read_b128 v[176:179], v143 offset:49152
	ds_read_b128 v[180:183], v143 offset:50176
	ds_read_b128 v[184:187], v143 offset:51200
	ds_read_b128 v[188:191], v143 offset:52224
	ds_read_b128 v[194:197], v143 offset:53248
	ds_read_b128 v[198:201], v143 offset:54272
	ds_read_b128 v[204:207], v143 offset:55296
	ds_read_b128 v[208:211], v143 offset:56320
	global_load_lds_dwordx4 v[138:139], off
	s_add_i32 m0, s43, 0x2000
	s_add_u32 s22, s22, 0x40080
	v_lshl_add_u64 v[138:139], v[212:213], 0, s[94:95]
	s_addc_u32 s23, s23, 0
	s_add_i32 s43, s44, s35
	global_load_lds_dwordx4 v[138:139], off
	v_lshl_add_u64 v[138:139], s[22:23], 0, v[192:193]
	s_mov_b32 m0, s43
	s_nop 0
	global_load_lds_dwordx4 v[138:139], off
	v_lshl_add_u64 v[138:139], s[22:23], 0, v[128:129]
	s_add_i32 m0, s43, 0x2000
	s_nop 0
	global_load_lds_dwordx4 v[138:139], off
	v_lshl_add_u64 v[138:139], v[214:215], 0, s[94:95]
	s_mov_b32 m0, s47
	s_nop 0
	global_load_lds_dwordx4 v[138:139], off
	v_lshl_add_u64 v[138:139], v[216:217], 0, s[94:95]
	s_mov_b32 m0, s51
	s_nop 0
	global_load_lds_dwordx4 v[138:139], off
	s_waitcnt vmcnt(8)
	s_waitcnt lgkmcnt(0)
	s_barrier
	s_setprio 1
	s_waitcnt lgkmcnt(0)
	v_mfma_f32_16x16x32_bf16 v[60:63], v[144:147], v[176:179], v[60:63]
	v_mfma_f32_16x16x32_bf16 v[56:59], v[152:155], v[176:179], v[56:59]
	v_mfma_f32_16x16x32_bf16 v[44:47], v[144:147], v[184:187], v[44:47]
	v_mfma_f32_16x16x32_bf16 v[40:43], v[152:155], v[184:187], v[40:43]
	v_mfma_f32_16x16x32_bf16 v[28:31], v[144:147], v[194:197], v[28:31]
	v_mfma_f32_16x16x32_bf16 v[24:27], v[152:155], v[194:197], v[24:27]
	v_mfma_f32_16x16x32_bf16 v[12:15], v[144:147], v[204:207], v[12:15]
	v_mfma_f32_16x16x32_bf16 v[8:11], v[152:155], v[204:207], v[8:11]
	v_mfma_f32_16x16x32_bf16 v[60:63], v[148:151], v[180:183], v[60:63]
	v_mfma_f32_16x16x32_bf16 v[56:59], v[156:159], v[180:183], v[56:59]
	v_mfma_f32_16x16x32_bf16 v[44:47], v[148:151], v[188:191], v[44:47]
	v_mfma_f32_16x16x32_bf16 v[40:43], v[156:159], v[188:191], v[40:43]
	v_mfma_f32_16x16x32_bf16 v[28:31], v[148:151], v[198:201], v[28:31]
	v_mfma_f32_16x16x32_bf16 v[24:27], v[156:159], v[198:201], v[24:27]
	v_mfma_f32_16x16x32_bf16 v[12:15], v[148:151], v[208:211], v[12:15]
	v_mfma_f32_16x16x32_bf16 v[8:11], v[156:159], v[208:211], v[8:11]
	s_setprio 0
	s_setprio 1
	v_mfma_f32_16x16x32_bf16 v[52:55], v[160:163], v[176:179], v[52:55]
	v_mfma_f32_16x16x32_bf16 v[48:51], v[168:171], v[176:179], v[48:51]
	v_mfma_f32_16x16x32_bf16 v[36:39], v[160:163], v[184:187], v[36:39]
	v_mfma_f32_16x16x32_bf16 v[32:35], v[168:171], v[184:187], v[32:35]
	v_mfma_f32_16x16x32_bf16 v[20:23], v[160:163], v[194:197], v[20:23]
	v_mfma_f32_16x16x32_bf16 v[16:19], v[168:171], v[194:197], v[16:19]
	v_mfma_f32_16x16x32_bf16 v[4:7], v[160:163], v[204:207], v[4:7]
	v_mfma_f32_16x16x32_bf16 v[0:3], v[168:171], v[204:207], v[0:3]
	v_mfma_f32_16x16x32_bf16 v[52:55], v[164:167], v[180:183], v[52:55]
	v_mfma_f32_16x16x32_bf16 v[48:51], v[172:175], v[180:183], v[48:51]
	v_mfma_f32_16x16x32_bf16 v[36:39], v[164:167], v[188:191], v[36:39]
	v_mfma_f32_16x16x32_bf16 v[32:35], v[172:175], v[188:191], v[32:35]
	v_mfma_f32_16x16x32_bf16 v[20:23], v[164:167], v[198:201], v[20:23]
	v_mfma_f32_16x16x32_bf16 v[16:19], v[172:175], v[198:201], v[16:19]
	v_mfma_f32_16x16x32_bf16 v[4:7], v[164:167], v[208:211], v[4:7]
	v_mfma_f32_16x16x32_bf16 v[0:3], v[172:175], v[208:211], v[0:3]
	s_add_i32 s42, s42, 2
	s_add_u32 s20, s20, 0x100
	s_addc_u32 s21, s21, 0
	s_add_u32 s13, s13, 0x100
	s_addc_u32 s15, s15, 0
	s_cmp_gt_u32 s42, 13
	s_setprio 0
	s_barrier
	s_cbranch_scc0 .LBB0_1336

; #define PG8_STAGE(bufoff, gbase, voff) do { _Pragma("unroll") for (int _i = 0; _i < 2; ++_i) \
;         __builtin_amdgcn_global_load_lds((const unsigned*)((const char*)(gbase) + (voff)[_i]), (LAS unsigned*)(lds + (bufoff) + ldsw + _i * 8192), 16, 0, 0); } while (0)
; #define PG8_LDA(dst, b, h) do { _Pragma("unroll") for (int m = 0; m < 4; ++m) _Pragma("unroll") for (int k = 0; k < 2; ++k) dst[m][k] = *(const LAS bf16x8*)(lds + PG8_SA(b, h) + aoff + m * 2048 + k * 1024); } while (0)
; #define PG8_LDB(dst, b, h) do { _Pragma("unroll") for (int n = 0; n < 2; ++n) _Pragma("unroll") for (int k = 0; k < 2; ++k) dst[n][k] = *(const LAS bf16x8*)(lds + PG8_SB(b, h) + boff + n * 2048 + k * 1024); } while (0)
; #define PG8_MMA(ai, bj, At, Bt) do { __builtin_amdgcn_s_setprio(1); _Pragma("unroll") for (int m = 0; m < 4; ++m) _Pragma("unroll") for (int n = 0; n < 2; ++n) _Pragma("unroll") for (int k = 0; k < 2; ++k) \
;         acc[ai][bj][m][n] = __builtin_amdgcn_mfma_f32_16x16x32_bf16(Bt[n][k], At[m][k], acc[ai][bj][m][n], 0, 0, 0); __builtin_amdgcn_s_setprio(0); } while (0)
; #define PG8_WAIT_V(n) asm volatile("s_waitcnt vmcnt(" #n ")" ::: "memory")
; #define PG8_WAIT_L(n) asm volatile("s_waitcnt lgkmcnt(" #n ")" ::: "memory")
; #define PG8_BAR __builtin_amdgcn_s_barrier()
; #define PG8_SCHED __builtin_amdgcn_sched_barrier(0)
; template <class Epi>
; __device__ __forceinline__ void gemm_phase(LAS unsigned char* lds, const Gemm g, const Sched& S, const Epi& E, const int tid) {
;     ...
;         for (int t = 0; t < nt; t += 2) {
;             const bool last = (t == nt - 2);
;             const char* a1 = cA + (size_t)(t + 1) * kstep;
;             const char* a2 = last ? nA : cA + (size_t)(t + 2) * kstep; const char* b2 = last ? nB : cB + (size_t)(t + 2) * kstep;
;             const char* a3 = a2 + kstep; const char* b3 = b2 + kstep;
;             PG8_LDB(B0, 0, 0); PG8_LDB(B1, 0, 1); PG8_SCHED; PG8_LDA(At, 0, 0); PG8_STAGE(PG8_SA(1, 1), a1 + hA, voffA);
;             PG8_WAIT_V(8); PG8_WAIT_L(0); PG8_BAR; PG8_MMA(0, 0, At, B0); PG8_MMA(0, 1, At, B1); PG8_BAR; PG8_SCHED;
;             PG8_LDA(At, 0, 1); PG8_STAGE(PG8_SB(0, 0), b2, voffB); PG8_STAGE(PG8_SB(0, 1), b2 + hB, voffB); PG8_STAGE(PG8_SA(0, 0), a2, voffA);
;             PG8_WAIT_V(8); PG8_WAIT_L(0); PG8_BAR; PG8_MMA(1, 0, At, B0); PG8_MMA(1, 1, At, B1); PG8_BAR; PG8_SCHED;
.LBB0_1410:
	s_add_u32 s80, s18, 0x100
	s_addc_u32 s81, s19, 0
	s_mov_b32 vcc_lo, -2
	s_add_u32 s18, s16, 0x100
	s_addc_u32 s19, s17, 0
	s_add_i32 s43, 0, 0x10000
	s_cmp_eq_u32 vcc_lo, 40
	s_cselect_b32 s23, s7, s19
	s_cselect_b32 s22, s6, s18
	s_cselect_b32 s21, s15, s81
	s_cselect_b32 s20, s14, s80
	s_add_i32 s44, 0, 0x14000
	v_add_u32_e32 v92, s43, v157
	v_add_u32_e32 v154, s44, v157
	ds_read_b128 v[64:67], v92
	ds_read_b128 v[68:71], v92 offset:1024
	ds_read_b128 v[80:83], v92 offset:2048
	ds_read_b128 v[92:95], v92 offset:3072
	ds_read_b128 v[160:163], v154
	ds_read_b128 v[164:167], v154 offset:1024
	ds_read_b128 v[168:171], v154 offset:2048
	ds_read_b128 v[172:175], v154 offset:3072
	v_lshl_add_u64 v[154:155], s[16:17], 0, v[150:151]
	s_add_i32 m0, s40, 0xc000
	ds_read_b128 v[176:179], v159
	ds_read_b128 v[180:183], v159 offset:1024
	ds_read_b128 v[184:187], v159 offset:2048
	ds_read_b128 v[188:191], v159 offset:3072
	ds_read_b128 v[194:197], v159 offset:4096
	ds_read_b128 v[198:201], v159 offset:5120
	ds_read_b128 v[204:207], v159 offset:6144
	ds_read_b128 v[208:211], v159 offset:7168
	global_load_lds_dwordx4 v[154:155], off
	v_lshl_add_u64 v[154:155], s[16:17], 0, v[152:153]
	s_add_i32 m0, s40, 0xe000
	s_nop 0
	global_load_lds_dwordx4 v[154:155], off
	s_waitcnt vmcnt(8)
	s_waitcnt lgkmcnt(0)
	s_barrier
	s_setprio 1
	s_waitcnt lgkmcnt(0)
	v_mfma_f32_16x16x32_bf16 v[140:143], v[64:67], v[176:179], 0
	v_mfma_f32_16x16x32_bf16 v[136:139], v[80:83], v[176:179], 0
	v_mfma_f32_16x16x32_bf16 v[132:135], v[64:67], v[184:187], 0
	v_mfma_f32_16x16x32_bf16 v[128:131], v[80:83], v[184:187], 0
	v_mfma_f32_16x16x32_bf16 v[108:111], v[64:67], v[194:197], 0
	v_mfma_f32_16x16x32_bf16 v[104:107], v[80:83], v[194:197], 0
	v_mfma_f32_16x16x32_bf16 v[100:103], v[64:67], v[204:207], 0
	v_mfma_f32_16x16x32_bf16 v[96:99], v[80:83], v[204:207], 0
	v_mfma_f32_16x16x32_bf16 v[140:143], v[68:71], v[180:183], v[140:143]
	v_mfma_f32_16x16x32_bf16 v[136:139], v[92:95], v[180:183], v[136:139]
	v_mfma_f32_16x16x32_bf16 v[132:135], v[68:71], v[188:191], v[132:135]
	v_mfma_f32_16x16x32_bf16 v[128:131], v[92:95], v[188:191], v[128:131]
	v_mfma_f32_16x16x32_bf16 v[108:111], v[68:71], v[198:201], v[108:111]
	v_mfma_f32_16x16x32_bf16 v[104:107], v[92:95], v[198:201], v[104:107]
	v_mfma_f32_16x16x32_bf16 v[100:103], v[68:71], v[208:211], v[100:103]
	v_mfma_f32_16x16x32_bf16 v[96:99], v[92:95], v[208:211], v[96:99]
	s_setprio 0
	s_setprio 1
	v_mfma_f32_16x16x32_bf16 v[124:127], v[160:163], v[176:179], 0
	v_mfma_f32_16x16x32_bf16 v[120:123], v[168:171], v[176:179], 0
	v_mfma_f32_16x16x32_bf16 v[116:119], v[160:163], v[184:187], 0
	v_mfma_f32_16x16x32_bf16 v[112:115], v[168:171], v[184:187], 0
	v_mfma_f32_16x16x32_bf16 v[88:91], v[160:163], v[194:197], 0
	v_mfma_f32_16x16x32_bf16 v[84:87], v[168:171], v[194:197], 0
	v_mfma_f32_16x16x32_bf16 v[76:79], v[160:163], v[204:207], 0
	v_mfma_f32_16x16x32_bf16 v[72:75], v[168:171], v[204:207], 0
	v_mfma_f32_16x16x32_bf16 v[124:127], v[164:167], v[180:183], v[124:127]
	v_mfma_f32_16x16x32_bf16 v[120:123], v[172:175], v[180:183], v[120:123]
	v_mfma_f32_16x16x32_bf16 v[116:119], v[164:167], v[188:191], v[116:119]
	v_mfma_f32_16x16x32_bf16 v[112:115], v[172:175], v[188:191], v[112:115]
	v_mfma_f32_16x16x32_bf16 v[88:91], v[164:167], v[198:201], v[88:91]
	v_mfma_f32_16x16x32_bf16 v[84:87], v[172:175], v[198:201], v[84:87]
	v_mfma_f32_16x16x32_bf16 v[76:79], v[164:167], v[208:211], v[76:79]
	v_mfma_f32_16x16x32_bf16 v[72:75], v[172:175], v[208:211], v[72:75]
	s_setprio 0
	s_barrier
	s_add_i32 s16, s43, s39
	v_lshl_add_u64 v[154:155], s[20:21], 0, v[192:193]
	s_mov_b32 m0, s16
	ds_read_b128 v[176:179], v159 offset:16384
	ds_read_b128 v[180:183], v159 offset:17408
	ds_read_b128 v[184:187], v159 offset:18432
	ds_read_b128 v[188:191], v159 offset:19456
	ds_read_b128 v[194:197], v159 offset:20480
	ds_read_b128 v[198:201], v159 offset:21504
	ds_read_b128 v[204:207], v159 offset:22528
	ds_read_b128 v[208:211], v159 offset:23552
	global_load_lds_dwordx4 v[154:155], off
	s_add_i32 m0, s16, 0x2000
	s_add_u32 s16, s20, 0xb0000
	v_lshl_add_u64 v[212:213], s[20:21], 0, v[144:145]
	s_addc_u32 s17, s21, 0
	s_add_i32 s43, s44, s39
	global_load_lds_dwordx4 v[212:213], off
	v_lshl_add_u64 v[214:215], s[16:17], 0, v[192:193]
	s_mov_b32 m0, s43
	v_lshl_add_u64 v[216:217], s[22:23], 0, v[146:147]
	global_load_lds_dwordx4 v[214:215], off
	v_lshl_add_u64 v[214:215], s[16:17], 0, v[144:145]
	s_add_i32 m0, s43, 0x2000
	s_nop 0
	global_load_lds_dwordx4 v[214:215], off
	v_lshl_add_u64 v[214:215], s[22:23], 0, v[148:149]
	s_mov_b32 m0, s40
	s_nop 0
	global_load_lds_dwordx4 v[214:215], off
	s_mov_b32 m0, s73
	s_nop 0
	global_load_lds_dwordx4 v[216:217], off
	s_waitcnt vmcnt(8)
	s_waitcnt lgkmcnt(0)
	s_barrier
; #define PG8_STAGE(bufoff, gbase, voff) do { _Pragma("unroll") for (int _i = 0; _i < 2; ++_i) \
;         __builtin_amdgcn_global_load_lds((const unsigned*)((const char*)(gbase) + (voff)[_i]), (LAS unsigned*)(lds + (bufoff) + ldsw + _i * 8192), 16, 0, 0); } while (0)
; #define PG8_LDA(dst, b, h) do { _Pragma("unroll") for (int m = 0; m < 4; ++m) _Pragma("unroll") for (int k = 0; k < 2; ++k) dst[m][k] = *(const LAS bf16x8*)(lds + PG8_SA(b, h) + aoff + m * 2048 + k * 1024); } while (0)
; #define PG8_LDB(dst, b, h) do { _Pragma("unroll") for (int n = 0; n < 2; ++n) _Pragma("unroll") for (int k = 0; k < 2; ++k) dst[n][k] = *(const LAS bf16x8*)(lds + PG8_SB(b, h) + boff + n * 2048 + k * 1024); } while (0)
; #define PG8_MMA(ai, bj, At, Bt) do { __builtin_amdgcn_s_setprio(1); _Pragma("unroll") for (int m = 0; m < 4; ++m) _Pragma("unroll") for (int n = 0; n < 2; ++n) _Pragma("unroll") for (int k = 0; k < 2; ++k) \
;         acc[ai][bj][m][n] = __builtin_amdgcn_mfma_f32_16x16x32_bf16(Bt[n][k], At[m][k], acc[ai][bj][m][n], 0, 0, 0); __builtin_amdgcn_s_setprio(0); } while (0)
; #define PG8_WAIT_V(n) asm volatile("s_waitcnt vmcnt(" #n ")" ::: "memory")
; #define PG8_WAIT_L(n) asm volatile("s_waitcnt lgkmcnt(" #n ")" ::: "memory")
; #define PG8_BAR __builtin_amdgcn_s_barrier()
; #define PG8_SCHED __builtin_amdgcn_sched_barrier(0)
; template <class Epi>
; __device__ __forceinline__ void gemm_phase(LAS unsigned char* lds, const Gemm g, const Sched& S, const Epi& E, const int tid) {
;     ...
;             PG8_WAIT_V(8); PG8_WAIT_L(0); PG8_BAR; PG8_MMA(1, 0, At, B0); PG8_MMA(1, 1, At, B1); PG8_BAR; PG8_SCHED;
;             PG8_LDB(B0, 1, 0); PG8_LDB(B1, 1, 1); PG8_SCHED; PG8_LDA(At, 1, 0); PG8_STAGE(PG8_SA(0, 1), a2 + hA, voffA);
;             PG8_WAIT_V(8); PG8_WAIT_L(0); PG8_BAR; PG8_MMA(0, 0, At, B0); PG8_MMA(0, 1, At, B1); PG8_BAR; PG8_SCHED;
	s_setprio 1
	s_waitcnt lgkmcnt(0)
	v_mfma_f32_16x16x32_bf16 v[60:63], v[64:67], v[176:179], 0
	v_mfma_f32_16x16x32_bf16 v[56:59], v[80:83], v[176:179], 0
	v_mfma_f32_16x16x32_bf16 v[52:55], v[64:67], v[184:187], 0
	v_mfma_f32_16x16x32_bf16 v[48:51], v[80:83], v[184:187], 0
	v_mfma_f32_16x16x32_bf16 v[28:31], v[64:67], v[194:197], 0
	v_mfma_f32_16x16x32_bf16 v[24:27], v[80:83], v[194:197], 0
	v_mfma_f32_16x16x32_bf16 v[16:19], v[64:67], v[204:207], 0
	v_mfma_f32_16x16x32_bf16 v[8:11], v[80:83], v[204:207], 0
	v_mfma_f32_16x16x32_bf16 v[60:63], v[68:71], v[180:183], v[60:63]
	v_mfma_f32_16x16x32_bf16 v[56:59], v[92:95], v[180:183], v[56:59]
	v_mfma_f32_16x16x32_bf16 v[52:55], v[68:71], v[188:191], v[52:55]
	v_mfma_f32_16x16x32_bf16 v[48:51], v[92:95], v[188:191], v[48:51]
	v_mfma_f32_16x16x32_bf16 v[28:31], v[68:71], v[198:201], v[28:31]
	v_mfma_f32_16x16x32_bf16 v[24:27], v[92:95], v[198:201], v[24:27]
	v_mfma_f32_16x16x32_bf16 v[16:19], v[68:71], v[208:211], v[16:19]
	v_mfma_f32_16x16x32_bf16 v[8:11], v[92:95], v[208:211], v[8:11]
	s_setprio 0
	s_setprio 1
	v_mfma_f32_16x16x32_bf16 v[44:47], v[160:163], v[176:179], 0
	v_mfma_f32_16x16x32_bf16 v[40:43], v[168:171], v[176:179], 0
	v_mfma_f32_16x16x32_bf16 v[36:39], v[160:163], v[184:187], 0
	v_mfma_f32_16x16x32_bf16 v[32:35], v[168:171], v[184:187], 0
	v_mfma_f32_16x16x32_bf16 v[20:23], v[160:163], v[194:197], 0
	v_mfma_f32_16x16x32_bf16 v[12:15], v[168:171], v[194:197], 0
	v_mfma_f32_16x16x32_bf16 v[4:7], v[160:163], v[204:207], 0
	v_mfma_f32_16x16x32_bf16 v[0:3], v[168:171], v[204:207], 0
	v_mfma_f32_16x16x32_bf16 v[44:47], v[164:167], v[180:183], v[44:47]
	v_mfma_f32_16x16x32_bf16 v[40:43], v[172:175], v[180:183], v[40:43]
	v_mfma_f32_16x16x32_bf16 v[36:39], v[164:167], v[188:191], v[36:39]
	v_mfma_f32_16x16x32_bf16 v[32:35], v[172:175], v[188:191], v[32:35]
	v_mfma_f32_16x16x32_bf16 v[20:23], v[164:167], v[198:201], v[20:23]
	v_mfma_f32_16x16x32_bf16 v[12:15], v[172:175], v[198:201], v[12:15]
	v_mfma_f32_16x16x32_bf16 v[4:7], v[164:167], v[208:211], v[4:7]
	v_mfma_f32_16x16x32_bf16 v[0:3], v[172:175], v[208:211], v[0:3]
	s_setprio 0
	s_barrier
	s_add_i32 s43, 0, 0x18000
	s_add_i32 s44, 0, 0x1c000
	v_add_u32_e32 v92, s43, v157
	v_add_u32_e32 v172, s44, v157
	ds_read_b128 v[64:67], v92
	ds_read_b128 v[68:71], v92 offset:1024
	ds_read_b128 v[80:83], v92 offset:2048
	ds_read_b128 v[92:95], v92 offset:3072
	ds_read_b128 v[160:163], v172
	ds_read_b128 v[164:167], v172 offset:1024
	ds_read_b128 v[168:171], v172 offset:2048
	ds_read_b128 v[172:175], v172 offset:3072
	s_add_u32 s16, s22, 0xb0000
	s_addc_u32 s17, s23, 0
	s_mov_b32 m0, s74
	v_lshl_add_u64 v[218:219], s[16:17], 0, v[148:149]
	ds_read_b128 v[176:179], v159 offset:32768
	ds_read_b128 v[180:183], v159 offset:33792
	ds_read_b128 v[184:187], v159 offset:34816
	ds_read_b128 v[188:191], v159 offset:35840
	ds_read_b128 v[194:197], v159 offset:36864
	ds_read_b128 v[198:201], v159 offset:37888
	ds_read_b128 v[204:207], v159 offset:38912
	ds_read_b128 v[208:211], v159 offset:39936
	global_load_lds_dwordx4 v[218:219], off
	v_lshl_add_u64 v[218:219], s[16:17], 0, v[146:147]
	s_mov_b32 m0, s75
	s_nop 0
	global_load_lds_dwordx4 v[218:219], off
	s_waitcnt vmcnt(8)
	s_waitcnt lgkmcnt(0)
	s_barrier
	s_setprio 1
	s_waitcnt lgkmcnt(0)
	v_mfma_f32_16x16x32_bf16 v[140:143], v[64:67], v[176:179], v[140:143]
	v_mfma_f32_16x16x32_bf16 v[136:139], v[80:83], v[176:179], v[136:139]
	v_mfma_f32_16x16x32_bf16 v[132:135], v[64:67], v[184:187], v[132:135]
	v_mfma_f32_16x16x32_bf16 v[128:131], v[80:83], v[184:187], v[128:131]
	v_mfma_f32_16x16x32_bf16 v[108:111], v[64:67], v[194:197], v[108:111]
	v_mfma_f32_16x16x32_bf16 v[104:107], v[80:83], v[194:197], v[104:107]
	v_mfma_f32_16x16x32_bf16 v[100:103], v[64:67], v[204:207], v[100:103]
	v_mfma_f32_16x16x32_bf16 v[96:99], v[80:83], v[204:207], v[96:99]
	v_mfma_f32_16x16x32_bf16 v[140:143], v[68:71], v[180:183], v[140:143]
	v_mfma_f32_16x16x32_bf16 v[136:139], v[92:95], v[180:183], v[136:139]
	v_mfma_f32_16x16x32_bf16 v[132:135], v[68:71], v[188:191], v[132:135]
	v_mfma_f32_16x16x32_bf16 v[128:131], v[92:95], v[188:191], v[128:131]
	v_mfma_f32_16x16x32_bf16 v[108:111], v[68:71], v[198:201], v[108:111]
	v_mfma_f32_16x16x32_bf16 v[104:107], v[92:95], v[198:201], v[104:107]
	v_mfma_f32_16x16x32_bf16 v[100:103], v[68:71], v[208:211], v[100:103]
	v_mfma_f32_16x16x32_bf16 v[96:99], v[92:95], v[208:211], v[96:99]
	s_setprio 0
	s_setprio 1
	v_mfma_f32_16x16x32_bf16 v[124:127], v[160:163], v[176:179], v[124:127]
	v_mfma_f32_16x16x32_bf16 v[120:123], v[168:171], v[176:179], v[120:123]
	v_mfma_f32_16x16x32_bf16 v[116:119], v[160:163], v[184:187], v[116:119]
	v_mfma_f32_16x16x32_bf16 v[112:115], v[168:171], v[184:187], v[112:115]
	v_mfma_f32_16x16x32_bf16 v[88:91], v[160:163], v[194:197], v[88:91]
	v_mfma_f32_16x16x32_bf16 v[84:87], v[168:171], v[194:197], v[84:87]
	v_mfma_f32_16x16x32_bf16 v[76:79], v[160:163], v[204:207], v[76:79]
	v_mfma_f32_16x16x32_bf16 v[72:75], v[168:171], v[204:207], v[72:75]
	v_mfma_f32_16x16x32_bf16 v[124:127], v[164:167], v[180:183], v[124:127]
	v_mfma_f32_16x16x32_bf16 v[120:123], v[172:175], v[180:183], v[120:123]
	v_mfma_f32_16x16x32_bf16 v[116:119], v[164:167], v[188:191], v[116:119]
	v_mfma_f32_16x16x32_bf16 v[112:115], v[172:175], v[188:191], v[112:115]
	v_mfma_f32_16x16x32_bf16 v[88:91], v[164:167], v[198:201], v[88:91]
	v_mfma_f32_16x16x32_bf16 v[84:87], v[172:175], v[198:201], v[84:87]
	v_mfma_f32_16x16x32_bf16 v[76:79], v[164:167], v[208:211], v[76:79]
	v_mfma_f32_16x16x32_bf16 v[72:75], v[172:175], v[208:211], v[72:75]
	s_setprio 0
	s_barrier
; #define PG8_STAGE(bufoff, gbase, voff) do { _Pragma("unroll") for (int _i = 0; _i < 2; ++_i) \
;         __builtin_amdgcn_global_load_lds((const unsigned*)((const char*)(gbase) + (voff)[_i]), (LAS unsigned*)(lds + (bufoff) + ldsw + _i * 8192), 16, 0, 0); } while (0)
; #define PG8_LDA(dst, b, h) do { _Pragma("unroll") for (int m = 0; m < 4; ++m) _Pragma("unroll") for (int k = 0; k < 2; ++k) dst[m][k] = *(const LAS bf16x8*)(lds + PG8_SA(b, h) + aoff + m * 2048 + k * 1024); } while (0)
; #define PG8_LDB(dst, b, h) do { _Pragma("unroll") for (int n = 0; n < 2; ++n) _Pragma("unroll") for (int k = 0; k < 2; ++k) dst[n][k] = *(const LAS bf16x8*)(lds + PG8_SB(b, h) + boff + n * 2048 + k * 1024); } while (0)
; #define PG8_MMA(ai, bj, At, Bt) do { __builtin_amdgcn_s_setprio(1); _Pragma("unroll") for (int m = 0; m < 4; ++m) _Pragma("unroll") for (int n = 0; n < 2; ++n) _Pragma("unroll") for (int k = 0; k < 2; ++k) \
;         acc[ai][bj][m][n] = __builtin_amdgcn_mfma_f32_16x16x32_bf16(Bt[n][k], At[m][k], acc[ai][bj][m][n], 0, 0, 0); __builtin_amdgcn_s_setprio(0); } while (0)
; #define PG8_WAIT_V(n) asm volatile("s_waitcnt vmcnt(" #n ")" ::: "memory")
; #define PG8_WAIT_L(n) asm volatile("s_waitcnt lgkmcnt(" #n ")" ::: "memory")
; #define PG8_BAR __builtin_amdgcn_s_barrier()
; #define PG8_SCHED __builtin_amdgcn_sched_barrier(0)
; template <class Epi>
; __device__ __forceinline__ void gemm_phase(LAS unsigned char* lds, const Gemm g, const Sched& S, const Epi& E, const int tid) {
;     ...
;         for (int t = 0; t < nt; t += 2) {
;             const bool last = (t == nt - 2);
;             const char* a1 = cA + (size_t)(t + 1) * kstep;
;             const char* a2 = last ? nA : cA + (size_t)(t + 2) * kstep; const char* b2 = last ? nB : cB + (size_t)(t + 2) * kstep;
;             const char* a3 = a2 + kstep; const char* b3 = b2 + kstep;
;             PG8_LDB(B0, 0, 0); PG8_LDB(B1, 0, 1); PG8_SCHED; PG8_LDA(At, 0, 0); PG8_STAGE(PG8_SA(1, 1), a1 + hA, voffA);
;     ...
;             PG8_LDA(At, 1, 1); PG8_STAGE(PG8_SB(1, 0), b3, voffB); PG8_STAGE(PG8_SB(1, 1), b3 + hB, voffB); PG8_STAGE(PG8_SA(1, 0), a3, voffA);
;             PG8_WAIT_V(8); PG8_WAIT_L(0); PG8_BAR; PG8_MMA(1, 0, At, B0); PG8_MMA(1, 1, At, B1); PG8_BAR; PG8_SCHED;
	s_add_i32 s16, s43, s39
	v_lshl_add_u64 v[154:155], v[154:155], 0, s[94:95]
	s_mov_b32 m0, s16
	ds_read_b128 v[176:179], v159 offset:49152
	ds_read_b128 v[180:183], v159 offset:50176
	ds_read_b128 v[184:187], v159 offset:51200
	ds_read_b128 v[188:191], v159 offset:52224
	ds_read_b128 v[194:197], v159 offset:53248
	ds_read_b128 v[198:201], v159 offset:54272
	ds_read_b128 v[204:207], v159 offset:55296
	ds_read_b128 v[208:211], v159 offset:56320
	global_load_lds_dwordx4 v[154:155], off
	s_add_i32 m0, s16, 0x2000
	s_add_u32 s16, s20, 0xb0080
	v_lshl_add_u64 v[154:155], v[212:213], 0, s[94:95]
	s_addc_u32 s17, s21, 0
	s_add_i32 s20, s44, s39
	global_load_lds_dwordx4 v[154:155], off
	v_lshl_add_u64 v[154:155], s[16:17], 0, v[192:193]
	s_mov_b32 m0, s20
	s_nop 0
	global_load_lds_dwordx4 v[154:155], off
	v_lshl_add_u64 v[154:155], s[16:17], 0, v[144:145]
	s_add_i32 m0, s20, 0x2000
	s_nop 0
	global_load_lds_dwordx4 v[154:155], off
	v_lshl_add_u64 v[154:155], v[214:215], 0, s[94:95]
	s_mov_b32 m0, s51
	s_nop 0
	global_load_lds_dwordx4 v[154:155], off
	v_lshl_add_u64 v[154:155], v[216:217], 0, s[94:95]
	s_mov_b32 m0, s76
	s_nop 0
	global_load_lds_dwordx4 v[154:155], off
	s_waitcnt vmcnt(8)
	s_waitcnt lgkmcnt(0)
	s_barrier
	s_setprio 1
	s_waitcnt lgkmcnt(0)
	v_mfma_f32_16x16x32_bf16 v[60:63], v[64:67], v[176:179], v[60:63]
	v_mfma_f32_16x16x32_bf16 v[56:59], v[80:83], v[176:179], v[56:59]
	v_mfma_f32_16x16x32_bf16 v[52:55], v[64:67], v[184:187], v[52:55]
	v_mfma_f32_16x16x32_bf16 v[48:51], v[80:83], v[184:187], v[48:51]
	v_mfma_f32_16x16x32_bf16 v[28:31], v[64:67], v[194:197], v[28:31]
	v_mfma_f32_16x16x32_bf16 v[24:27], v[80:83], v[194:197], v[24:27]
	v_mfma_f32_16x16x32_bf16 v[16:19], v[64:67], v[204:207], v[16:19]
	v_mfma_f32_16x16x32_bf16 v[8:11], v[80:83], v[204:207], v[8:11]
	v_mfma_f32_16x16x32_bf16 v[60:63], v[68:71], v[180:183], v[60:63]
	v_mfma_f32_16x16x32_bf16 v[56:59], v[92:95], v[180:183], v[56:59]
	v_mfma_f32_16x16x32_bf16 v[52:55], v[68:71], v[188:191], v[52:55]
	v_mfma_f32_16x16x32_bf16 v[48:51], v[92:95], v[188:191], v[48:51]
	v_mfma_f32_16x16x32_bf16 v[28:31], v[68:71], v[198:201], v[28:31]
	v_mfma_f32_16x16x32_bf16 v[24:27], v[92:95], v[198:201], v[24:27]
	v_mfma_f32_16x16x32_bf16 v[16:19], v[68:71], v[208:211], v[16:19]
	v_mfma_f32_16x16x32_bf16 v[8:11], v[92:95], v[208:211], v[8:11]
	s_setprio 0
	s_setprio 1
	v_mfma_f32_16x16x32_bf16 v[44:47], v[160:163], v[176:179], v[44:47]
	v_mfma_f32_16x16x32_bf16 v[40:43], v[168:171], v[176:179], v[40:43]
	v_mfma_f32_16x16x32_bf16 v[36:39], v[160:163], v[184:187], v[36:39]
	v_mfma_f32_16x16x32_bf16 v[32:35], v[168:171], v[184:187], v[32:35]
	v_mfma_f32_16x16x32_bf16 v[20:23], v[160:163], v[194:197], v[20:23]
	v_mfma_f32_16x16x32_bf16 v[12:15], v[168:171], v[194:197], v[12:15]
	v_mfma_f32_16x16x32_bf16 v[4:7], v[160:163], v[204:207], v[4:7]
	v_mfma_f32_16x16x32_bf16 v[0:3], v[168:171], v[204:207], v[0:3]
	v_mfma_f32_16x16x32_bf16 v[44:47], v[164:167], v[180:183], v[44:47]
	v_mfma_f32_16x16x32_bf16 v[40:43], v[172:175], v[180:183], v[40:43]
	v_mfma_f32_16x16x32_bf16 v[36:39], v[164:167], v[188:191], v[36:39]
	v_mfma_f32_16x16x32_bf16 v[32:35], v[172:175], v[188:191], v[32:35]
	v_mfma_f32_16x16x32_bf16 v[20:23], v[164:167], v[198:201], v[20:23]
	v_mfma_f32_16x16x32_bf16 v[12:15], v[172:175], v[198:201], v[12:15]
	v_mfma_f32_16x16x32_bf16 v[4:7], v[164:167], v[208:211], v[4:7]
	v_mfma_f32_16x16x32_bf16 v[0:3], v[172:175], v[208:211], v[0:3]
	s_add_i32 vcc_lo, vcc_lo, 2
	s_add_u32 s80, s80, 0x100
	s_addc_u32 s81, s81, 0
	s_cmp_gt_u32 vcc_lo, 41
	s_mov_b64 s[16:17], s[18:19]
	s_setprio 0
	s_barrier
	s_cbranch_scc1 .Lgk_exit_5
.LBB0_1411:
	s_add_u32 s18, s16, 0x100
	s_addc_u32 s19, s17, 0
	s_add_i32 s43, 0, 0x10000
	s_cmp_eq_u32 vcc_lo, 40
	s_cselect_b32 s23, s7, s19
	s_cselect_b32 s22, s6, s18
	s_cselect_b32 s21, s15, s81
	s_cselect_b32 s20, s14, s80
	s_add_i32 s44, 0, 0x14000
	v_add_u32_e32 v92, s43, v157
	v_add_u32_e32 v154, s44, v157
	ds_read_b128 v[64:67], v92
	ds_read_b128 v[68:71], v92 offset:1024
	ds_read_b128 v[80:83], v92 offset:2048
	ds_read_b128 v[92:95], v92 offset:3072
	ds_read_b128 v[160:163], v154
	ds_read_b128 v[164:167], v154 offset:1024
	ds_read_b128 v[168:171], v154 offset:2048
	ds_read_b128 v[172:175], v154 offset:3072
	v_lshl_add_u64 v[154:155], s[16:17], 0, v[150:151]
	s_add_i32 m0, s40, 0xc000
	ds_read_b128 v[176:179], v159
	ds_read_b128 v[180:183], v159 offset:1024
	ds_read_b128 v[184:187], v159 offset:2048
	ds_read_b128 v[188:191], v159 offset:3072
	ds_read_b128 v[194:197], v159 offset:4096
	ds_read_b128 v[198:201], v159 offset:5120
	ds_read_b128 v[204:207], v159 offset:6144
	ds_read_b128 v[208:211], v159 offset:7168
	global_load_lds_dwordx4 v[154:155], off
	v_lshl_add_u64 v[154:155], s[16:17], 0, v[152:153]
	s_add_i32 m0, s40, 0xe000
	s_nop 0
	global_load_lds_dwordx4 v[154:155], off
	s_waitcnt vmcnt(8)
	s_waitcnt lgkmcnt(0)
	s_barrier
; #define PG8_STAGE(bufoff, gbase, voff) do { _Pragma("unroll") for (int _i = 0; _i < 2; ++_i) \
;         __builtin_amdgcn_global_load_lds((const unsigned*)((const char*)(gbase) + (voff)[_i]), (LAS unsigned*)(lds + (bufoff) + ldsw + _i * 8192), 16, 0, 0); } while (0)
; #define PG8_LDA(dst, b, h) do { _Pragma("unroll") for (int m = 0; m < 4; ++m) _Pragma("unroll") for (int k = 0; k < 2; ++k) dst[m][k] = *(const LAS bf16x8*)(lds + PG8_SA(b, h) + aoff + m * 2048 + k * 1024); } while (0)
; #define PG8_MMA(ai, bj, At, Bt) do { __builtin_amdgcn_s_setprio(1); _Pragma("unroll") for (int m = 0; m < 4; ++m) _Pragma("unroll") for (int n = 0; n < 2; ++n) _Pragma("unroll") for (int k = 0; k < 2; ++k) \
;         acc[ai][bj][m][n] = __builtin_amdgcn_mfma_f32_16x16x32_bf16(Bt[n][k], At[m][k], acc[ai][bj][m][n], 0, 0, 0); __builtin_amdgcn_s_setprio(0); } while (0)
; #define PG8_WAIT_V(n) asm volatile("s_waitcnt vmcnt(" #n ")" ::: "memory")
; #define PG8_WAIT_L(n) asm volatile("s_waitcnt lgkmcnt(" #n ")" ::: "memory")
; #define PG8_BAR __builtin_amdgcn_s_barrier()
; #define PG8_SCHED __builtin_amdgcn_sched_barrier(0)
; template <class Epi>
; __device__ __forceinline__ void gemm_phase(LAS unsigned char* lds, const Gemm g, const Sched& S, const Epi& E, const int tid) {
;     ...
;             PG8_WAIT_V(8); PG8_WAIT_L(0); PG8_BAR; PG8_MMA(0, 0, At, B0); PG8_MMA(0, 1, At, B1); PG8_BAR; PG8_SCHED;
;             PG8_LDA(At, 0, 1); PG8_STAGE(PG8_SB(0, 0), b2, voffB); PG8_STAGE(PG8_SB(0, 1), b2 + hB, voffB); PG8_STAGE(PG8_SA(0, 0), a2, voffA);
;             PG8_WAIT_V(8); PG8_WAIT_L(0); PG8_BAR; PG8_MMA(1, 0, At, B0); PG8_MMA(1, 1, At, B1); PG8_BAR; PG8_SCHED;
	s_setprio 1
	s_waitcnt lgkmcnt(0)
	v_mfma_f32_16x16x32_bf16 v[140:143], v[64:67], v[176:179], v[140:143]
	v_mfma_f32_16x16x32_bf16 v[136:139], v[80:83], v[176:179], v[136:139]
	v_mfma_f32_16x16x32_bf16 v[132:135], v[64:67], v[184:187], v[132:135]
	v_mfma_f32_16x16x32_bf16 v[128:131], v[80:83], v[184:187], v[128:131]
	v_mfma_f32_16x16x32_bf16 v[108:111], v[64:67], v[194:197], v[108:111]
	v_mfma_f32_16x16x32_bf16 v[104:107], v[80:83], v[194:197], v[104:107]
	v_mfma_f32_16x16x32_bf16 v[100:103], v[64:67], v[204:207], v[100:103]
	v_mfma_f32_16x16x32_bf16 v[96:99], v[80:83], v[204:207], v[96:99]
	v_mfma_f32_16x16x32_bf16 v[140:143], v[68:71], v[180:183], v[140:143]
	v_mfma_f32_16x16x32_bf16 v[136:139], v[92:95], v[180:183], v[136:139]
	v_mfma_f32_16x16x32_bf16 v[132:135], v[68:71], v[188:191], v[132:135]
	v_mfma_f32_16x16x32_bf16 v[128:131], v[92:95], v[188:191], v[128:131]
	v_mfma_f32_16x16x32_bf16 v[108:111], v[68:71], v[198:201], v[108:111]
	v_mfma_f32_16x16x32_bf16 v[104:107], v[92:95], v[198:201], v[104:107]
	v_mfma_f32_16x16x32_bf16 v[100:103], v[68:71], v[208:211], v[100:103]
	v_mfma_f32_16x16x32_bf16 v[96:99], v[92:95], v[208:211], v[96:99]
	s_setprio 0
	s_setprio 1
	v_mfma_f32_16x16x32_bf16 v[124:127], v[160:163], v[176:179], v[124:127]
	v_mfma_f32_16x16x32_bf16 v[120:123], v[168:171], v[176:179], v[120:123]
	v_mfma_f32_16x16x32_bf16 v[116:119], v[160:163], v[184:187], v[116:119]
	v_mfma_f32_16x16x32_bf16 v[112:115], v[168:171], v[184:187], v[112:115]
	v_mfma_f32_16x16x32_bf16 v[88:91], v[160:163], v[194:197], v[88:91]
	v_mfma_f32_16x16x32_bf16 v[84:87], v[168:171], v[194:197], v[84:87]
	v_mfma_f32_16x16x32_bf16 v[76:79], v[160:163], v[204:207], v[76:79]
	v_mfma_f32_16x16x32_bf16 v[72:75], v[168:171], v[204:207], v[72:75]
	v_mfma_f32_16x16x32_bf16 v[124:127], v[164:167], v[180:183], v[124:127]
	v_mfma_f32_16x16x32_bf16 v[120:123], v[172:175], v[180:183], v[120:123]
	v_mfma_f32_16x16x32_bf16 v[116:119], v[164:167], v[188:191], v[116:119]
	v_mfma_f32_16x16x32_bf16 v[112:115], v[172:175], v[188:191], v[112:115]
	v_mfma_f32_16x16x32_bf16 v[88:91], v[164:167], v[198:201], v[88:91]
	v_mfma_f32_16x16x32_bf16 v[84:87], v[172:175], v[198:201], v[84:87]
	v_mfma_f32_16x16x32_bf16 v[76:79], v[164:167], v[208:211], v[76:79]
	v_mfma_f32_16x16x32_bf16 v[72:75], v[172:175], v[208:211], v[72:75]
	s_setprio 0
	s_barrier
	s_add_i32 s16, s43, s39
	v_lshl_add_u64 v[154:155], s[20:21], 0, v[192:193]
	s_mov_b32 m0, s16
	ds_read_b128 v[176:179], v159 offset:16384
	ds_read_b128 v[180:183], v159 offset:17408
	ds_read_b128 v[184:187], v159 offset:18432
	ds_read_b128 v[188:191], v159 offset:19456
	ds_read_b128 v[194:197], v159 offset:20480
	ds_read_b128 v[198:201], v159 offset:21504
	ds_read_b128 v[204:207], v159 offset:22528
	ds_read_b128 v[208:211], v159 offset:23552
	global_load_lds_dwordx4 v[154:155], off
	s_add_i32 m0, s16, 0x2000
	s_add_u32 s16, s20, 0xb0000
	v_lshl_add_u64 v[212:213], s[20:21], 0, v[144:145]
	s_addc_u32 s17, s21, 0
	s_add_i32 s43, s44, s39
	global_load_lds_dwordx4 v[212:213], off
	v_lshl_add_u64 v[214:215], s[16:17], 0, v[192:193]
	s_mov_b32 m0, s43
	v_lshl_add_u64 v[216:217], s[22:23], 0, v[146:147]
	global_load_lds_dwordx4 v[214:215], off
	v_lshl_add_u64 v[214:215], s[16:17], 0, v[144:145]
	s_add_i32 m0, s43, 0x2000
	s_nop 0
	global_load_lds_dwordx4 v[214:215], off
	v_lshl_add_u64 v[214:215], s[22:23], 0, v[148:149]
	s_mov_b32 m0, s40
	s_nop 0
	global_load_lds_dwordx4 v[214:215], off
	s_mov_b32 m0, s73
	s_nop 0
	global_load_lds_dwordx4 v[216:217], off
	s_waitcnt vmcnt(8)
	s_waitcnt lgkmcnt(0)
	s_barrier
	s_setprio 1
	s_waitcnt lgkmcnt(0)
	v_mfma_f32_16x16x32_bf16 v[60:63], v[64:67], v[176:179], v[60:63]
	v_mfma_f32_16x16x32_bf16 v[56:59], v[80:83], v[176:179], v[56:59]
	v_mfma_f32_16x16x32_bf16 v[52:55], v[64:67], v[184:187], v[52:55]
	v_mfma_f32_16x16x32_bf16 v[48:51], v[80:83], v[184:187], v[48:51]
	v_mfma_f32_16x16x32_bf16 v[28:31], v[64:67], v[194:197], v[28:31]
	v_mfma_f32_16x16x32_bf16 v[24:27], v[80:83], v[194:197], v[24:27]
	v_mfma_f32_16x16x32_bf16 v[16:19], v[64:67], v[204:207], v[16:19]
	v_mfma_f32_16x16x32_bf16 v[8:11], v[80:83], v[204:207], v[8:11]
	v_mfma_f32_16x16x32_bf16 v[60:63], v[68:71], v[180:183], v[60:63]
	v_mfma_f32_16x16x32_bf16 v[56:59], v[92:95], v[180:183], v[56:59]
	v_mfma_f32_16x16x32_bf16 v[52:55], v[68:71], v[188:191], v[52:55]
	v_mfma_f32_16x16x32_bf16 v[48:51], v[92:95], v[188:191], v[48:51]
	v_mfma_f32_16x16x32_bf16 v[28:31], v[68:71], v[198:201], v[28:31]
	v_mfma_f32_16x16x32_bf16 v[24:27], v[92:95], v[198:201], v[24:27]
	v_mfma_f32_16x16x32_bf16 v[16:19], v[68:71], v[208:211], v[16:19]
	v_mfma_f32_16x16x32_bf16 v[8:11], v[92:95], v[208:211], v[8:11]
	s_setprio 0
	s_setprio 1
	v_mfma_f32_16x16x32_bf16 v[44:47], v[160:163], v[176:179], v[44:47]
	v_mfma_f32_16x16x32_bf16 v[40:43], v[168:171], v[176:179], v[40:43]
	v_mfma_f32_16x16x32_bf16 v[36:39], v[160:163], v[184:187], v[36:39]
	v_mfma_f32_16x16x32_bf16 v[32:35], v[168:171], v[184:187], v[32:35]
	v_mfma_f32_16x16x32_bf16 v[20:23], v[160:163], v[194:197], v[20:23]
	v_mfma_f32_16x16x32_bf16 v[12:15], v[168:171], v[194:197], v[12:15]
	v_mfma_f32_16x16x32_bf16 v[4:7], v[160:163], v[204:207], v[4:7]
	v_mfma_f32_16x16x32_bf16 v[0:3], v[168:171], v[204:207], v[0:3]
	v_mfma_f32_16x16x32_bf16 v[44:47], v[164:167], v[180:183], v[44:47]
	v_mfma_f32_16x16x32_bf16 v[40:43], v[172:175], v[180:183], v[40:43]
	v_mfma_f32_16x16x32_bf16 v[36:39], v[164:167], v[188:191], v[36:39]
	v_mfma_f32_16x16x32_bf16 v[32:35], v[172:175], v[188:191], v[32:35]
	v_mfma_f32_16x16x32_bf16 v[20:23], v[164:167], v[198:201], v[20:23]
	v_mfma_f32_16x16x32_bf16 v[12:15], v[172:175], v[198:201], v[12:15]
	v_mfma_f32_16x16x32_bf16 v[4:7], v[164:167], v[208:211], v[4:7]
	v_mfma_f32_16x16x32_bf16 v[0:3], v[172:175], v[208:211], v[0:3]
	s_setprio 0
	s_barrier
; #define PG8_STAGE(bufoff, gbase, voff) do { _Pragma("unroll") for (int _i = 0; _i < 2; ++_i) \
;         __builtin_amdgcn_global_load_lds((const unsigned*)((const char*)(gbase) + (voff)[_i]), (LAS unsigned*)(lds + (bufoff) + ldsw + _i * 8192), 16, 0, 0); } while (0)
; #define PG8_LDA(dst, b, h) do { _Pragma("unroll") for (int m = 0; m < 4; ++m) _Pragma("unroll") for (int k = 0; k < 2; ++k) dst[m][k] = *(const LAS bf16x8*)(lds + PG8_SA(b, h) + aoff + m * 2048 + k * 1024); } while (0)
; #define PG8_LDB(dst, b, h) do { _Pragma("unroll") for (int n = 0; n < 2; ++n) _Pragma("unroll") for (int k = 0; k < 2; ++k) dst[n][k] = *(const LAS bf16x8*)(lds + PG8_SB(b, h) + boff + n * 2048 + k * 1024); } while (0)
; #define PG8_MMA(ai, bj, At, Bt) do { __builtin_amdgcn_s_setprio(1); _Pragma("unroll") for (int m = 0; m < 4; ++m) _Pragma("unroll") for (int n = 0; n < 2; ++n) _Pragma("unroll") for (int k = 0; k < 2; ++k) \
;         acc[ai][bj][m][n] = __builtin_amdgcn_mfma_f32_16x16x32_bf16(Bt[n][k], At[m][k], acc[ai][bj][m][n], 0, 0, 0); __builtin_amdgcn_s_setprio(0); } while (0)
; #define PG8_WAIT_V(n) asm volatile("s_waitcnt vmcnt(" #n ")" ::: "memory")
; #define PG8_WAIT_L(n) asm volatile("s_waitcnt lgkmcnt(" #n ")" ::: "memory")
; #define PG8_BAR __builtin_amdgcn_s_barrier()
; #define PG8_SCHED __builtin_amdgcn_sched_barrier(0)
; template <class Epi>
; __device__ __forceinline__ void gemm_phase(LAS unsigned char* lds, const Gemm g, const Sched& S, const Epi& E, const int tid) {
;     ...
;             PG8_LDB(B0, 1, 0); PG8_LDB(B1, 1, 1); PG8_SCHED; PG8_LDA(At, 1, 0); PG8_STAGE(PG8_SA(0, 1), a2 + hA, voffA);
;             PG8_WAIT_V(8); PG8_WAIT_L(0); PG8_BAR; PG8_MMA(0, 0, At, B0); PG8_MMA(0, 1, At, B1); PG8_BAR; PG8_SCHED;
	s_add_i32 s43, 0, 0x18000
	s_add_i32 s44, 0, 0x1c000
	v_add_u32_e32 v92, s43, v157
	v_add_u32_e32 v172, s44, v157
	ds_read_b128 v[64:67], v92
	ds_read_b128 v[68:71], v92 offset:1024
	ds_read_b128 v[80:83], v92 offset:2048
	ds_read_b128 v[92:95], v92 offset:3072
	ds_read_b128 v[160:163], v172
	ds_read_b128 v[164:167], v172 offset:1024
	ds_read_b128 v[168:171], v172 offset:2048
	ds_read_b128 v[172:175], v172 offset:3072
	s_add_u32 s16, s22, 0xb0000
	s_addc_u32 s17, s23, 0
	s_mov_b32 m0, s74
	v_lshl_add_u64 v[218:219], s[16:17], 0, v[148:149]
	ds_read_b128 v[176:179], v159 offset:32768
	ds_read_b128 v[180:183], v159 offset:33792
	ds_read_b128 v[184:187], v159 offset:34816
	ds_read_b128 v[188:191], v159 offset:35840
	ds_read_b128 v[194:197], v159 offset:36864
	ds_read_b128 v[198:201], v159 offset:37888
	ds_read_b128 v[204:207], v159 offset:38912
	ds_read_b128 v[208:211], v159 offset:39936
	global_load_lds_dwordx4 v[218:219], off
	v_lshl_add_u64 v[218:219], s[16:17], 0, v[146:147]
	s_mov_b32 m0, s75
	s_nop 0
	global_load_lds_dwordx4 v[218:219], off
	s_waitcnt vmcnt(8)
	s_waitcnt lgkmcnt(0)
	s_barrier
	s_setprio 1
	s_waitcnt lgkmcnt(0)
	v_mfma_f32_16x16x32_bf16 v[140:143], v[64:67], v[176:179], v[140:143]
	v_mfma_f32_16x16x32_bf16 v[136:139], v[80:83], v[176:179], v[136:139]
	v_mfma_f32_16x16x32_bf16 v[132:135], v[64:67], v[184:187], v[132:135]
	v_mfma_f32_16x16x32_bf16 v[128:131], v[80:83], v[184:187], v[128:131]
	v_mfma_f32_16x16x32_bf16 v[108:111], v[64:67], v[194:197], v[108:111]
	v_mfma_f32_16x16x32_bf16 v[104:107], v[80:83], v[194:197], v[104:107]
	v_mfma_f32_16x16x32_bf16 v[100:103], v[64:67], v[204:207], v[100:103]
	v_mfma_f32_16x16x32_bf16 v[96:99], v[80:83], v[204:207], v[96:99]
	v_mfma_f32_16x16x32_bf16 v[140:143], v[68:71], v[180:183], v[140:143]
	v_mfma_f32_16x16x32_bf16 v[136:139], v[92:95], v[180:183], v[136:139]
	v_mfma_f32_16x16x32_bf16 v[132:135], v[68:71], v[188:191], v[132:135]
	v_mfma_f32_16x16x32_bf16 v[128:131], v[92:95], v[188:191], v[128:131]
	v_mfma_f32_16x16x32_bf16 v[108:111], v[68:71], v[198:201], v[108:111]
	v_mfma_f32_16x16x32_bf16 v[104:107], v[92:95], v[198:201], v[104:107]
	v_mfma_f32_16x16x32_bf16 v[100:103], v[68:71], v[208:211], v[100:103]
	v_mfma_f32_16x16x32_bf16 v[96:99], v[92:95], v[208:211], v[96:99]
	s_setprio 0
	s_setprio 1
	v_mfma_f32_16x16x32_bf16 v[124:127], v[160:163], v[176:179], v[124:127]
	v_mfma_f32_16x16x32_bf16 v[120:123], v[168:171], v[176:179], v[120:123]
	v_mfma_f32_16x16x32_bf16 v[116:119], v[160:163], v[184:187], v[116:119]
	v_mfma_f32_16x16x32_bf16 v[112:115], v[168:171], v[184:187], v[112:115]
	v_mfma_f32_16x16x32_bf16 v[88:91], v[160:163], v[194:197], v[88:91]
	v_mfma_f32_16x16x32_bf16 v[84:87], v[168:171], v[194:197], v[84:87]
	v_mfma_f32_16x16x32_bf16 v[76:79], v[160:163], v[204:207], v[76:79]
	v_mfma_f32_16x16x32_bf16 v[72:75], v[168:171], v[204:207], v[72:75]
	v_mfma_f32_16x16x32_bf16 v[124:127], v[164:167], v[180:183], v[124:127]
	v_mfma_f32_16x16x32_bf16 v[120:123], v[172:175], v[180:183], v[120:123]
	v_mfma_f32_16x16x32_bf16 v[116:119], v[164:167], v[188:191], v[116:119]
	v_mfma_f32_16x16x32_bf16 v[112:115], v[172:175], v[188:191], v[112:115]
	v_mfma_f32_16x16x32_bf16 v[88:91], v[164:167], v[198:201], v[88:91]
	v_mfma_f32_16x16x32_bf16 v[84:87], v[172:175], v[198:201], v[84:87]
	v_mfma_f32_16x16x32_bf16 v[76:79], v[164:167], v[208:211], v[76:79]
	v_mfma_f32_16x16x32_bf16 v[72:75], v[172:175], v[208:211], v[72:75]
	s_setprio 0
	s_barrier
; #define PG8_STAGE(bufoff, gbase, voff) do { _Pragma("unroll") for (int _i = 0; _i < 2; ++_i) \
;         __builtin_amdgcn_global_load_lds((const unsigned*)((const char*)(gbase) + (voff)[_i]), (LAS unsigned*)(lds + (bufoff) + ldsw + _i * 8192), 16, 0, 0); } while (0)
; #define PG8_LDA(dst, b, h) do { _Pragma("unroll") for (int m = 0; m < 4; ++m) _Pragma("unroll") for (int k = 0; k < 2; ++k) dst[m][k] = *(const LAS bf16x8*)(lds + PG8_SA(b, h) + aoff + m * 2048 + k * 1024); } while (0)
; #define PG8_MMA(ai, bj, At, Bt) do { __builtin_amdgcn_s_setprio(1); _Pragma("unroll") for (int m = 0; m < 4; ++m) _Pragma("unroll") for (int n = 0; n < 2; ++n) _Pragma("unroll") for (int k = 0; k < 2; ++k) \
;         acc[ai][bj][m][n] = __builtin_amdgcn_mfma_f32_16x16x32_bf16(Bt[n][k], At[m][k], acc[ai][bj][m][n], 0, 0, 0); __builtin_amdgcn_s_setprio(0); } while (0)
; #define PG8_WAIT_V(n) asm volatile("s_waitcnt vmcnt(" #n ")" ::: "memory")
; #define PG8_WAIT_L(n) asm volatile("s_waitcnt lgkmcnt(" #n ")" ::: "memory")
; #define PG8_BAR __builtin_amdgcn_s_barrier()
; #define PG8_SCHED __builtin_amdgcn_sched_barrier(0)
; template <class Epi>
; __device__ __forceinline__ void gemm_phase(LAS unsigned char* lds, const Gemm g, const Sched& S, const Epi& E, const int tid) {
;     ...
;             PG8_LDA(At, 1, 1); PG8_STAGE(PG8_SB(1, 0), b3, voffB); PG8_STAGE(PG8_SB(1, 1), b3 + hB, voffB); PG8_STAGE(PG8_SA(1, 0), a3, voffA);
;             PG8_WAIT_V(8); PG8_WAIT_L(0); PG8_BAR; PG8_MMA(1, 0, At, B0); PG8_MMA(1, 1, At, B1); PG8_BAR; PG8_SCHED;
;         }
	s_add_i32 s16, s43, s39
	v_lshl_add_u64 v[154:155], v[154:155], 0, s[94:95]
	s_mov_b32 m0, s16
	ds_read_b128 v[176:179], v159 offset:49152
	ds_read_b128 v[180:183], v159 offset:50176
	ds_read_b128 v[184:187], v159 offset:51200
	ds_read_b128 v[188:191], v159 offset:52224
	ds_read_b128 v[194:197], v159 offset:53248
	ds_read_b128 v[198:201], v159 offset:54272
	ds_read_b128 v[204:207], v159 offset:55296
	ds_read_b128 v[208:211], v159 offset:56320
	global_load_lds_dwordx4 v[154:155], off
	s_add_i32 m0, s16, 0x2000
	s_add_u32 s16, s20, 0xb0080
	v_lshl_add_u64 v[154:155], v[212:213], 0, s[94:95]
	s_addc_u32 s17, s21, 0
	s_add_i32 s20, s44, s39
	global_load_lds_dwordx4 v[154:155], off
	v_lshl_add_u64 v[154:155], s[16:17], 0, v[192:193]
	s_mov_b32 m0, s20
	s_nop 0
	global_load_lds_dwordx4 v[154:155], off
	v_lshl_add_u64 v[154:155], s[16:17], 0, v[144:145]
	s_add_i32 m0, s20, 0x2000
	s_nop 0
	global_load_lds_dwordx4 v[154:155], off
	v_lshl_add_u64 v[154:155], v[214:215], 0, s[94:95]
	s_mov_b32 m0, s51
	s_nop 0
	global_load_lds_dwordx4 v[154:155], off
	v_lshl_add_u64 v[154:155], v[216:217], 0, s[94:95]
	s_mov_b32 m0, s76
	s_nop 0
	global_load_lds_dwordx4 v[154:155], off
	s_waitcnt vmcnt(8)
	s_waitcnt lgkmcnt(0)
	s_barrier
	s_setprio 1
	s_waitcnt lgkmcnt(0)
	v_mfma_f32_16x16x32_bf16 v[60:63], v[64:67], v[176:179], v[60:63]
	v_mfma_f32_16x16x32_bf16 v[56:59], v[80:83], v[176:179], v[56:59]
	v_mfma_f32_16x16x32_bf16 v[52:55], v[64:67], v[184:187], v[52:55]
	v_mfma_f32_16x16x32_bf16 v[48:51], v[80:83], v[184:187], v[48:51]
	v_mfma_f32_16x16x32_bf16 v[28:31], v[64:67], v[194:197], v[28:31]
	v_mfma_f32_16x16x32_bf16 v[24:27], v[80:83], v[194:197], v[24:27]
	v_mfma_f32_16x16x32_bf16 v[16:19], v[64:67], v[204:207], v[16:19]
	v_mfma_f32_16x16x32_bf16 v[8:11], v[80:83], v[204:207], v[8:11]
	v_mfma_f32_16x16x32_bf16 v[60:63], v[68:71], v[180:183], v[60:63]
	v_mfma_f32_16x16x32_bf16 v[56:59], v[92:95], v[180:183], v[56:59]
	v_mfma_f32_16x16x32_bf16 v[52:55], v[68:71], v[188:191], v[52:55]
	v_mfma_f32_16x16x32_bf16 v[48:51], v[92:95], v[188:191], v[48:51]
	v_mfma_f32_16x16x32_bf16 v[28:31], v[68:71], v[198:201], v[28:31]
	v_mfma_f32_16x16x32_bf16 v[24:27], v[92:95], v[198:201], v[24:27]
	v_mfma_f32_16x16x32_bf16 v[16:19], v[68:71], v[208:211], v[16:19]
	v_mfma_f32_16x16x32_bf16 v[8:11], v[92:95], v[208:211], v[8:11]
	s_setprio 0
	s_setprio 1
	v_mfma_f32_16x16x32_bf16 v[44:47], v[160:163], v[176:179], v[44:47]
	v_mfma_f32_16x16x32_bf16 v[40:43], v[168:171], v[176:179], v[40:43]
	v_mfma_f32_16x16x32_bf16 v[36:39], v[160:163], v[184:187], v[36:39]
	v_mfma_f32_16x16x32_bf16 v[32:35], v[168:171], v[184:187], v[32:35]
	v_mfma_f32_16x16x32_bf16 v[20:23], v[160:163], v[194:197], v[20:23]
	v_mfma_f32_16x16x32_bf16 v[12:15], v[168:171], v[194:197], v[12:15]
	v_mfma_f32_16x16x32_bf16 v[4:7], v[160:163], v[204:207], v[4:7]
	v_mfma_f32_16x16x32_bf16 v[0:3], v[168:171], v[204:207], v[0:3]
	v_mfma_f32_16x16x32_bf16 v[44:47], v[164:167], v[180:183], v[44:47]
	v_mfma_f32_16x16x32_bf16 v[40:43], v[172:175], v[180:183], v[40:43]
	v_mfma_f32_16x16x32_bf16 v[36:39], v[164:167], v[188:191], v[36:39]
	v_mfma_f32_16x16x32_bf16 v[32:35], v[172:175], v[188:191], v[32:35]
	v_mfma_f32_16x16x32_bf16 v[20:23], v[164:167], v[198:201], v[20:23]
	v_mfma_f32_16x16x32_bf16 v[12:15], v[172:175], v[198:201], v[12:15]
	v_mfma_f32_16x16x32_bf16 v[4:7], v[164:167], v[208:211], v[4:7]
	v_mfma_f32_16x16x32_bf16 v[0:3], v[172:175], v[208:211], v[0:3]
	s_add_i32 vcc_lo, vcc_lo, 2
	s_add_u32 s80, s80, 0x100
	s_addc_u32 s81, s81, 0
	s_cmp_gt_u32 vcc_lo, 41
	s_mov_b64 s[16:17], s[18:19]
	s_setprio 0
	s_barrier
	s_cbranch_scc0 .LBB0_1411
